# 4-phase GEMM loops with balanced 4/4/4/4 LDS-DMA stagings: ph8 staging moved across the back-edge into phase 1 (address from the running B pointer), no staging inside MFMA segments
# baseline (speedup 1.0000x reference)
; #define PG8_STAGE(bufoff, gbase, voff) do { _Pragma("unroll") for (int _i = 0; _i < 2; ++_i) \
;         __builtin_amdgcn_global_load_lds((const unsigned*)((const char*)(gbase) + (voff)[_i]), (LAS unsigned*)(lds + (bufoff) + ldsw + _i * 8192), 16, 0, 0); } while (0)
; #define PG8_LDA(dst, b, h) do { _Pragma("unroll") for (int m = 0; m < 4; ++m) _Pragma("unroll") for (int k = 0; k < 2; ++k) dst[m][k] = *(const LAS bf16x8*)(lds + PG8_SA(b, h) + aoff + m * 2048 + k * 1024); } while (0)
; #define PG8_LDB(dst, b, h) do { _Pragma("unroll") for (int n = 0; n < 2; ++n) _Pragma("unroll") for (int k = 0; k < 2; ++k) dst[n][k] = *(const LAS bf16x8*)(lds + PG8_SB(b, h) + boff + n * 2048 + k * 1024); } while (0)
; #define PG8_MMA(ai, bj, At, Bt) do { __builtin_amdgcn_s_setprio(1); _Pragma("unroll") for (int m = 0; m < 4; ++m) _Pragma("unroll") for (int n = 0; n < 2; ++n) _Pragma("unroll") for (int k = 0; k < 2; ++k) \
;         acc[ai][bj][m][n] = __builtin_amdgcn_mfma_f32_16x16x32_bf16(Bt[n][k], At[m][k], acc[ai][bj][m][n], 0, 0, 0); __builtin_amdgcn_s_setprio(0); } while (0)
; #define PG8_WAIT_L(n) asm volatile("s_waitcnt lgkmcnt(" #n ")" ::: "memory")
; #define PG8_BAR __builtin_amdgcn_s_barrier()
; #define PG8_SCHED __builtin_amdgcn_sched_barrier(0)
; template <class Epi, class Sched>
; __device__ __forceinline__ void gemm_phase(LAS unsigned char* lds, const Gemm g, const Sched& S, const Epi& E) {
;     ...
;         for (int t = 0; t < nt; t += 2) {
;             const bool last = (t == nt - 2);
;             const char* a1 = cA + (size_t)(t + 1) * kstep;
;             const char* a2 = last ? nA : cA + (size_t)(t + 2) * kstep; const char* b2 = last ? nB : cB + (size_t)(t + 2) * kstep;
;             const char* a3 = a2 + kstep; const char* b3 = b2 + kstep;
;             PG8_LDB(B0, 0, 0); PG8_SCHED; PG8_LDA(At, 0, 0); PG8_STAGE(PG8_SA(1, 1), a1 + hstep, voffA);
;             PG8_WAIT_L(8); PG8_BAR; PG8_WAIT_L(0); PG8_MMA(0, 0, At, B0); PG8_BAR; PG8_SCHED;
;             PG8_LDB(B1, 0, 1); PG8_STAGE(PG8_SB(0, 0), b2, voffB);
;             PG8_BAR; PG8_WAIT_L(0); PG8_MMA(0, 1, At, B1); PG8_BAR;
;             PG8_LDA(At, 0, 1); PG8_STAGE(PG8_SA(0, 0), a2, voffA);
;             PG8_BAR; PG8_WAIT_L(0); PG8_MMA(1, 0, At, B0); PG8_BAR; PG8_SCHED;
.LBB0_44:
	s_add_u32 s100, s73, 0x1fff80
	s_addc_u32 s101, s74, 0
	v_lshl_add_u64 v[66:67], s[100:101], 0, v[0:1]
	s_add_i32 m0, s60, 0x1c000
	s_nop 0
	global_load_lds_dwordx4 v[66:67], off
	v_lshl_add_u64 v[66:67], s[100:101], 0, v[146:147]
	s_add_i32 m0, s60, 0x1e000
	s_nop 0
	global_load_lds_dwordx4 v[66:67], off
	s_add_u32 s50, s28, 0x100
	s_addc_u32 s51, s29, 0
	s_cmpk_eq_i32 s75, 0x7c
	s_cselect_b32 s55, s27, s51
	s_cselect_b32 s54, s71, s50
	s_cselect_b32 s53, s25, s74
	s_cselect_b32 s52, s72, s73
	v_lshl_add_u64 v[156:157], s[28:29], 0, v[150:151]
	s_add_i32 m0, s9, 0xc000
	s_nop 0
	global_load_lds_dwordx4 v[156:157], off
	v_lshl_add_u64 v[156:157], s[28:29], 0, v[148:149]
	s_add_i32 m0, s9, 0xe000
	s_nop 0
	global_load_lds_dwordx4 v[156:157], off
	s_add_i32 s38, 0, 0x10000
	v_add_u32_e32 v78, s38, v163
	ds_read_b128 v[66:69], v78
	ds_read_b128 v[70:73], v78 offset:1024
	ds_read_b128 v[74:77], v78 offset:2048
	ds_read_b128 v[78:81], v78 offset:3072
	ds_read_b128 v[152:155], v165
	ds_read_b128 v[166:169], v165 offset:1024
	ds_read_b128 v[170:173], v165 offset:2048
	ds_read_b128 v[174:177], v165 offset:3072
	ds_read_b128 v[178:181], v165 offset:4096
	ds_read_b128 v[182:185], v165 offset:5120
	ds_read_b128 v[186:189], v165 offset:6144
	ds_read_b128 v[190:193], v165 offset:7168
	s_add_i32 s39, 0, 0x14000
	v_add_u32_e32 v156, s39, v163
	ds_read_b128 v[194:197], v156
	ds_read_b128 v[198:201], v156 offset:1024
	ds_read_b128 v[202:205], v156 offset:2048
	ds_read_b128 v[210:213], v156 offset:3072
	s_waitcnt lgkmcnt(4)
	s_barrier
	s_waitcnt lgkmcnt(0)
	s_setprio 1
	v_mfma_f32_16x16x32_bf16 v[142:145], v[66:69], v[152:155], v[142:145]
	v_mfma_f32_16x16x32_bf16 v[138:141], v[74:77], v[152:155], v[138:141]
	v_mfma_f32_16x16x32_bf16 v[126:129], v[66:69], v[170:173], v[126:129]
	v_mfma_f32_16x16x32_bf16 v[122:125], v[74:77], v[170:173], v[122:125]
	v_mfma_f32_16x16x32_bf16 v[110:113], v[66:69], v[178:181], v[110:113]
	v_mfma_f32_16x16x32_bf16 v[106:109], v[74:77], v[178:181], v[106:109]
	v_mfma_f32_16x16x32_bf16 v[102:105], v[66:69], v[186:189], v[102:105]
	v_mfma_f32_16x16x32_bf16 v[98:101], v[74:77], v[186:189], v[98:101]
	v_mfma_f32_16x16x32_bf16 v[142:145], v[70:73], v[166:169], v[142:145]
	v_mfma_f32_16x16x32_bf16 v[138:141], v[78:81], v[166:169], v[138:141]
	v_mfma_f32_16x16x32_bf16 v[126:129], v[70:73], v[174:177], v[126:129]
	v_mfma_f32_16x16x32_bf16 v[122:125], v[78:81], v[174:177], v[122:125]
	v_mfma_f32_16x16x32_bf16 v[110:113], v[70:73], v[182:185], v[110:113]
	v_mfma_f32_16x16x32_bf16 v[106:109], v[78:81], v[182:185], v[106:109]
	v_mfma_f32_16x16x32_bf16 v[102:105], v[70:73], v[190:193], v[102:105]
	v_mfma_f32_16x16x32_bf16 v[98:101], v[78:81], v[190:193], v[98:101]
	v_mfma_f32_16x16x32_bf16 v[134:137], v[194:197], v[152:155], v[134:137]
	v_mfma_f32_16x16x32_bf16 v[130:133], v[202:205], v[152:155], v[130:133]
	v_mfma_f32_16x16x32_bf16 v[118:121], v[194:197], v[170:173], v[118:121]
	v_mfma_f32_16x16x32_bf16 v[114:117], v[202:205], v[170:173], v[114:117]
	v_mfma_f32_16x16x32_bf16 v[94:97], v[194:197], v[178:181], v[94:97]
	v_mfma_f32_16x16x32_bf16 v[90:93], v[202:205], v[178:181], v[90:93]
	v_mfma_f32_16x16x32_bf16 v[86:89], v[194:197], v[186:189], v[86:89]
	v_mfma_f32_16x16x32_bf16 v[82:85], v[202:205], v[186:189], v[82:85]
	v_mfma_f32_16x16x32_bf16 v[134:137], v[198:201], v[166:169], v[134:137]
	v_mfma_f32_16x16x32_bf16 v[130:133], v[210:213], v[166:169], v[130:133]
	v_mfma_f32_16x16x32_bf16 v[118:121], v[198:201], v[174:177], v[118:121]
	v_mfma_f32_16x16x32_bf16 v[114:117], v[210:213], v[174:177], v[114:117]
	v_mfma_f32_16x16x32_bf16 v[94:97], v[198:201], v[182:185], v[94:97]
	v_mfma_f32_16x16x32_bf16 v[90:93], v[210:213], v[182:185], v[90:93]
	v_mfma_f32_16x16x32_bf16 v[86:89], v[198:201], v[190:193], v[86:89]
	v_mfma_f32_16x16x32_bf16 v[82:85], v[210:213], v[190:193], v[82:85]
	s_setprio 0
	s_barrier
	s_add_i32 s28, s38, s60
	v_lshl_add_u64 v[156:157], s[52:53], 0, v[0:1]
	s_mov_b32 m0, s28
	v_lshl_add_u64 v[160:161], s[52:53], 0, v[146:147]
	global_load_lds_dwordx4 v[156:157], off
	s_add_i32 m0, s28, 0x2000
	s_nop 0
	global_load_lds_dwordx4 v[160:161], off
	s_mov_b32 m0, s9
	v_lshl_add_u64 v[206:207], s[54:55], 0, v[0:1]
	global_load_lds_dwordx4 v[206:207], off
	v_lshl_add_u64 v[214:215], s[54:55], 0, v[146:147]
	s_mov_b32 m0, s61
	s_nop 0
	global_load_lds_dwordx4 v[214:215], off
	ds_read_b128 v[152:155], v165 offset:16384
	ds_read_b128 v[166:169], v165 offset:17408
	ds_read_b128 v[170:173], v165 offset:18432
	ds_read_b128 v[174:177], v165 offset:19456
	ds_read_b128 v[178:181], v165 offset:20480
	ds_read_b128 v[182:185], v165 offset:21504
	ds_read_b128 v[186:189], v165 offset:22528
	ds_read_b128 v[190:193], v165 offset:23552
	s_waitcnt vmcnt(4)
	s_waitcnt lgkmcnt(0)
	s_barrier
; #define PG8_STAGE(bufoff, gbase, voff) do { _Pragma("unroll") for (int _i = 0; _i < 2; ++_i) \
;         __builtin_amdgcn_global_load_lds((const unsigned*)((const char*)(gbase) + (voff)[_i]), (LAS unsigned*)(lds + (bufoff) + ldsw + _i * 8192), 16, 0, 0); } while (0)
; #define PG8_LDA(dst, b, h) do { _Pragma("unroll") for (int m = 0; m < 4; ++m) _Pragma("unroll") for (int k = 0; k < 2; ++k) dst[m][k] = *(const LAS bf16x8*)(lds + PG8_SA(b, h) + aoff + m * 2048 + k * 1024); } while (0)
; #define PG8_LDB(dst, b, h) do { _Pragma("unroll") for (int n = 0; n < 2; ++n) _Pragma("unroll") for (int k = 0; k < 2; ++k) dst[n][k] = *(const LAS bf16x8*)(lds + PG8_SB(b, h) + boff + n * 2048 + k * 1024); } while (0)
; #define PG8_MMA(ai, bj, At, Bt) do { __builtin_amdgcn_s_setprio(1); _Pragma("unroll") for (int m = 0; m < 4; ++m) _Pragma("unroll") for (int n = 0; n < 2; ++n) _Pragma("unroll") for (int k = 0; k < 2; ++k) \
;         acc[ai][bj][m][n] = __builtin_amdgcn_mfma_f32_16x16x32_bf16(Bt[n][k], At[m][k], acc[ai][bj][m][n], 0, 0, 0); __builtin_amdgcn_s_setprio(0); } while (0)
; #define PG8_WAIT_V(n) asm volatile("s_waitcnt vmcnt(" #n ")" ::: "memory")
; #define PG8_WAIT_L(n) asm volatile("s_waitcnt lgkmcnt(" #n ")" ::: "memory")
; #define PG8_BAR __builtin_amdgcn_s_barrier()
; #define PG8_SCHED __builtin_amdgcn_sched_barrier(0)
; template <class Epi, class Sched>
; __device__ __forceinline__ void gemm_phase(LAS unsigned char* lds, const Gemm g, const Sched& S, const Epi& E) {
;     ...
;             PG8_BAR; PG8_WAIT_L(0); PG8_MMA(1, 0, At, B0); PG8_BAR; PG8_SCHED;
;             PG8_STAGE(PG8_SB(0, 1), b2 + hstep, voffB);
;             PG8_WAIT_V(6); PG8_BAR; PG8_MMA(1, 1, At, B1); PG8_BAR;
;             PG8_LDB(B0, 1, 0); PG8_SCHED; PG8_LDA(At, 1, 0); PG8_STAGE(PG8_SA(0, 1), a2 + hstep, voffA);
;             PG8_WAIT_L(8); PG8_BAR; PG8_WAIT_L(0); PG8_MMA(0, 0, At, B0); PG8_BAR; PG8_SCHED;
;             PG8_LDB(B1, 1, 1); PG8_STAGE(PG8_SB(1, 0), b3, voffB);
	s_setprio 1
	v_mfma_f32_16x16x32_bf16 v[62:65], v[66:69], v[152:155], v[62:65]
	v_mfma_f32_16x16x32_bf16 v[58:61], v[74:77], v[152:155], v[58:61]
	v_mfma_f32_16x16x32_bf16 v[46:49], v[66:69], v[170:173], v[46:49]
	v_mfma_f32_16x16x32_bf16 v[42:45], v[74:77], v[170:173], v[42:45]
	v_mfma_f32_16x16x32_bf16 v[30:33], v[66:69], v[178:181], v[30:33]
	v_mfma_f32_16x16x32_bf16 v[26:29], v[74:77], v[178:181], v[26:29]
	v_mfma_f32_16x16x32_bf16 v[22:25], v[66:69], v[186:189], v[22:25]
	v_mfma_f32_16x16x32_bf16 v[14:17], v[74:77], v[186:189], v[14:17]
	v_mfma_f32_16x16x32_bf16 v[62:65], v[70:73], v[166:169], v[62:65]
	v_mfma_f32_16x16x32_bf16 v[58:61], v[78:81], v[166:169], v[58:61]
	v_mfma_f32_16x16x32_bf16 v[46:49], v[70:73], v[174:177], v[46:49]
	v_mfma_f32_16x16x32_bf16 v[42:45], v[78:81], v[174:177], v[42:45]
	v_mfma_f32_16x16x32_bf16 v[30:33], v[70:73], v[182:185], v[30:33]
	v_mfma_f32_16x16x32_bf16 v[26:29], v[78:81], v[182:185], v[26:29]
	v_mfma_f32_16x16x32_bf16 v[22:25], v[70:73], v[190:193], v[22:25]
	v_mfma_f32_16x16x32_bf16 v[14:17], v[78:81], v[190:193], v[14:17]
	v_mfma_f32_16x16x32_bf16 v[54:57], v[194:197], v[152:155], v[54:57]
	v_mfma_f32_16x16x32_bf16 v[50:53], v[202:205], v[152:155], v[50:53]
	v_mfma_f32_16x16x32_bf16 v[38:41], v[194:197], v[170:173], v[38:41]
	v_mfma_f32_16x16x32_bf16 v[34:37], v[202:205], v[170:173], v[34:37]
	v_mfma_f32_16x16x32_bf16 v[18:21], v[194:197], v[178:181], v[18:21]
	v_mfma_f32_16x16x32_bf16 v[10:13], v[202:205], v[178:181], v[10:13]
	v_mfma_f32_16x16x32_bf16 v[6:9], v[194:197], v[186:189], v[6:9]
	v_mfma_f32_16x16x32_bf16 v[2:5], v[202:205], v[186:189], v[2:5]
	v_mfma_f32_16x16x32_bf16 v[54:57], v[198:201], v[166:169], v[54:57]
	v_mfma_f32_16x16x32_bf16 v[50:53], v[210:213], v[166:169], v[50:53]
	v_mfma_f32_16x16x32_bf16 v[38:41], v[198:201], v[174:177], v[38:41]
	v_mfma_f32_16x16x32_bf16 v[34:37], v[210:213], v[174:177], v[34:37]
	v_mfma_f32_16x16x32_bf16 v[18:21], v[198:201], v[182:185], v[18:21]
	v_mfma_f32_16x16x32_bf16 v[10:13], v[210:213], v[182:185], v[10:13]
	v_mfma_f32_16x16x32_bf16 v[6:9], v[198:201], v[190:193], v[6:9]
	v_mfma_f32_16x16x32_bf16 v[2:5], v[210:213], v[190:193], v[2:5]
	s_setprio 0
	s_barrier
	s_add_u32 s28, s52, 0x200000
	s_addc_u32 s29, s53, 0
	s_add_i32 s38, s39, s60
	v_lshl_add_u64 v[66:67], s[28:29], 0, v[0:1]
	s_mov_b32 m0, s38
	s_nop 0
	global_load_lds_dwordx4 v[66:67], off
	v_lshl_add_u64 v[66:67], s[28:29], 0, v[146:147]
	s_add_i32 m0, s38, 0x2000
	s_nop 0
	global_load_lds_dwordx4 v[66:67], off
	s_add_u32 s28, s54, 0x200000
	s_addc_u32 s29, s55, 0
	s_mov_b32 m0, s62
	v_lshl_add_u64 v[194:195], s[28:29], 0, v[0:1]
	global_load_lds_dwordx4 v[194:195], off
	v_lshl_add_u64 v[194:195], s[28:29], 0, v[146:147]
	s_mov_b32 m0, s63
	s_nop 0
	global_load_lds_dwordx4 v[194:195], off
	s_add_i32 s38, 0, 0x18000
	v_add_u32_e32 v78, s38, v163
	ds_read_b128 v[66:69], v78
	ds_read_b128 v[70:73], v78 offset:1024
	ds_read_b128 v[74:77], v78 offset:2048
	ds_read_b128 v[78:81], v78 offset:3072
	ds_read_b128 v[152:155], v165 offset:32768
	ds_read_b128 v[166:169], v165 offset:33792
	ds_read_b128 v[170:173], v165 offset:34816
	ds_read_b128 v[174:177], v165 offset:35840
	ds_read_b128 v[178:181], v165 offset:36864
	ds_read_b128 v[182:185], v165 offset:37888
	ds_read_b128 v[186:189], v165 offset:38912
	ds_read_b128 v[190:193], v165 offset:39936
	s_add_i32 s39, 0, 0x1c000
	v_add_u32_e32 v210, s39, v163
	ds_read_b128 v[194:197], v210
	ds_read_b128 v[198:201], v210 offset:1024
	ds_read_b128 v[202:205], v210 offset:2048
	ds_read_b128 v[210:213], v210 offset:3072
	s_waitcnt lgkmcnt(4)
	s_barrier
; #define PG8_STAGE(bufoff, gbase, voff) do { _Pragma("unroll") for (int _i = 0; _i < 2; ++_i) \
;         __builtin_amdgcn_global_load_lds((const unsigned*)((const char*)(gbase) + (voff)[_i]), (LAS unsigned*)(lds + (bufoff) + ldsw + _i * 8192), 16, 0, 0); } while (0)
; #define PG8_LDA(dst, b, h) do { _Pragma("unroll") for (int m = 0; m < 4; ++m) _Pragma("unroll") for (int k = 0; k < 2; ++k) dst[m][k] = *(const LAS bf16x8*)(lds + PG8_SA(b, h) + aoff + m * 2048 + k * 1024); } while (0)
; #define PG8_LDB(dst, b, h) do { _Pragma("unroll") for (int n = 0; n < 2; ++n) _Pragma("unroll") for (int k = 0; k < 2; ++k) dst[n][k] = *(const LAS bf16x8*)(lds + PG8_SB(b, h) + boff + n * 2048 + k * 1024); } while (0)
; #define PG8_MMA(ai, bj, At, Bt) do { __builtin_amdgcn_s_setprio(1); _Pragma("unroll") for (int m = 0; m < 4; ++m) _Pragma("unroll") for (int n = 0; n < 2; ++n) _Pragma("unroll") for (int k = 0; k < 2; ++k) \
;         acc[ai][bj][m][n] = __builtin_amdgcn_mfma_f32_16x16x32_bf16(Bt[n][k], At[m][k], acc[ai][bj][m][n], 0, 0, 0); __builtin_amdgcn_s_setprio(0); } while (0)
; #define PG8_WAIT_V(n) asm volatile("s_waitcnt vmcnt(" #n ")" ::: "memory")
; #define PG8_WAIT_L(n) asm volatile("s_waitcnt lgkmcnt(" #n ")" ::: "memory")
; #define PG8_BAR __builtin_amdgcn_s_barrier()
; #define PG8_SCHED __builtin_amdgcn_sched_barrier(0)
; template <class Epi, class Sched>
; __device__ __forceinline__ void gemm_phase(LAS unsigned char* lds, const Gemm g, const Sched& S, const Epi& E) {
;     ...
;             PG8_WAIT_L(8); PG8_BAR; PG8_WAIT_L(0); PG8_MMA(0, 0, At, B0); PG8_BAR; PG8_SCHED;
;             PG8_LDB(B1, 1, 1); PG8_STAGE(PG8_SB(1, 0), b3, voffB);
;             PG8_BAR; PG8_WAIT_L(0); PG8_MMA(0, 1, At, B1); PG8_BAR;
;             PG8_LDA(At, 1, 1); PG8_STAGE(PG8_SA(1, 0), a3, voffA);
;             PG8_BAR; PG8_WAIT_L(0); PG8_MMA(1, 0, At, B0); PG8_BAR; PG8_SCHED;
;             PG8_STAGE(PG8_SB(1, 1), b3 + hstep, voffB);
;             PG8_WAIT_V(6); PG8_BAR; PG8_MMA(1, 1, At, B1); PG8_BAR;
;         }
;         E(acc, cur, wr, wc, fr, fq);
	s_waitcnt lgkmcnt(0)
	s_setprio 1
	v_mfma_f32_16x16x32_bf16 v[142:145], v[66:69], v[152:155], v[142:145]
	v_mfma_f32_16x16x32_bf16 v[138:141], v[74:77], v[152:155], v[138:141]
	v_mfma_f32_16x16x32_bf16 v[126:129], v[66:69], v[170:173], v[126:129]
	v_mfma_f32_16x16x32_bf16 v[122:125], v[74:77], v[170:173], v[122:125]
	v_mfma_f32_16x16x32_bf16 v[110:113], v[66:69], v[178:181], v[110:113]
	v_mfma_f32_16x16x32_bf16 v[106:109], v[74:77], v[178:181], v[106:109]
	v_mfma_f32_16x16x32_bf16 v[102:105], v[66:69], v[186:189], v[102:105]
	v_mfma_f32_16x16x32_bf16 v[98:101], v[74:77], v[186:189], v[98:101]
	v_mfma_f32_16x16x32_bf16 v[142:145], v[70:73], v[166:169], v[142:145]
	v_mfma_f32_16x16x32_bf16 v[138:141], v[78:81], v[166:169], v[138:141]
	v_mfma_f32_16x16x32_bf16 v[126:129], v[70:73], v[174:177], v[126:129]
	v_mfma_f32_16x16x32_bf16 v[122:125], v[78:81], v[174:177], v[122:125]
	v_mfma_f32_16x16x32_bf16 v[110:113], v[70:73], v[182:185], v[110:113]
	v_mfma_f32_16x16x32_bf16 v[106:109], v[78:81], v[182:185], v[106:109]
	v_mfma_f32_16x16x32_bf16 v[102:105], v[70:73], v[190:193], v[102:105]
	v_mfma_f32_16x16x32_bf16 v[98:101], v[78:81], v[190:193], v[98:101]
	v_mfma_f32_16x16x32_bf16 v[134:137], v[194:197], v[152:155], v[134:137]
	v_mfma_f32_16x16x32_bf16 v[130:133], v[202:205], v[152:155], v[130:133]
	v_mfma_f32_16x16x32_bf16 v[118:121], v[194:197], v[170:173], v[118:121]
	v_mfma_f32_16x16x32_bf16 v[114:117], v[202:205], v[170:173], v[114:117]
	v_mfma_f32_16x16x32_bf16 v[94:97], v[194:197], v[178:181], v[94:97]
	v_mfma_f32_16x16x32_bf16 v[90:93], v[202:205], v[178:181], v[90:93]
	v_mfma_f32_16x16x32_bf16 v[86:89], v[194:197], v[186:189], v[86:89]
	v_mfma_f32_16x16x32_bf16 v[82:85], v[202:205], v[186:189], v[82:85]
	v_mfma_f32_16x16x32_bf16 v[134:137], v[198:201], v[166:169], v[134:137]
	v_mfma_f32_16x16x32_bf16 v[130:133], v[210:213], v[166:169], v[130:133]
	v_mfma_f32_16x16x32_bf16 v[118:121], v[198:201], v[174:177], v[118:121]
	v_mfma_f32_16x16x32_bf16 v[114:117], v[210:213], v[174:177], v[114:117]
	v_mfma_f32_16x16x32_bf16 v[94:97], v[198:201], v[182:185], v[94:97]
	v_mfma_f32_16x16x32_bf16 v[90:93], v[210:213], v[182:185], v[90:93]
	v_mfma_f32_16x16x32_bf16 v[86:89], v[198:201], v[190:193], v[86:89]
	v_mfma_f32_16x16x32_bf16 v[82:85], v[210:213], v[190:193], v[82:85]
	s_setprio 0
	s_barrier
	s_add_i32 s28, s38, s60
	v_lshl_add_u64 v[156:157], v[156:157], 0, s[36:37]
	s_mov_b32 m0, s28
	s_nop 0
	global_load_lds_dwordx4 v[156:157], off
	v_lshl_add_u64 v[156:157], v[160:161], 0, s[36:37]
	s_add_i32 m0, s28, 0x2000
	s_nop 0
	global_load_lds_dwordx4 v[156:157], off
	s_mov_b32 m0, s66
	v_lshl_add_u64 v[156:157], v[206:207], 0, s[36:37]
	global_load_lds_dwordx4 v[156:157], off
	v_lshl_add_u64 v[156:157], v[214:215], 0, s[36:37]
	s_mov_b32 m0, s67
	s_nop 0
	global_load_lds_dwordx4 v[156:157], off
	ds_read_b128 v[152:155], v165 offset:49152
	ds_read_b128 v[166:169], v165 offset:50176
	ds_read_b128 v[170:173], v165 offset:51200
	ds_read_b128 v[174:177], v165 offset:52224
	ds_read_b128 v[178:181], v165 offset:53248
	ds_read_b128 v[182:185], v165 offset:54272
	ds_read_b128 v[186:189], v165 offset:55296
	ds_read_b128 v[190:193], v165 offset:56320
	s_waitcnt vmcnt(4)
	s_waitcnt lgkmcnt(0)
	s_barrier
	s_setprio 1
	v_mfma_f32_16x16x32_bf16 v[62:65], v[66:69], v[152:155], v[62:65]
	v_mfma_f32_16x16x32_bf16 v[58:61], v[74:77], v[152:155], v[58:61]
	v_mfma_f32_16x16x32_bf16 v[46:49], v[66:69], v[170:173], v[46:49]
	v_mfma_f32_16x16x32_bf16 v[42:45], v[74:77], v[170:173], v[42:45]
	v_mfma_f32_16x16x32_bf16 v[30:33], v[66:69], v[178:181], v[30:33]
	v_mfma_f32_16x16x32_bf16 v[26:29], v[74:77], v[178:181], v[26:29]
	v_mfma_f32_16x16x32_bf16 v[22:25], v[66:69], v[186:189], v[22:25]
	v_mfma_f32_16x16x32_bf16 v[14:17], v[74:77], v[186:189], v[14:17]
	v_mfma_f32_16x16x32_bf16 v[62:65], v[70:73], v[166:169], v[62:65]
	v_mfma_f32_16x16x32_bf16 v[58:61], v[78:81], v[166:169], v[58:61]
	v_mfma_f32_16x16x32_bf16 v[46:49], v[70:73], v[174:177], v[46:49]
	v_mfma_f32_16x16x32_bf16 v[42:45], v[78:81], v[174:177], v[42:45]
	v_mfma_f32_16x16x32_bf16 v[30:33], v[70:73], v[182:185], v[30:33]
	v_mfma_f32_16x16x32_bf16 v[26:29], v[78:81], v[182:185], v[26:29]
	v_mfma_f32_16x16x32_bf16 v[22:25], v[70:73], v[190:193], v[22:25]
	v_mfma_f32_16x16x32_bf16 v[14:17], v[78:81], v[190:193], v[14:17]
	v_mfma_f32_16x16x32_bf16 v[54:57], v[194:197], v[152:155], v[54:57]
	v_mfma_f32_16x16x32_bf16 v[50:53], v[202:205], v[152:155], v[50:53]
	v_mfma_f32_16x16x32_bf16 v[38:41], v[194:197], v[170:173], v[38:41]
	v_mfma_f32_16x16x32_bf16 v[34:37], v[202:205], v[170:173], v[34:37]
	v_mfma_f32_16x16x32_bf16 v[18:21], v[194:197], v[178:181], v[18:21]
	v_mfma_f32_16x16x32_bf16 v[10:13], v[202:205], v[178:181], v[10:13]
	v_mfma_f32_16x16x32_bf16 v[6:9], v[194:197], v[186:189], v[6:9]
	v_mfma_f32_16x16x32_bf16 v[2:5], v[202:205], v[186:189], v[2:5]
	v_mfma_f32_16x16x32_bf16 v[54:57], v[198:201], v[166:169], v[54:57]
	v_mfma_f32_16x16x32_bf16 v[50:53], v[210:213], v[166:169], v[50:53]
	v_mfma_f32_16x16x32_bf16 v[38:41], v[198:201], v[174:177], v[38:41]
	v_mfma_f32_16x16x32_bf16 v[34:37], v[210:213], v[174:177], v[34:37]
	v_mfma_f32_16x16x32_bf16 v[18:21], v[198:201], v[182:185], v[18:21]
	v_mfma_f32_16x16x32_bf16 v[10:13], v[210:213], v[182:185], v[10:13]
	v_mfma_f32_16x16x32_bf16 v[6:9], v[198:201], v[190:193], v[6:9]
	v_mfma_f32_16x16x32_bf16 v[2:5], v[210:213], v[190:193], v[2:5]
	s_setprio 0
	s_add_i32 s75, s75, 2
	s_add_u32 s73, s73, 0x100
	s_addc_u32 s74, s74, 0
	s_cmpk_gt_u32 s75, 0x7d
	s_mov_b64 s[28:29], s[50:51]
	s_barrier
	s_cbranch_scc0 .LBB0_44
	s_cmp_lt_i32 s8, 64
	s_cselect_b64 s[50:51], -1, 0
	s_cmp_gt_i32 s8, 63
	s_cbranch_scc0 .LBB0_35
	s_mov_b64 s[52:53], 0x18000
	s_mov_b64 s[28:29], s[46:47]
	s_branch .LBB0_36

; #define PG8_STAGE(bufoff, gbase, voff) do { _Pragma("unroll") for (int _i = 0; _i < 2; ++_i) \
;         __builtin_amdgcn_global_load_lds((const unsigned*)((const char*)(gbase) + (voff)[_i]), (LAS unsigned*)(lds + (bufoff) + ldsw + _i * 8192), 16, 0, 0); } while (0)
; #define PG8_LDA(dst, b, h) do { _Pragma("unroll") for (int m = 0; m < 4; ++m) _Pragma("unroll") for (int k = 0; k < 2; ++k) dst[m][k] = *(const LAS bf16x8*)(lds + PG8_SA(b, h) + aoff + m * 2048 + k * 1024); } while (0)
; #define PG8_LDB(dst, b, h) do { _Pragma("unroll") for (int n = 0; n < 2; ++n) _Pragma("unroll") for (int k = 0; k < 2; ++k) dst[n][k] = *(const LAS bf16x8*)(lds + PG8_SB(b, h) + boff + n * 2048 + k * 1024); } while (0)
; #define PG8_MMA(ai, bj, At, Bt) do { __builtin_amdgcn_s_setprio(1); _Pragma("unroll") for (int m = 0; m < 4; ++m) _Pragma("unroll") for (int n = 0; n < 2; ++n) _Pragma("unroll") for (int k = 0; k < 2; ++k) \
;         acc[ai][bj][m][n] = __builtin_amdgcn_mfma_f32_16x16x32_bf16(Bt[n][k], At[m][k], acc[ai][bj][m][n], 0, 0, 0); __builtin_amdgcn_s_setprio(0); } while (0)
; #define PG8_WAIT_L(n) asm volatile("s_waitcnt lgkmcnt(" #n ")" ::: "memory")
; #define PG8_BAR __builtin_amdgcn_s_barrier()
; #define PG8_SCHED __builtin_amdgcn_sched_barrier(0)
; template <class Epi, class Sched>
; __device__ __forceinline__ void gemm_phase(LAS unsigned char* lds, const Gemm g, const Sched& S, const Epi& E) {
;     ...
;             PG8_LDB(B0, 0, 0); PG8_SCHED; PG8_LDA(At, 0, 0); PG8_STAGE(PG8_SA(1, 1), a1 + hstep, voffA);
;             PG8_WAIT_L(8); PG8_BAR; PG8_WAIT_L(0); PG8_MMA(0, 0, At, B0); PG8_BAR; PG8_SCHED;
;             PG8_LDB(B1, 0, 1); PG8_STAGE(PG8_SB(0, 0), b2, voffB);
;             PG8_BAR; PG8_WAIT_L(0); PG8_MMA(0, 1, At, B1); PG8_BAR;
;             PG8_LDA(At, 0, 1); PG8_STAGE(PG8_SA(0, 0), a2, voffA);
;             PG8_BAR; PG8_WAIT_L(0); PG8_MMA(1, 0, At, B0); PG8_BAR; PG8_SCHED;
;             PG8_STAGE(PG8_SB(0, 1), b2 + hstep, voffB);
.LBB0_58:
	s_add_u32 s100, s69, 0x1fff80
	s_addc_u32 s101, s70, 0
	v_lshl_add_u64 v[140:141], s[100:101], 0, v[0:1]
	s_add_i32 m0, s63, 0x1c000
	s_nop 0
	global_load_lds_dwordx4 v[140:141], off
	v_lshl_add_u64 v[140:141], s[100:101], 0, v[130:131]
	s_add_i32 m0, s63, 0x1e000
	s_nop 0
	global_load_lds_dwordx4 v[140:141], off
	s_add_u32 s52, s50, 0x100
	s_addc_u32 s53, s51, 0
	s_cmp_eq_u32 s71, 28
	s_cselect_b32 s57, s11, s53
	s_cselect_b32 s56, s29, s52
	s_cselect_b32 s55, s41, s70
	s_cselect_b32 s54, s43, s69
	v_lshl_add_u64 v[156:157], s[50:51], 0, v[134:135]
	s_add_i32 m0, s25, 0xc000
	s_nop 0
	global_load_lds_dwordx4 v[156:157], off
	v_lshl_add_u64 v[156:157], s[50:51], 0, v[132:133]
	s_add_i32 m0, s25, 0xe000
	s_nop 0
	global_load_lds_dwordx4 v[156:157], off
	s_add_i32 s38, 0, 0x10000
	v_add_u32_e32 v152, s38, v137
	ds_read_b128 v[140:143], v152
	ds_read_b128 v[144:147], v152 offset:1024
	ds_read_b128 v[148:151], v152 offset:2048
	ds_read_b128 v[152:155], v152 offset:3072
	ds_read_b128 v[160:163], v139
	ds_read_b128 v[164:167], v139 offset:1024
	ds_read_b128 v[168:171], v139 offset:2048
	ds_read_b128 v[172:175], v139 offset:3072
	ds_read_b128 v[176:179], v139 offset:4096
	ds_read_b128 v[180:183], v139 offset:5120
	ds_read_b128 v[184:187], v139 offset:6144
	ds_read_b128 v[188:191], v139 offset:7168
	s_add_i32 s50, 0, 0x14000
	v_add_u32_e32 v156, s50, v137
	ds_read_b128 v[192:195], v156
	ds_read_b128 v[196:199], v156 offset:1024
	ds_read_b128 v[200:203], v156 offset:2048
	ds_read_b128 v[204:207], v156 offset:3072
	s_waitcnt lgkmcnt(4)
	s_barrier
	s_waitcnt lgkmcnt(0)
	s_setprio 1
	v_mfma_f32_16x16x32_bf16 v[126:129], v[140:143], v[160:163], v[126:129]
	v_mfma_f32_16x16x32_bf16 v[122:125], v[148:151], v[160:163], v[122:125]
	v_mfma_f32_16x16x32_bf16 v[118:121], v[140:143], v[168:171], v[118:121]
	v_mfma_f32_16x16x32_bf16 v[114:117], v[148:151], v[168:171], v[114:117]
	v_mfma_f32_16x16x32_bf16 v[106:109], v[140:143], v[176:179], v[106:109]
	v_mfma_f32_16x16x32_bf16 v[98:101], v[148:151], v[176:179], v[98:101]
	v_mfma_f32_16x16x32_bf16 v[90:93], v[140:143], v[184:187], v[90:93]
	v_mfma_f32_16x16x32_bf16 v[82:85], v[148:151], v[184:187], v[82:85]
	v_mfma_f32_16x16x32_bf16 v[126:129], v[144:147], v[164:167], v[126:129]
	v_mfma_f32_16x16x32_bf16 v[122:125], v[152:155], v[164:167], v[122:125]
	v_mfma_f32_16x16x32_bf16 v[118:121], v[144:147], v[172:175], v[118:121]
	v_mfma_f32_16x16x32_bf16 v[114:117], v[152:155], v[172:175], v[114:117]
	v_mfma_f32_16x16x32_bf16 v[106:109], v[144:147], v[180:183], v[106:109]
	v_mfma_f32_16x16x32_bf16 v[98:101], v[152:155], v[180:183], v[98:101]
	v_mfma_f32_16x16x32_bf16 v[90:93], v[144:147], v[188:191], v[90:93]
	v_mfma_f32_16x16x32_bf16 v[82:85], v[152:155], v[188:191], v[82:85]
	v_mfma_f32_16x16x32_bf16 v[110:113], v[192:195], v[160:163], v[110:113]
	v_mfma_f32_16x16x32_bf16 v[102:105], v[200:203], v[160:163], v[102:105]
	v_mfma_f32_16x16x32_bf16 v[94:97], v[192:195], v[168:171], v[94:97]
	v_mfma_f32_16x16x32_bf16 v[86:89], v[200:203], v[168:171], v[86:89]
	v_mfma_f32_16x16x32_bf16 v[78:81], v[192:195], v[176:179], v[78:81]
	v_mfma_f32_16x16x32_bf16 v[74:77], v[200:203], v[176:179], v[74:77]
	v_mfma_f32_16x16x32_bf16 v[70:73], v[192:195], v[184:187], v[70:73]
	v_mfma_f32_16x16x32_bf16 v[66:69], v[200:203], v[184:187], v[66:69]
	v_mfma_f32_16x16x32_bf16 v[110:113], v[196:199], v[164:167], v[110:113]
	v_mfma_f32_16x16x32_bf16 v[102:105], v[204:207], v[164:167], v[102:105]
	v_mfma_f32_16x16x32_bf16 v[94:97], v[196:199], v[172:175], v[94:97]
	v_mfma_f32_16x16x32_bf16 v[86:89], v[204:207], v[172:175], v[86:89]
	v_mfma_f32_16x16x32_bf16 v[78:81], v[196:199], v[180:183], v[78:81]
	v_mfma_f32_16x16x32_bf16 v[74:77], v[204:207], v[180:183], v[74:77]
	v_mfma_f32_16x16x32_bf16 v[70:73], v[196:199], v[188:191], v[70:73]
	v_mfma_f32_16x16x32_bf16 v[66:69], v[204:207], v[188:191], v[66:69]
	s_setprio 0
	s_barrier
	s_add_i32 s38, s38, s63
	v_lshl_add_u64 v[156:157], s[54:55], 0, v[0:1]
	s_mov_b32 m0, s38
	v_lshl_add_u64 v[210:211], s[54:55], 0, v[130:131]
	global_load_lds_dwordx4 v[156:157], off
	s_add_i32 m0, s38, 0x2000
	s_nop 0
	global_load_lds_dwordx4 v[210:211], off
	s_mov_b32 m0, s25
	v_lshl_add_u64 v[212:213], s[56:57], 0, v[0:1]
	global_load_lds_dwordx4 v[212:213], off
	v_lshl_add_u64 v[214:215], s[56:57], 0, v[130:131]
	s_mov_b32 m0, s27
	s_nop 0
	global_load_lds_dwordx4 v[214:215], off
	ds_read_b128 v[160:163], v139 offset:16384
	ds_read_b128 v[164:167], v139 offset:17408
	ds_read_b128 v[168:171], v139 offset:18432
	ds_read_b128 v[172:175], v139 offset:19456
	ds_read_b128 v[176:179], v139 offset:20480
	ds_read_b128 v[180:183], v139 offset:21504
	ds_read_b128 v[184:187], v139 offset:22528
	ds_read_b128 v[188:191], v139 offset:23552
	s_waitcnt vmcnt(4)
	s_waitcnt lgkmcnt(0)
	s_barrier
; #define PG8_STAGE(bufoff, gbase, voff) do { _Pragma("unroll") for (int _i = 0; _i < 2; ++_i) \
;         __builtin_amdgcn_global_load_lds((const unsigned*)((const char*)(gbase) + (voff)[_i]), (LAS unsigned*)(lds + (bufoff) + ldsw + _i * 8192), 16, 0, 0); } while (0)
; #define PG8_LDA(dst, b, h) do { _Pragma("unroll") for (int m = 0; m < 4; ++m) _Pragma("unroll") for (int k = 0; k < 2; ++k) dst[m][k] = *(const LAS bf16x8*)(lds + PG8_SA(b, h) + aoff + m * 2048 + k * 1024); } while (0)
; #define PG8_LDB(dst, b, h) do { _Pragma("unroll") for (int n = 0; n < 2; ++n) _Pragma("unroll") for (int k = 0; k < 2; ++k) dst[n][k] = *(const LAS bf16x8*)(lds + PG8_SB(b, h) + boff + n * 2048 + k * 1024); } while (0)
; #define PG8_MMA(ai, bj, At, Bt) do { __builtin_amdgcn_s_setprio(1); _Pragma("unroll") for (int m = 0; m < 4; ++m) _Pragma("unroll") for (int n = 0; n < 2; ++n) _Pragma("unroll") for (int k = 0; k < 2; ++k) \
;         acc[ai][bj][m][n] = __builtin_amdgcn_mfma_f32_16x16x32_bf16(Bt[n][k], At[m][k], acc[ai][bj][m][n], 0, 0, 0); __builtin_amdgcn_s_setprio(0); } while (0)
; #define PG8_WAIT_V(n) asm volatile("s_waitcnt vmcnt(" #n ")" ::: "memory")
; #define PG8_WAIT_L(n) asm volatile("s_waitcnt lgkmcnt(" #n ")" ::: "memory")
; #define PG8_BAR __builtin_amdgcn_s_barrier()
; #define PG8_SCHED __builtin_amdgcn_sched_barrier(0)
; template <class Epi, class Sched>
; __device__ __forceinline__ void gemm_phase(LAS unsigned char* lds, const Gemm g, const Sched& S, const Epi& E) {
;     ...
;             PG8_BAR; PG8_WAIT_L(0); PG8_MMA(1, 0, At, B0); PG8_BAR; PG8_SCHED;
;             PG8_STAGE(PG8_SB(0, 1), b2 + hstep, voffB);
;             PG8_WAIT_V(6); PG8_BAR; PG8_MMA(1, 1, At, B1); PG8_BAR;
;             PG8_LDB(B0, 1, 0); PG8_SCHED; PG8_LDA(At, 1, 0); PG8_STAGE(PG8_SA(0, 1), a2 + hstep, voffA);
;             PG8_WAIT_L(8); PG8_BAR; PG8_WAIT_L(0); PG8_MMA(0, 0, At, B0); PG8_BAR; PG8_SCHED;
;             PG8_LDB(B1, 1, 1); PG8_STAGE(PG8_SB(1, 0), b3, voffB);
;             PG8_BAR; PG8_WAIT_L(0); PG8_MMA(0, 1, At, B1); PG8_BAR;
	s_setprio 1
	v_mfma_f32_16x16x32_bf16 v[62:65], v[140:143], v[160:163], v[62:65]
	v_mfma_f32_16x16x32_bf16 v[58:61], v[148:151], v[160:163], v[58:61]
	v_mfma_f32_16x16x32_bf16 v[54:57], v[140:143], v[168:171], v[54:57]
	v_mfma_f32_16x16x32_bf16 v[50:53], v[148:151], v[168:171], v[50:53]
	v_mfma_f32_16x16x32_bf16 v[38:41], v[140:143], v[176:179], v[38:41]
	v_mfma_f32_16x16x32_bf16 v[34:37], v[148:151], v[176:179], v[34:37]
	v_mfma_f32_16x16x32_bf16 v[22:25], v[140:143], v[184:187], v[22:25]
	v_mfma_f32_16x16x32_bf16 v[18:21], v[148:151], v[184:187], v[18:21]
	v_mfma_f32_16x16x32_bf16 v[62:65], v[144:147], v[164:167], v[62:65]
	v_mfma_f32_16x16x32_bf16 v[58:61], v[152:155], v[164:167], v[58:61]
	v_mfma_f32_16x16x32_bf16 v[54:57], v[144:147], v[172:175], v[54:57]
	v_mfma_f32_16x16x32_bf16 v[50:53], v[152:155], v[172:175], v[50:53]
	v_mfma_f32_16x16x32_bf16 v[38:41], v[144:147], v[180:183], v[38:41]
	v_mfma_f32_16x16x32_bf16 v[34:37], v[152:155], v[180:183], v[34:37]
	v_mfma_f32_16x16x32_bf16 v[22:25], v[144:147], v[188:191], v[22:25]
	v_mfma_f32_16x16x32_bf16 v[18:21], v[152:155], v[188:191], v[18:21]
	v_mfma_f32_16x16x32_bf16 v[46:49], v[192:195], v[160:163], v[46:49]
	v_mfma_f32_16x16x32_bf16 v[42:45], v[200:203], v[160:163], v[42:45]
	v_mfma_f32_16x16x32_bf16 v[30:33], v[192:195], v[168:171], v[30:33]
	v_mfma_f32_16x16x32_bf16 v[26:29], v[200:203], v[168:171], v[26:29]
	v_mfma_f32_16x16x32_bf16 v[14:17], v[192:195], v[176:179], v[14:17]
	v_mfma_f32_16x16x32_bf16 v[10:13], v[200:203], v[176:179], v[10:13]
	v_mfma_f32_16x16x32_bf16 v[6:9], v[192:195], v[184:187], v[6:9]
	v_mfma_f32_16x16x32_bf16 v[2:5], v[200:203], v[184:187], v[2:5]
	v_mfma_f32_16x16x32_bf16 v[46:49], v[196:199], v[164:167], v[46:49]
	v_mfma_f32_16x16x32_bf16 v[42:45], v[204:207], v[164:167], v[42:45]
	v_mfma_f32_16x16x32_bf16 v[30:33], v[196:199], v[172:175], v[30:33]
	v_mfma_f32_16x16x32_bf16 v[26:29], v[204:207], v[172:175], v[26:29]
	v_mfma_f32_16x16x32_bf16 v[14:17], v[196:199], v[180:183], v[14:17]
	v_mfma_f32_16x16x32_bf16 v[10:13], v[204:207], v[180:183], v[10:13]
	v_mfma_f32_16x16x32_bf16 v[6:9], v[196:199], v[188:191], v[6:9]
	v_mfma_f32_16x16x32_bf16 v[2:5], v[204:207], v[188:191], v[2:5]
	s_setprio 0
	s_barrier
	s_add_u32 s38, s54, 0x200000
	s_addc_u32 s39, s55, 0
	s_add_i32 s50, s50, s63
	v_lshl_add_u64 v[140:141], s[38:39], 0, v[0:1]
	s_mov_b32 m0, s50
	s_nop 0
	global_load_lds_dwordx4 v[140:141], off
	v_lshl_add_u64 v[140:141], s[38:39], 0, v[130:131]
	s_add_i32 m0, s50, 0x2000
	s_nop 0
	global_load_lds_dwordx4 v[140:141], off
	s_add_u32 s38, s56, 0x200000
	s_addc_u32 s39, s57, 0
	s_mov_b32 m0, s64
	v_lshl_add_u64 v[192:193], s[38:39], 0, v[0:1]
	global_load_lds_dwordx4 v[192:193], off
	v_lshl_add_u64 v[192:193], s[38:39], 0, v[130:131]
	s_mov_b32 m0, s65
	s_nop 0
	global_load_lds_dwordx4 v[192:193], off
	s_add_i32 s50, 0, 0x18000
	v_add_u32_e32 v152, s50, v137
	ds_read_b128 v[140:143], v152
	ds_read_b128 v[144:147], v152 offset:1024
	ds_read_b128 v[148:151], v152 offset:2048
	ds_read_b128 v[152:155], v152 offset:3072
	ds_read_b128 v[160:163], v139 offset:32768
	ds_read_b128 v[164:167], v139 offset:33792
	ds_read_b128 v[168:171], v139 offset:34816
	ds_read_b128 v[172:175], v139 offset:35840
	ds_read_b128 v[176:179], v139 offset:36864
	ds_read_b128 v[180:183], v139 offset:37888
	ds_read_b128 v[184:187], v139 offset:38912
	ds_read_b128 v[188:191], v139 offset:39936
	s_add_i32 s51, 0, 0x1c000
	v_add_u32_e32 v204, s51, v137
	ds_read_b128 v[192:195], v204
	ds_read_b128 v[196:199], v204 offset:1024
	ds_read_b128 v[200:203], v204 offset:2048
	ds_read_b128 v[204:207], v204 offset:3072
	s_waitcnt lgkmcnt(4)
	s_barrier
	s_waitcnt lgkmcnt(0)
	s_setprio 1
	v_mfma_f32_16x16x32_bf16 v[126:129], v[140:143], v[160:163], v[126:129]
	v_mfma_f32_16x16x32_bf16 v[122:125], v[148:151], v[160:163], v[122:125]
	v_mfma_f32_16x16x32_bf16 v[118:121], v[140:143], v[168:171], v[118:121]
	v_mfma_f32_16x16x32_bf16 v[114:117], v[148:151], v[168:171], v[114:117]
	v_mfma_f32_16x16x32_bf16 v[106:109], v[140:143], v[176:179], v[106:109]
	v_mfma_f32_16x16x32_bf16 v[98:101], v[148:151], v[176:179], v[98:101]
	v_mfma_f32_16x16x32_bf16 v[90:93], v[140:143], v[184:187], v[90:93]
	v_mfma_f32_16x16x32_bf16 v[82:85], v[148:151], v[184:187], v[82:85]
	v_mfma_f32_16x16x32_bf16 v[126:129], v[144:147], v[164:167], v[126:129]
	v_mfma_f32_16x16x32_bf16 v[122:125], v[152:155], v[164:167], v[122:125]
	v_mfma_f32_16x16x32_bf16 v[118:121], v[144:147], v[172:175], v[118:121]
	v_mfma_f32_16x16x32_bf16 v[114:117], v[152:155], v[172:175], v[114:117]
	v_mfma_f32_16x16x32_bf16 v[106:109], v[144:147], v[180:183], v[106:109]
	v_mfma_f32_16x16x32_bf16 v[98:101], v[152:155], v[180:183], v[98:101]
	v_mfma_f32_16x16x32_bf16 v[90:93], v[144:147], v[188:191], v[90:93]
	v_mfma_f32_16x16x32_bf16 v[82:85], v[152:155], v[188:191], v[82:85]
	v_mfma_f32_16x16x32_bf16 v[110:113], v[192:195], v[160:163], v[110:113]
	v_mfma_f32_16x16x32_bf16 v[102:105], v[200:203], v[160:163], v[102:105]
	v_mfma_f32_16x16x32_bf16 v[94:97], v[192:195], v[168:171], v[94:97]
	v_mfma_f32_16x16x32_bf16 v[86:89], v[200:203], v[168:171], v[86:89]
	v_mfma_f32_16x16x32_bf16 v[78:81], v[192:195], v[176:179], v[78:81]
	v_mfma_f32_16x16x32_bf16 v[74:77], v[200:203], v[176:179], v[74:77]
	v_mfma_f32_16x16x32_bf16 v[70:73], v[192:195], v[184:187], v[70:73]
	v_mfma_f32_16x16x32_bf16 v[66:69], v[200:203], v[184:187], v[66:69]
	v_mfma_f32_16x16x32_bf16 v[110:113], v[196:199], v[164:167], v[110:113]
	v_mfma_f32_16x16x32_bf16 v[102:105], v[204:207], v[164:167], v[102:105]
	v_mfma_f32_16x16x32_bf16 v[94:97], v[196:199], v[172:175], v[94:97]
	v_mfma_f32_16x16x32_bf16 v[86:89], v[204:207], v[172:175], v[86:89]
	v_mfma_f32_16x16x32_bf16 v[78:81], v[196:199], v[180:183], v[78:81]
	v_mfma_f32_16x16x32_bf16 v[74:77], v[204:207], v[180:183], v[74:77]
	v_mfma_f32_16x16x32_bf16 v[70:73], v[196:199], v[188:191], v[70:73]
	v_mfma_f32_16x16x32_bf16 v[66:69], v[204:207], v[188:191], v[66:69]
	s_setprio 0
	s_barrier
; #define PG8_STAGE(bufoff, gbase, voff) do { _Pragma("unroll") for (int _i = 0; _i < 2; ++_i) \
;         __builtin_amdgcn_global_load_lds((const unsigned*)((const char*)(gbase) + (voff)[_i]), (LAS unsigned*)(lds + (bufoff) + ldsw + _i * 8192), 16, 0, 0); } while (0)
; #define PG8_LDA(dst, b, h) do { _Pragma("unroll") for (int m = 0; m < 4; ++m) _Pragma("unroll") for (int k = 0; k < 2; ++k) dst[m][k] = *(const LAS bf16x8*)(lds + PG8_SA(b, h) + aoff + m * 2048 + k * 1024); } while (0)
; #define PG8_MMA(ai, bj, At, Bt) do { __builtin_amdgcn_s_setprio(1); _Pragma("unroll") for (int m = 0; m < 4; ++m) _Pragma("unroll") for (int n = 0; n < 2; ++n) _Pragma("unroll") for (int k = 0; k < 2; ++k) \
;         acc[ai][bj][m][n] = __builtin_amdgcn_mfma_f32_16x16x32_bf16(Bt[n][k], At[m][k], acc[ai][bj][m][n], 0, 0, 0); __builtin_amdgcn_s_setprio(0); } while (0)
; #define PG8_WAIT_V(n) asm volatile("s_waitcnt vmcnt(" #n ")" ::: "memory")
; #define PG8_WAIT_L(n) asm volatile("s_waitcnt lgkmcnt(" #n ")" ::: "memory")
; #define PG8_BAR __builtin_amdgcn_s_barrier()
; #define PG8_SCHED __builtin_amdgcn_sched_barrier(0)
;     __device__ __forceinline__ void operator()(const f32x4 (&acc)[2][2][4][2], const Unit& u, int wr, int wc, int fr, int fq) const {
;         const int row0 = u.pm * BM + wr * 64 + fr, col0 = u.pn * BM + wc * 32 + 4 * fq;
;         float* base = part + (size_t)u.ks * Mp * ldc;
; #pragma unroll
;         for (int ai = 0; ai < 2; ++ai)
; #pragma unroll
;             for (int m = 0; m < 4; ++m) { float* rowp = base + (size_t)(row0 + ai * HALF + m * 16) * ldc + col0;
; #pragma unroll
;                 for (int bj = 0; bj < 2; ++bj)
; #pragma unroll
;                     for (int n = 0; n < 2; ++n) *(f32x4*)(rowp + bj * HALF + n * 16) = acc[ai][bj][m][n]; }
;     }
; template <class Epi, class Sched>
; __device__ __forceinline__ void gemm_phase(LAS unsigned char* lds, const Gemm g, const Sched& S, const Epi& E) {
;     ...
;             PG8_BAR; PG8_WAIT_L(0); PG8_MMA(0, 1, At, B1); PG8_BAR;
;             PG8_LDA(At, 1, 1); PG8_STAGE(PG8_SA(1, 0), a3, voffA);
;             PG8_BAR; PG8_WAIT_L(0); PG8_MMA(1, 0, At, B0); PG8_BAR; PG8_SCHED;
;             PG8_STAGE(PG8_SB(1, 1), b3 + hstep, voffB);
;             PG8_WAIT_V(6); PG8_BAR; PG8_MMA(1, 1, At, B1); PG8_BAR;
;         }
;         E(acc, cur, wr, wc, fr, fq);
	s_add_i32 s38, s50, s63
	v_lshl_add_u64 v[156:157], v[156:157], 0, s[36:37]
	s_mov_b32 m0, s38
	s_nop 0
	global_load_lds_dwordx4 v[156:157], off
	v_lshl_add_u64 v[156:157], v[210:211], 0, s[36:37]
	s_add_i32 m0, s38, 0x2000
	s_nop 0
	global_load_lds_dwordx4 v[156:157], off
	s_mov_b32 m0, s66
	v_lshl_add_u64 v[156:157], v[212:213], 0, s[36:37]
	global_load_lds_dwordx4 v[156:157], off
	v_lshl_add_u64 v[156:157], v[214:215], 0, s[36:37]
	s_mov_b32 m0, s67
	s_nop 0
	global_load_lds_dwordx4 v[156:157], off
	ds_read_b128 v[160:163], v139 offset:49152
	ds_read_b128 v[164:167], v139 offset:50176
	ds_read_b128 v[168:171], v139 offset:51200
	ds_read_b128 v[172:175], v139 offset:52224
	ds_read_b128 v[176:179], v139 offset:53248
	ds_read_b128 v[180:183], v139 offset:54272
	ds_read_b128 v[184:187], v139 offset:55296
	ds_read_b128 v[188:191], v139 offset:56320
	s_waitcnt vmcnt(4)
	s_waitcnt lgkmcnt(0)
	s_barrier
	s_setprio 1
	v_mfma_f32_16x16x32_bf16 v[62:65], v[140:143], v[160:163], v[62:65]
	v_mfma_f32_16x16x32_bf16 v[58:61], v[148:151], v[160:163], v[58:61]
	v_mfma_f32_16x16x32_bf16 v[54:57], v[140:143], v[168:171], v[54:57]
	v_mfma_f32_16x16x32_bf16 v[50:53], v[148:151], v[168:171], v[50:53]
	v_mfma_f32_16x16x32_bf16 v[38:41], v[140:143], v[176:179], v[38:41]
	v_mfma_f32_16x16x32_bf16 v[34:37], v[148:151], v[176:179], v[34:37]
	v_mfma_f32_16x16x32_bf16 v[22:25], v[140:143], v[184:187], v[22:25]
	v_mfma_f32_16x16x32_bf16 v[18:21], v[148:151], v[184:187], v[18:21]
	v_mfma_f32_16x16x32_bf16 v[62:65], v[144:147], v[164:167], v[62:65]
	v_mfma_f32_16x16x32_bf16 v[58:61], v[152:155], v[164:167], v[58:61]
	v_mfma_f32_16x16x32_bf16 v[54:57], v[144:147], v[172:175], v[54:57]
	v_mfma_f32_16x16x32_bf16 v[50:53], v[152:155], v[172:175], v[50:53]
	v_mfma_f32_16x16x32_bf16 v[38:41], v[144:147], v[180:183], v[38:41]
	v_mfma_f32_16x16x32_bf16 v[34:37], v[152:155], v[180:183], v[34:37]
	v_mfma_f32_16x16x32_bf16 v[22:25], v[144:147], v[188:191], v[22:25]
	v_mfma_f32_16x16x32_bf16 v[18:21], v[152:155], v[188:191], v[18:21]
	v_mfma_f32_16x16x32_bf16 v[46:49], v[192:195], v[160:163], v[46:49]
	v_mfma_f32_16x16x32_bf16 v[42:45], v[200:203], v[160:163], v[42:45]
	v_mfma_f32_16x16x32_bf16 v[30:33], v[192:195], v[168:171], v[30:33]
	v_mfma_f32_16x16x32_bf16 v[26:29], v[200:203], v[168:171], v[26:29]
	v_mfma_f32_16x16x32_bf16 v[14:17], v[192:195], v[176:179], v[14:17]
	v_mfma_f32_16x16x32_bf16 v[10:13], v[200:203], v[176:179], v[10:13]
	v_mfma_f32_16x16x32_bf16 v[6:9], v[192:195], v[184:187], v[6:9]
	v_mfma_f32_16x16x32_bf16 v[2:5], v[200:203], v[184:187], v[2:5]
	v_mfma_f32_16x16x32_bf16 v[46:49], v[196:199], v[164:167], v[46:49]
	v_mfma_f32_16x16x32_bf16 v[42:45], v[204:207], v[164:167], v[42:45]
	v_mfma_f32_16x16x32_bf16 v[30:33], v[196:199], v[172:175], v[30:33]
	v_mfma_f32_16x16x32_bf16 v[26:29], v[204:207], v[172:175], v[26:29]
	v_mfma_f32_16x16x32_bf16 v[14:17], v[196:199], v[180:183], v[14:17]
	v_mfma_f32_16x16x32_bf16 v[10:13], v[204:207], v[180:183], v[10:13]
	v_mfma_f32_16x16x32_bf16 v[6:9], v[196:199], v[188:191], v[6:9]
	v_mfma_f32_16x16x32_bf16 v[2:5], v[204:207], v[188:191], v[2:5]
	s_setprio 0
	s_add_i32 s71, s71, 2
	s_add_u32 s69, s69, 0x100
	s_addc_u32 s70, s70, 0
	s_cmp_gt_u32 s71, 29
	s_mov_b64 s[50:51], s[52:53]
	s_barrier
	s_cbranch_scc0 .LBB0_58
	s_ashr_i32 s11, s10, 31
	s_lshl_b64 s[10:11], s[10:11], 24
	v_lshl_or_b32 v140, s26, 8, v138
	s_add_u32 s10, s8, s10
	v_lshl_add_u32 v142, s24, 8, v136
	s_addc_u32 s11, s9, s11
	v_ashrrev_i32_e32 v141, 31, v140
	v_ashrrev_i32_e32 v143, 31, v142
	v_lshl_add_u64 v[140:141], v[140:141], 2, s[10:11]
	v_lshlrev_b64 v[144:145], 13, v[142:143]
	v_lshl_add_u64 v[144:145], v[140:141], 0, v[144:145]
	global_store_dwordx4 v[144:145], v[126:129], off
	global_store_dwordx4 v[144:145], v[122:125], off offset:64
	global_store_dwordx4 v[144:145], v[110:113], off offset:512
	global_store_dwordx4 v[144:145], v[102:105], off offset:576
	s_mov_b64 s[10:11], 0x100000
	s_mov_b32 s26, s40
	v_or_b32_e32 v102, 16, v142
	v_ashrrev_i32_e32 v103, 31, v102
	v_lshlrev_b64 v[102:103], 13, v[102:103]
	v_lshl_add_u64 v[102:103], v[140:141], 0, v[102:103]
	global_store_dwordx4 v[102:103], v[118:121], off
	global_store_dwordx4 v[102:103], v[114:117], off offset:64
	global_store_dwordx4 v[102:103], v[94:97], off offset:512
	global_store_dwordx4 v[102:103], v[86:89], off offset:576
	s_mov_b32 s24, s42
	s_mov_b64 s[52:53], s[48:49]
	v_or_b32_e32 v86, 32, v142
	v_ashrrev_i32_e32 v87, 31, v86
	v_lshlrev_b64 v[86:87], 13, v[86:87]
	v_lshl_add_u64 v[86:87], v[140:141], 0, v[86:87]
	global_store_dwordx4 v[86:87], v[106:109], off
	global_store_dwordx4 v[86:87], v[98:101], off offset:64
	global_store_dwordx4 v[86:87], v[78:81], off offset:512
	global_store_dwordx4 v[86:87], v[74:77], off offset:576
	s_mov_b64 s[50:51], s[46:47]
	s_nop 0
	v_or_b32_e32 v74, 48, v142
	v_ashrrev_i32_e32 v75, 31, v74
	v_lshlrev_b64 v[74:75], 13, v[74:75]
	v_lshl_add_u64 v[74:75], v[140:141], 0, v[74:75]
	global_store_dwordx4 v[74:75], v[90:93], off
	global_store_dwordx4 v[74:75], v[82:85], off offset:64
	global_store_dwordx4 v[74:75], v[70:73], off offset:512
	global_store_dwordx4 v[74:75], v[66:69], off offset:576
	s_nop 1
	v_add_co_u32_e32 v68, vcc, s93, v144
	v_lshl_add_u64 v[66:67], v[144:145], 0, s[10:11]
	s_nop 0
	v_addc_co_u32_e32 v69, vcc, 0, v145, vcc
	s_mov_b64 s[10:11], 0x120000
	global_store_dwordx4 v[68:69], v[62:65], off
	global_store_dwordx4 v[66:67], v[58:61], off offset:64
	global_store_dwordx4 v[66:67], v[46:49], off offset:512
	global_store_dwordx4 v[66:67], v[42:45], off offset:576
	s_nop 1
	v_lshl_add_u64 v[42:43], v[144:145], 0, s[10:11]
	s_mov_b32 s10, 0x120000
	v_add_co_u32_e32 v44, vcc, s10, v144
	s_mov_b64 s[10:11], 0x140000
	s_nop 0
	v_addc_co_u32_e32 v45, vcc, 0, v145, vcc
	global_store_dwordx4 v[44:45], v[54:57], off
	global_store_dwordx4 v[42:43], v[50:53], off offset:64
	global_store_dwordx4 v[42:43], v[30:33], off offset:512
	global_store_dwordx4 v[42:43], v[26:29], off offset:576
	s_nop 1
	v_lshl_add_u64 v[26:27], v[144:145], 0, s[10:11]
	s_mov_b32 s10, 0x140000
	v_add_co_u32_e32 v28, vcc, s10, v144
	s_mov_b64 s[10:11], 0x160000
	s_nop 0
	v_addc_co_u32_e32 v29, vcc, 0, v145, vcc
	global_store_dwordx4 v[28:29], v[38:41], off
	global_store_dwordx4 v[26:27], v[34:37], off offset:64
	global_store_dwordx4 v[26:27], v[14:17], off offset:512
	global_store_dwordx4 v[26:27], v[10:13], off offset:576
	s_nop 1
	v_add_co_u32_e32 v12, vcc, 0x160000, v144
	v_lshl_add_u64 v[10:11], v[144:145], 0, s[10:11]
	s_nop 0
	v_addc_co_u32_e32 v13, vcc, 0, v145, vcc
	s_and_b64 vcc, exec, s[44:45]
	s_mov_b32 s10, s28
	global_store_dwordx4 v[12:13], v[22:25], off
	global_store_dwordx4 v[10:11], v[18:21], off offset:64
	global_store_dwordx4 v[10:11], v[6:9], off offset:512
	global_store_dwordx4 v[10:11], v[2:5], off offset:576
	s_cbranch_vccz .LBB0_55
	s_waitcnt vmcnt(0)
	s_cmpk_gt_u32 s60, 0xff
	s_cbranch_scc1 .LBB0_62
	s_barrier

; #define PG8_STAGE(bufoff, gbase, voff) do { _Pragma("unroll") for (int _i = 0; _i < 2; ++_i) \
;         __builtin_amdgcn_global_load_lds((const unsigned*)((const char*)(gbase) + (voff)[_i]), (LAS unsigned*)(lds + (bufoff) + ldsw + _i * 8192), 16, 0, 0); } while (0)
; #define PG8_LDA(dst, b, h) do { _Pragma("unroll") for (int m = 0; m < 4; ++m) _Pragma("unroll") for (int k = 0; k < 2; ++k) dst[m][k] = *(const LAS bf16x8*)(lds + PG8_SA(b, h) + aoff + m * 2048 + k * 1024); } while (0)
; #define PG8_LDB(dst, b, h) do { _Pragma("unroll") for (int n = 0; n < 2; ++n) _Pragma("unroll") for (int k = 0; k < 2; ++k) dst[n][k] = *(const LAS bf16x8*)(lds + PG8_SB(b, h) + boff + n * 2048 + k * 1024); } while (0)
; #define PG8_MMA(ai, bj, At, Bt) do { __builtin_amdgcn_s_setprio(1); _Pragma("unroll") for (int m = 0; m < 4; ++m) _Pragma("unroll") for (int n = 0; n < 2; ++n) _Pragma("unroll") for (int k = 0; k < 2; ++k) \
;         acc[ai][bj][m][n] = __builtin_amdgcn_mfma_f32_16x16x32_bf16(Bt[n][k], At[m][k], acc[ai][bj][m][n], 0, 0, 0); __builtin_amdgcn_s_setprio(0); } while (0)
; #define PG8_WAIT_L(n) asm volatile("s_waitcnt lgkmcnt(" #n ")" ::: "memory")
; #define PG8_BAR __builtin_amdgcn_s_barrier()
; #define PG8_SCHED __builtin_amdgcn_sched_barrier(0)
; template <class Epi, class Sched>
; __device__ __forceinline__ void gemm_phase(LAS unsigned char* lds, const Gemm g, const Sched& S, const Epi& E) {
;     ...
;             PG8_LDB(B0, 0, 0); PG8_SCHED; PG8_LDA(At, 0, 0); PG8_STAGE(PG8_SA(1, 1), a1 + hstep, voffA);
;             PG8_WAIT_L(8); PG8_BAR; PG8_WAIT_L(0); PG8_MMA(0, 0, At, B0); PG8_BAR; PG8_SCHED;
;             PG8_LDB(B1, 0, 1); PG8_STAGE(PG8_SB(0, 0), b2, voffB);
;             PG8_BAR; PG8_WAIT_L(0); PG8_MMA(0, 1, At, B1); PG8_BAR;
;             PG8_LDA(At, 0, 1); PG8_STAGE(PG8_SA(0, 0), a2, voffA);
;             PG8_BAR; PG8_WAIT_L(0); PG8_MMA(1, 0, At, B0); PG8_BAR; PG8_SCHED;
;             PG8_STAGE(PG8_SB(0, 1), b2 + hstep, voffB);
.LBB0_73:
	s_add_u32 s100, s71, 0x7ff80
	s_addc_u32 s101, s72, 0
	v_lshl_add_u64 v[140:141], s[100:101], 0, v[0:1]
	s_add_i32 m0, s56, 0x1c000
	s_nop 0
	global_load_lds_dwordx4 v[140:141], off
	v_lshl_add_u64 v[140:141], s[100:101], 0, v[130:131]
	s_add_i32 m0, s56, 0x1e000
	s_nop 0
	global_load_lds_dwordx4 v[140:141], off
	s_add_u32 s38, s46, 0xfff80080
	s_addc_u32 s39, s47, -1
	s_cmp_eq_u32 s73, 28
	s_cselect_b32 s51, s29, s39
	s_cselect_b32 s50, s69, s38
	s_cselect_b32 s49, s27, s72
	s_cselect_b32 s48, s70, s71
	v_lshl_add_u64 v[140:141], s[46:47], 0, v[138:139]
	s_add_i32 m0, s9, 0xc000
	s_nop 0
	global_load_lds_dwordx4 v[140:141], off
	v_lshl_add_u64 v[140:141], s[46:47], 0, v[136:137]
	s_add_i32 m0, s9, 0xe000
	s_nop 0
	global_load_lds_dwordx4 v[140:141], off
	s_add_i32 s74, 0, 0x10000
	v_add_u32_e32 v140, s74, v143
	ds_read_b128 v[146:149], v140
	ds_read_b128 v[150:153], v140 offset:1024
	ds_read_b128 v[154:157], v140 offset:2048
	ds_read_b128 v[160:163], v140 offset:3072
	ds_read_b128 v[164:167], v145
	ds_read_b128 v[168:171], v145 offset:1024
	ds_read_b128 v[172:175], v145 offset:2048
	ds_read_b128 v[176:179], v145 offset:3072
	ds_read_b128 v[180:183], v145 offset:4096
	ds_read_b128 v[184:187], v145 offset:5120
	ds_read_b128 v[188:191], v145 offset:6144
	ds_read_b128 v[192:195], v145 offset:7168
	s_add_i32 s75, 0, 0x14000
	v_add_u32_e32 v140, s75, v143
	ds_read_b128 v[196:199], v140
	ds_read_b128 v[200:203], v140 offset:1024
	ds_read_b128 v[204:207], v140 offset:2048
	ds_read_b128 v[210:213], v140 offset:3072
	s_waitcnt lgkmcnt(4)
	s_barrier
	s_waitcnt lgkmcnt(0)
	s_setprio 1
	v_mfma_f32_16x16x32_bf16 v[126:129], v[146:149], v[164:167], v[126:129]
	v_mfma_f32_16x16x32_bf16 v[122:125], v[154:157], v[164:167], v[122:125]
	v_mfma_f32_16x16x32_bf16 v[110:113], v[146:149], v[172:175], v[110:113]
	v_mfma_f32_16x16x32_bf16 v[106:109], v[154:157], v[172:175], v[106:109]
	v_mfma_f32_16x16x32_bf16 v[94:97], v[146:149], v[180:183], v[94:97]
	v_mfma_f32_16x16x32_bf16 v[90:93], v[154:157], v[180:183], v[90:93]
	v_mfma_f32_16x16x32_bf16 v[78:81], v[146:149], v[188:191], v[78:81]
	v_mfma_f32_16x16x32_bf16 v[74:77], v[154:157], v[188:191], v[74:77]
	v_mfma_f32_16x16x32_bf16 v[126:129], v[150:153], v[168:171], v[126:129]
	v_mfma_f32_16x16x32_bf16 v[122:125], v[160:163], v[168:171], v[122:125]
	v_mfma_f32_16x16x32_bf16 v[110:113], v[150:153], v[176:179], v[110:113]
	v_mfma_f32_16x16x32_bf16 v[106:109], v[160:163], v[176:179], v[106:109]
	v_mfma_f32_16x16x32_bf16 v[94:97], v[150:153], v[184:187], v[94:97]
	v_mfma_f32_16x16x32_bf16 v[90:93], v[160:163], v[184:187], v[90:93]
	v_mfma_f32_16x16x32_bf16 v[78:81], v[150:153], v[192:195], v[78:81]
	v_mfma_f32_16x16x32_bf16 v[74:77], v[160:163], v[192:195], v[74:77]
	v_mfma_f32_16x16x32_bf16 v[118:121], v[196:199], v[164:167], v[118:121]
	v_mfma_f32_16x16x32_bf16 v[114:117], v[204:207], v[164:167], v[114:117]
	v_mfma_f32_16x16x32_bf16 v[102:105], v[196:199], v[172:175], v[102:105]
	v_mfma_f32_16x16x32_bf16 v[98:101], v[204:207], v[172:175], v[98:101]
	v_mfma_f32_16x16x32_bf16 v[86:89], v[196:199], v[180:183], v[86:89]
	v_mfma_f32_16x16x32_bf16 v[82:85], v[204:207], v[180:183], v[82:85]
	v_mfma_f32_16x16x32_bf16 v[70:73], v[196:199], v[188:191], v[70:73]
	v_mfma_f32_16x16x32_bf16 v[66:69], v[204:207], v[188:191], v[66:69]
	v_mfma_f32_16x16x32_bf16 v[118:121], v[200:203], v[168:171], v[118:121]
	v_mfma_f32_16x16x32_bf16 v[114:117], v[210:213], v[168:171], v[114:117]
	v_mfma_f32_16x16x32_bf16 v[102:105], v[200:203], v[176:179], v[102:105]
	v_mfma_f32_16x16x32_bf16 v[98:101], v[210:213], v[176:179], v[98:101]
	v_mfma_f32_16x16x32_bf16 v[86:89], v[200:203], v[184:187], v[86:89]
	v_mfma_f32_16x16x32_bf16 v[82:85], v[210:213], v[184:187], v[82:85]
	v_mfma_f32_16x16x32_bf16 v[70:73], v[200:203], v[192:195], v[70:73]
	v_mfma_f32_16x16x32_bf16 v[66:69], v[210:213], v[192:195], v[66:69]
	s_setprio 0
	s_barrier
	s_add_i32 s38, s74, s56
	v_lshl_add_u64 v[140:141], s[48:49], 0, v[0:1]
	s_mov_b32 m0, s38
	v_lshl_add_u64 v[214:215], s[48:49], 0, v[130:131]
	global_load_lds_dwordx4 v[140:141], off
	s_add_i32 m0, s38, 0x2000
	s_nop 0
	global_load_lds_dwordx4 v[214:215], off
	s_mov_b32 m0, s9
	v_lshl_add_u64 v[216:217], s[50:51], 0, v[134:135]
	global_load_lds_dwordx4 v[216:217], off
	v_lshl_add_u64 v[224:225], s[50:51], 0, v[132:133]
	s_mov_b32 m0, s60
	s_nop 0
	global_load_lds_dwordx4 v[224:225], off
	ds_read_b128 v[164:167], v145 offset:16384
	ds_read_b128 v[168:171], v145 offset:17408
	ds_read_b128 v[172:175], v145 offset:18432
	ds_read_b128 v[176:179], v145 offset:19456
	ds_read_b128 v[180:183], v145 offset:20480
	ds_read_b128 v[184:187], v145 offset:21504
	ds_read_b128 v[188:191], v145 offset:22528
	ds_read_b128 v[192:195], v145 offset:23552
	s_waitcnt vmcnt(4)
	s_waitcnt lgkmcnt(0)
	s_barrier
; #define PG8_STAGE(bufoff, gbase, voff) do { _Pragma("unroll") for (int _i = 0; _i < 2; ++_i) \
;         __builtin_amdgcn_global_load_lds((const unsigned*)((const char*)(gbase) + (voff)[_i]), (LAS unsigned*)(lds + (bufoff) + ldsw + _i * 8192), 16, 0, 0); } while (0)
; #define PG8_LDA(dst, b, h) do { _Pragma("unroll") for (int m = 0; m < 4; ++m) _Pragma("unroll") for (int k = 0; k < 2; ++k) dst[m][k] = *(const LAS bf16x8*)(lds + PG8_SA(b, h) + aoff + m * 2048 + k * 1024); } while (0)
; #define PG8_LDB(dst, b, h) do { _Pragma("unroll") for (int n = 0; n < 2; ++n) _Pragma("unroll") for (int k = 0; k < 2; ++k) dst[n][k] = *(const LAS bf16x8*)(lds + PG8_SB(b, h) + boff + n * 2048 + k * 1024); } while (0)
; #define PG8_MMA(ai, bj, At, Bt) do { __builtin_amdgcn_s_setprio(1); _Pragma("unroll") for (int m = 0; m < 4; ++m) _Pragma("unroll") for (int n = 0; n < 2; ++n) _Pragma("unroll") for (int k = 0; k < 2; ++k) \
;         acc[ai][bj][m][n] = __builtin_amdgcn_mfma_f32_16x16x32_bf16(Bt[n][k], At[m][k], acc[ai][bj][m][n], 0, 0, 0); __builtin_amdgcn_s_setprio(0); } while (0)
; #define PG8_WAIT_V(n) asm volatile("s_waitcnt vmcnt(" #n ")" ::: "memory")
; #define PG8_WAIT_L(n) asm volatile("s_waitcnt lgkmcnt(" #n ")" ::: "memory")
; #define PG8_BAR __builtin_amdgcn_s_barrier()
; #define PG8_SCHED __builtin_amdgcn_sched_barrier(0)
; template <class Epi, class Sched>
; __device__ __forceinline__ void gemm_phase(LAS unsigned char* lds, const Gemm g, const Sched& S, const Epi& E) {
;     ...
;             PG8_BAR; PG8_WAIT_L(0); PG8_MMA(1, 0, At, B0); PG8_BAR; PG8_SCHED;
;             PG8_STAGE(PG8_SB(0, 1), b2 + hstep, voffB);
;             PG8_WAIT_V(6); PG8_BAR; PG8_MMA(1, 1, At, B1); PG8_BAR;
;             PG8_LDB(B0, 1, 0); PG8_SCHED; PG8_LDA(At, 1, 0); PG8_STAGE(PG8_SA(0, 1), a2 + hstep, voffA);
;             PG8_WAIT_L(8); PG8_BAR; PG8_WAIT_L(0); PG8_MMA(0, 0, At, B0); PG8_BAR; PG8_SCHED;
;             PG8_LDB(B1, 1, 1); PG8_STAGE(PG8_SB(1, 0), b3, voffB);
;             PG8_BAR; PG8_WAIT_L(0); PG8_MMA(0, 1, At, B1); PG8_BAR;
	s_setprio 1
	v_mfma_f32_16x16x32_bf16 v[62:65], v[146:149], v[164:167], v[62:65]
	v_mfma_f32_16x16x32_bf16 v[58:61], v[154:157], v[164:167], v[58:61]
	v_mfma_f32_16x16x32_bf16 v[46:49], v[146:149], v[172:175], v[46:49]
	v_mfma_f32_16x16x32_bf16 v[42:45], v[154:157], v[172:175], v[42:45]
	v_mfma_f32_16x16x32_bf16 v[30:33], v[146:149], v[180:183], v[30:33]
	v_mfma_f32_16x16x32_bf16 v[26:29], v[154:157], v[180:183], v[26:29]
	v_mfma_f32_16x16x32_bf16 v[14:17], v[146:149], v[188:191], v[14:17]
	v_mfma_f32_16x16x32_bf16 v[10:13], v[154:157], v[188:191], v[10:13]
	v_mfma_f32_16x16x32_bf16 v[62:65], v[150:153], v[168:171], v[62:65]
	v_mfma_f32_16x16x32_bf16 v[58:61], v[160:163], v[168:171], v[58:61]
	v_mfma_f32_16x16x32_bf16 v[46:49], v[150:153], v[176:179], v[46:49]
	v_mfma_f32_16x16x32_bf16 v[42:45], v[160:163], v[176:179], v[42:45]
	v_mfma_f32_16x16x32_bf16 v[30:33], v[150:153], v[184:187], v[30:33]
	v_mfma_f32_16x16x32_bf16 v[26:29], v[160:163], v[184:187], v[26:29]
	v_mfma_f32_16x16x32_bf16 v[14:17], v[150:153], v[192:195], v[14:17]
	v_mfma_f32_16x16x32_bf16 v[10:13], v[160:163], v[192:195], v[10:13]
	v_mfma_f32_16x16x32_bf16 v[54:57], v[196:199], v[164:167], v[54:57]
	v_mfma_f32_16x16x32_bf16 v[50:53], v[204:207], v[164:167], v[50:53]
	v_mfma_f32_16x16x32_bf16 v[38:41], v[196:199], v[172:175], v[38:41]
	v_mfma_f32_16x16x32_bf16 v[34:37], v[204:207], v[172:175], v[34:37]
	v_mfma_f32_16x16x32_bf16 v[22:25], v[196:199], v[180:183], v[22:25]
	v_mfma_f32_16x16x32_bf16 v[18:21], v[204:207], v[180:183], v[18:21]
	v_mfma_f32_16x16x32_bf16 v[6:9], v[196:199], v[188:191], v[6:9]
	v_mfma_f32_16x16x32_bf16 v[2:5], v[204:207], v[188:191], v[2:5]
	v_mfma_f32_16x16x32_bf16 v[54:57], v[200:203], v[168:171], v[54:57]
	v_mfma_f32_16x16x32_bf16 v[50:53], v[210:213], v[168:171], v[50:53]
	v_mfma_f32_16x16x32_bf16 v[38:41], v[200:203], v[176:179], v[38:41]
	v_mfma_f32_16x16x32_bf16 v[34:37], v[210:213], v[176:179], v[34:37]
	v_mfma_f32_16x16x32_bf16 v[22:25], v[200:203], v[184:187], v[22:25]
	v_mfma_f32_16x16x32_bf16 v[18:21], v[210:213], v[184:187], v[18:21]
	v_mfma_f32_16x16x32_bf16 v[6:9], v[200:203], v[192:195], v[6:9]
	v_mfma_f32_16x16x32_bf16 v[2:5], v[210:213], v[192:195], v[2:5]
	s_setprio 0
	s_barrier
	s_add_u32 s38, s48, 0x80000
	s_addc_u32 s39, s49, 0
	s_add_i32 s74, s75, s56
	v_lshl_add_u64 v[146:147], s[38:39], 0, v[0:1]
	s_mov_b32 m0, s74
	s_nop 0
	global_load_lds_dwordx4 v[146:147], off
	v_lshl_add_u64 v[146:147], s[38:39], 0, v[130:131]
	s_add_i32 m0, s74, 0x2000
	s_nop 0
	global_load_lds_dwordx4 v[146:147], off
	s_add_u32 s38, s50, 0x80000
	s_addc_u32 s39, s51, 0
	s_mov_b32 m0, s61
	v_lshl_add_u64 v[196:197], s[38:39], 0, v[134:135]
	global_load_lds_dwordx4 v[196:197], off
	v_lshl_add_u64 v[196:197], s[38:39], 0, v[132:133]
	s_mov_b32 m0, s62
	s_nop 0
	global_load_lds_dwordx4 v[196:197], off
	s_add_i32 s74, 0, 0x18000
	v_add_u32_e32 v160, s74, v143
	ds_read_b128 v[146:149], v160
	ds_read_b128 v[150:153], v160 offset:1024
	ds_read_b128 v[154:157], v160 offset:2048
	ds_read_b128 v[160:163], v160 offset:3072
	ds_read_b128 v[164:167], v145 offset:32768
	ds_read_b128 v[168:171], v145 offset:33792
	ds_read_b128 v[172:175], v145 offset:34816
	ds_read_b128 v[176:179], v145 offset:35840
	ds_read_b128 v[180:183], v145 offset:36864
	ds_read_b128 v[184:187], v145 offset:37888
	ds_read_b128 v[188:191], v145 offset:38912
	ds_read_b128 v[192:195], v145 offset:39936
	s_add_i32 s50, 0, 0x1c000
	v_add_u32_e32 v210, s50, v143
	ds_read_b128 v[196:199], v210
	ds_read_b128 v[200:203], v210 offset:1024
	ds_read_b128 v[204:207], v210 offset:2048
	ds_read_b128 v[210:213], v210 offset:3072
	s_waitcnt lgkmcnt(4)
	s_barrier
	s_waitcnt lgkmcnt(0)
	s_setprio 1
	v_mfma_f32_16x16x32_bf16 v[126:129], v[146:149], v[164:167], v[126:129]
	v_mfma_f32_16x16x32_bf16 v[122:125], v[154:157], v[164:167], v[122:125]
	v_mfma_f32_16x16x32_bf16 v[110:113], v[146:149], v[172:175], v[110:113]
	v_mfma_f32_16x16x32_bf16 v[106:109], v[154:157], v[172:175], v[106:109]
	v_mfma_f32_16x16x32_bf16 v[94:97], v[146:149], v[180:183], v[94:97]
	v_mfma_f32_16x16x32_bf16 v[90:93], v[154:157], v[180:183], v[90:93]
	v_mfma_f32_16x16x32_bf16 v[78:81], v[146:149], v[188:191], v[78:81]
	v_mfma_f32_16x16x32_bf16 v[74:77], v[154:157], v[188:191], v[74:77]
	v_mfma_f32_16x16x32_bf16 v[126:129], v[150:153], v[168:171], v[126:129]
	v_mfma_f32_16x16x32_bf16 v[122:125], v[160:163], v[168:171], v[122:125]
	v_mfma_f32_16x16x32_bf16 v[110:113], v[150:153], v[176:179], v[110:113]
	v_mfma_f32_16x16x32_bf16 v[106:109], v[160:163], v[176:179], v[106:109]
	v_mfma_f32_16x16x32_bf16 v[94:97], v[150:153], v[184:187], v[94:97]
	v_mfma_f32_16x16x32_bf16 v[90:93], v[160:163], v[184:187], v[90:93]
	v_mfma_f32_16x16x32_bf16 v[78:81], v[150:153], v[192:195], v[78:81]
	v_mfma_f32_16x16x32_bf16 v[74:77], v[160:163], v[192:195], v[74:77]
	v_mfma_f32_16x16x32_bf16 v[118:121], v[196:199], v[164:167], v[118:121]
	v_mfma_f32_16x16x32_bf16 v[114:117], v[204:207], v[164:167], v[114:117]
	v_mfma_f32_16x16x32_bf16 v[102:105], v[196:199], v[172:175], v[102:105]
	v_mfma_f32_16x16x32_bf16 v[98:101], v[204:207], v[172:175], v[98:101]
	v_mfma_f32_16x16x32_bf16 v[86:89], v[196:199], v[180:183], v[86:89]
	v_mfma_f32_16x16x32_bf16 v[82:85], v[204:207], v[180:183], v[82:85]
	v_mfma_f32_16x16x32_bf16 v[70:73], v[196:199], v[188:191], v[70:73]
	v_mfma_f32_16x16x32_bf16 v[66:69], v[204:207], v[188:191], v[66:69]
	v_mfma_f32_16x16x32_bf16 v[118:121], v[200:203], v[168:171], v[118:121]
	v_mfma_f32_16x16x32_bf16 v[114:117], v[210:213], v[168:171], v[114:117]
	v_mfma_f32_16x16x32_bf16 v[102:105], v[200:203], v[176:179], v[102:105]
	v_mfma_f32_16x16x32_bf16 v[98:101], v[210:213], v[176:179], v[98:101]
	v_mfma_f32_16x16x32_bf16 v[86:89], v[200:203], v[184:187], v[86:89]
	v_mfma_f32_16x16x32_bf16 v[82:85], v[210:213], v[184:187], v[82:85]
	v_mfma_f32_16x16x32_bf16 v[70:73], v[200:203], v[192:195], v[70:73]
	v_mfma_f32_16x16x32_bf16 v[66:69], v[210:213], v[192:195], v[66:69]
	s_setprio 0
	s_barrier
; __device__ __forceinline__ unsigned cvt_pk_bf16(float lo, float hi) { unsigned r; asm("v_cvt_pk_bf16_f32 %0, %1, %2" : "=v"(r) : "v"(lo), "v"(hi)); return r; }
; #define PG8_STAGE(bufoff, gbase, voff) do { _Pragma("unroll") for (int _i = 0; _i < 2; ++_i) \
;         __builtin_amdgcn_global_load_lds((const unsigned*)((const char*)(gbase) + (voff)[_i]), (LAS unsigned*)(lds + (bufoff) + ldsw + _i * 8192), 16, 0, 0); } while (0)
; #define PG8_LDA(dst, b, h) do { _Pragma("unroll") for (int m = 0; m < 4; ++m) _Pragma("unroll") for (int k = 0; k < 2; ++k) dst[m][k] = *(const LAS bf16x8*)(lds + PG8_SA(b, h) + aoff + m * 2048 + k * 1024); } while (0)
; #define PG8_WAIT_V(n) asm volatile("s_waitcnt vmcnt(" #n ")" ::: "memory")
; #define PG8_BAR __builtin_amdgcn_s_barrier()
;     __device__ __forceinline__ void operator()(const f32x4 (&acc)[2][2][4][2], const Unit& u, int wr, int wc, int fr, int fq) const {
;         const int row0 = u.pm * BM + wr * 64 + fr, col0 = u.pn * BM + wc * 32 + 8 * fq;
; #pragma unroll
;         for (int ai = 0; ai < 2; ++ai)
; #pragma unroll
;             for (int m = 0; m < 4; ++m) { bf16_t* rowp = O + (size_t)(row0 + ai * HALF + m * 16) * ldc + col0;
; #pragma unroll
;                 for (int bj = 0; bj < 2; ++bj) { f32x4 v0 = acc[ai][bj][m][0], v1 = acc[ai][bj][m][1];
;                     if (ACT == 1) {
; #pragma unroll
;                         for (int j = 0; j < 4; ++j) { float a = fmaxf(v0[j], 0.f), b = fmaxf(v1[j], 0.f); v0[j] = a * a; v1[j] = b * b; } }
;                     u32x4 w; w.x = cvt_pk_bf16(v0[0], v0[1]); w.y = cvt_pk_bf16(v0[2], v0[3]); w.z = cvt_pk_bf16(v1[0], v1[1]); w.w = cvt_pk_bf16(v1[2], v1[3]);
;                     if (ACT == 1) __builtin_nontemporal_store(w, (u32x4*)(rowp + bj * HALF));
;                     else *(u32x4*)(rowp + bj * HALF) = w; } }
; template <class Epi, class Sched>
; __device__ __forceinline__ void gemm_phase(LAS unsigned char* lds, const Gemm g, const Sched& S, const Epi& E) {
;     ...
;             PG8_BAR; PG8_WAIT_L(0); PG8_MMA(0, 1, At, B1); PG8_BAR;
;             PG8_LDA(At, 1, 1); PG8_STAGE(PG8_SA(1, 0), a3, voffA);
;             PG8_BAR; PG8_WAIT_L(0); PG8_MMA(1, 0, At, B0); PG8_BAR; PG8_SCHED;
;             PG8_STAGE(PG8_SB(1, 1), b3 + hstep, voffB);
;             PG8_WAIT_V(6); PG8_BAR; PG8_MMA(1, 1, At, B1); PG8_BAR;
;         }
;         E(acc, cur, wr, wc, fr, fq);
	s_add_i32 s38, s74, s56
	v_lshl_add_u64 v[140:141], v[140:141], 0, s[36:37]
	s_mov_b32 m0, s38
	s_nop 0
	global_load_lds_dwordx4 v[140:141], off
	v_lshl_add_u64 v[140:141], v[214:215], 0, s[36:37]
	s_add_i32 m0, s38, 0x2000
	s_nop 0
	global_load_lds_dwordx4 v[140:141], off
	s_mov_b32 m0, s64
	v_lshl_add_u64 v[140:141], v[216:217], 0, s[36:37]
	global_load_lds_dwordx4 v[140:141], off
	v_lshl_add_u64 v[140:141], v[224:225], 0, s[36:37]
	s_mov_b32 m0, s65
	s_nop 0
	global_load_lds_dwordx4 v[140:141], off
	ds_read_b128 v[164:167], v145 offset:49152
	ds_read_b128 v[168:171], v145 offset:50176
	ds_read_b128 v[172:175], v145 offset:51200
	ds_read_b128 v[176:179], v145 offset:52224
	ds_read_b128 v[180:183], v145 offset:53248
	ds_read_b128 v[184:187], v145 offset:54272
	ds_read_b128 v[188:191], v145 offset:55296
	ds_read_b128 v[192:195], v145 offset:56320
	s_waitcnt vmcnt(4)
	s_waitcnt lgkmcnt(0)
	s_barrier
	s_setprio 1
	v_mfma_f32_16x16x32_bf16 v[62:65], v[146:149], v[164:167], v[62:65]
	v_mfma_f32_16x16x32_bf16 v[58:61], v[154:157], v[164:167], v[58:61]
	v_mfma_f32_16x16x32_bf16 v[46:49], v[146:149], v[172:175], v[46:49]
	v_mfma_f32_16x16x32_bf16 v[42:45], v[154:157], v[172:175], v[42:45]
	v_mfma_f32_16x16x32_bf16 v[30:33], v[146:149], v[180:183], v[30:33]
	v_mfma_f32_16x16x32_bf16 v[26:29], v[154:157], v[180:183], v[26:29]
	v_mfma_f32_16x16x32_bf16 v[14:17], v[146:149], v[188:191], v[14:17]
	v_mfma_f32_16x16x32_bf16 v[10:13], v[154:157], v[188:191], v[10:13]
	v_mfma_f32_16x16x32_bf16 v[62:65], v[150:153], v[168:171], v[62:65]
	v_mfma_f32_16x16x32_bf16 v[58:61], v[160:163], v[168:171], v[58:61]
	v_mfma_f32_16x16x32_bf16 v[46:49], v[150:153], v[176:179], v[46:49]
	v_mfma_f32_16x16x32_bf16 v[42:45], v[160:163], v[176:179], v[42:45]
	v_mfma_f32_16x16x32_bf16 v[30:33], v[150:153], v[184:187], v[30:33]
	v_mfma_f32_16x16x32_bf16 v[26:29], v[160:163], v[184:187], v[26:29]
	v_mfma_f32_16x16x32_bf16 v[14:17], v[150:153], v[192:195], v[14:17]
	v_mfma_f32_16x16x32_bf16 v[10:13], v[160:163], v[192:195], v[10:13]
	v_mfma_f32_16x16x32_bf16 v[54:57], v[196:199], v[164:167], v[54:57]
	v_mfma_f32_16x16x32_bf16 v[50:53], v[204:207], v[164:167], v[50:53]
	v_mfma_f32_16x16x32_bf16 v[38:41], v[196:199], v[172:175], v[38:41]
	v_mfma_f32_16x16x32_bf16 v[34:37], v[204:207], v[172:175], v[34:37]
	v_mfma_f32_16x16x32_bf16 v[22:25], v[196:199], v[180:183], v[22:25]
	v_mfma_f32_16x16x32_bf16 v[18:21], v[204:207], v[180:183], v[18:21]
	v_mfma_f32_16x16x32_bf16 v[6:9], v[196:199], v[188:191], v[6:9]
	v_mfma_f32_16x16x32_bf16 v[2:5], v[204:207], v[188:191], v[2:5]
	v_mfma_f32_16x16x32_bf16 v[54:57], v[200:203], v[168:171], v[54:57]
	v_mfma_f32_16x16x32_bf16 v[50:53], v[210:213], v[168:171], v[50:53]
	v_mfma_f32_16x16x32_bf16 v[38:41], v[200:203], v[176:179], v[38:41]
	v_mfma_f32_16x16x32_bf16 v[34:37], v[210:213], v[176:179], v[34:37]
	v_mfma_f32_16x16x32_bf16 v[22:25], v[200:203], v[184:187], v[22:25]
	v_mfma_f32_16x16x32_bf16 v[18:21], v[210:213], v[184:187], v[18:21]
	v_mfma_f32_16x16x32_bf16 v[6:9], v[200:203], v[192:195], v[6:9]
	v_mfma_f32_16x16x32_bf16 v[2:5], v[210:213], v[192:195], v[2:5]
	s_setprio 0
	s_add_i32 s73, s73, 2
	s_add_u32 s71, s71, 0x100
	s_addc_u32 s72, s72, 0
	s_add_u32 s46, s46, 0x100
	s_addc_u32 s47, s47, 0
	s_cmp_gt_u32 s73, 29
	s_barrier
	s_cbranch_scc0 .LBB0_73
	v_lshl_add_u32 v146, s8, 8, v142
	v_max_f32_e32 v122, v122, v122
	v_ashrrev_i32_e32 v147, 31, v146
	v_max_f32_e32 v122, 0, v122
	v_max_f32_e32 v123, v123, v123
	v_max_f32_e32 v124, v124, v124
	v_lshl_or_b32 v140, s68, 8, v144
	v_lshlrev_b64 v[148:149], 14, v[146:147]
	v_mul_f32_e32 v147, v122, v122
	v_max_f32_e32 v122, v127, v127
	v_max_f32_e32 v123, 0, v123
	v_max_f32_e32 v124, 0, v124
	v_ashrrev_i32_e32 v141, 31, v140
	v_max_f32_e32 v126, v126, v126
	v_max_f32_e32 v122, 0, v122
	v_mul_f32_e32 v127, v123, v123
	v_max_f32_e32 v123, v128, v128
	v_mul_f32_e32 v128, v124, v124
	v_max_f32_e32 v124, v129, v129
	v_max_f32_e32 v125, v125, v125
	v_lshl_add_u64 v[148:149], s[24:25], 0, v[148:149]
	v_lshlrev_b64 v[150:151], 1, v[140:141]
	v_max_f32_e32 v126, 0, v126
	v_mul_f32_e32 v122, v122, v122
	v_max_f32_e32 v123, 0, v123
	v_max_f32_e32 v124, 0, v124
	v_max_f32_e32 v125, 0, v125
	v_max_f32_e32 v114, v114, v114
	v_lshl_add_u64 v[140:141], v[148:149], 0, v[150:151]
	v_mul_f32_e32 v126, v126, v126
	v_mul_f32_e32 v123, v123, v123
	v_mul_f32_e32 v124, v124, v124
	v_mul_f32_e32 v125, v125, v125
	v_cvt_pk_bf16_f32 v122, v126, v122
	v_max_f32_e32 v114, 0, v114
	v_max_f32_e32 v115, v115, v115
	v_max_f32_e32 v116, v116, v116
	v_cvt_pk_bf16_f32 v123, v123, v124
	v_cvt_pk_bf16_f32 v124, v147, v127
	v_cvt_pk_bf16_f32 v125, v128, v125
	global_store_dwordx4 v[140:141], v[122:125], off nt
	v_max_f32_e32 v115, 0, v115
	v_max_f32_e32 v116, 0, v116
	v_mul_f32_e32 v122, v114, v114
	v_max_f32_e32 v114, v119, v119
	v_max_f32_e32 v118, v118, v118
	v_max_f32_e32 v114, 0, v114
	v_mul_f32_e32 v119, v115, v115
	v_max_f32_e32 v115, v120, v120
	v_mul_f32_e32 v120, v116, v116
	v_max_f32_e32 v116, v121, v121
	v_max_f32_e32 v117, v117, v117
	v_max_f32_e32 v118, 0, v118
	v_mul_f32_e32 v114, v114, v114
	v_max_f32_e32 v115, 0, v115
	v_max_f32_e32 v116, 0, v116
	v_max_f32_e32 v117, 0, v117
	v_mul_f32_e32 v118, v118, v118
	v_mul_f32_e32 v115, v115, v115
	v_mul_f32_e32 v116, v116, v116
	v_mul_f32_e32 v117, v117, v117
	v_cvt_pk_bf16_f32 v114, v118, v114
	v_max_f32_e32 v106, v106, v106
	v_cvt_pk_bf16_f32 v115, v115, v116
	v_cvt_pk_bf16_f32 v116, v122, v119
	v_cvt_pk_bf16_f32 v117, v120, v117
	global_store_dwordx4 v[140:141], v[114:117], off offset:256 nt
	v_max_f32_e32 v106, 0, v106
	v_max_f32_e32 v107, v107, v107
	v_or_b32_e32 v114, 16, v146
; __device__ __forceinline__ unsigned cvt_pk_bf16(float lo, float hi) { unsigned r; asm("v_cvt_pk_bf16_f32 %0, %1, %2" : "=v"(r) : "v"(lo), "v"(hi)); return r; }
;     __device__ __forceinline__ void operator()(const f32x4 (&acc)[2][2][4][2], const Unit& u, int wr, int wc, int fr, int fq) const {
;         const int row0 = u.pm * BM + wr * 64 + fr, col0 = u.pn * BM + wc * 32 + 8 * fq;
; #pragma unroll
;         for (int ai = 0; ai < 2; ++ai)
; #pragma unroll
;             for (int m = 0; m < 4; ++m) { bf16_t* rowp = O + (size_t)(row0 + ai * HALF + m * 16) * ldc + col0;
; #pragma unroll
;                 for (int bj = 0; bj < 2; ++bj) { f32x4 v0 = acc[ai][bj][m][0], v1 = acc[ai][bj][m][1];
;                     if (ACT == 1) {
; #pragma unroll
;                         for (int j = 0; j < 4; ++j) { float a = fmaxf(v0[j], 0.f), b = fmaxf(v1[j], 0.f); v0[j] = a * a; v1[j] = b * b; } }
;                     u32x4 w; w.x = cvt_pk_bf16(v0[0], v0[1]); w.y = cvt_pk_bf16(v0[2], v0[3]); w.z = cvt_pk_bf16(v1[0], v1[1]); w.w = cvt_pk_bf16(v1[2], v1[3]);
;                     if (ACT == 1) __builtin_nontemporal_store(w, (u32x4*)(rowp + bj * HALF));
;                     else *(u32x4*)(rowp + bj * HALF) = w; } }
	v_max_f32_e32 v108, v108, v108
	v_ashrrev_i32_e32 v115, 31, v114
	v_mul_f32_e32 v116, v106, v106
	v_max_f32_e32 v106, v111, v111
	v_max_f32_e32 v107, 0, v107
	v_max_f32_e32 v108, 0, v108
	v_lshlrev_b64 v[114:115], 14, v[114:115]
	v_max_f32_e32 v110, v110, v110
	v_max_f32_e32 v106, 0, v106
	v_mul_f32_e32 v111, v107, v107
	v_max_f32_e32 v107, v112, v112
	v_mul_f32_e32 v112, v108, v108
	v_max_f32_e32 v108, v113, v113
	v_max_f32_e32 v109, v109, v109
	v_lshl_add_u64 v[114:115], s[24:25], 0, v[114:115]
	v_max_f32_e32 v110, 0, v110
	v_mul_f32_e32 v106, v106, v106
	v_max_f32_e32 v107, 0, v107
	v_max_f32_e32 v108, 0, v108
	v_max_f32_e32 v109, 0, v109
	v_max_f32_e32 v98, v98, v98
	v_lshl_add_u64 v[114:115], v[114:115], 0, v[150:151]
	v_mul_f32_e32 v110, v110, v110
	v_mul_f32_e32 v107, v107, v107
	v_mul_f32_e32 v108, v108, v108
	v_mul_f32_e32 v109, v109, v109
	v_cvt_pk_bf16_f32 v106, v110, v106
	v_max_f32_e32 v98, 0, v98
	v_max_f32_e32 v99, v99, v99
	v_max_f32_e32 v100, v100, v100
	v_cvt_pk_bf16_f32 v107, v107, v108
	v_cvt_pk_bf16_f32 v108, v116, v111
	v_cvt_pk_bf16_f32 v109, v112, v109
	global_store_dwordx4 v[114:115], v[106:109], off nt
	v_max_f32_e32 v99, 0, v99
	v_max_f32_e32 v100, 0, v100
	v_mul_f32_e32 v106, v98, v98
	v_max_f32_e32 v98, v103, v103
	v_max_f32_e32 v102, v102, v102
	v_max_f32_e32 v98, 0, v98
	v_mul_f32_e32 v103, v99, v99
	v_max_f32_e32 v99, v104, v104
	v_mul_f32_e32 v104, v100, v100
	v_max_f32_e32 v100, v105, v105
	v_max_f32_e32 v101, v101, v101
	v_max_f32_e32 v102, 0, v102
	v_mul_f32_e32 v98, v98, v98
	v_max_f32_e32 v99, 0, v99
	v_max_f32_e32 v100, 0, v100
	v_max_f32_e32 v101, 0, v101
	v_mul_f32_e32 v102, v102, v102
	v_mul_f32_e32 v99, v99, v99
	v_mul_f32_e32 v100, v100, v100
	v_mul_f32_e32 v101, v101, v101
	v_cvt_pk_bf16_f32 v98, v102, v98
	v_max_f32_e32 v90, v90, v90
	v_cvt_pk_bf16_f32 v99, v99, v100
	v_cvt_pk_bf16_f32 v100, v106, v103
	v_cvt_pk_bf16_f32 v101, v104, v101
	global_store_dwordx4 v[114:115], v[98:101], off offset:256 nt
	v_max_f32_e32 v90, 0, v90
	v_max_f32_e32 v91, v91, v91
	v_or_b32_e32 v98, 32, v146
	v_max_f32_e32 v92, v92, v92
	v_ashrrev_i32_e32 v99, 31, v98
	v_mul_f32_e32 v100, v90, v90
	v_max_f32_e32 v90, v95, v95
	v_max_f32_e32 v91, 0, v91
	v_max_f32_e32 v92, 0, v92
	v_lshlrev_b64 v[98:99], 14, v[98:99]
	v_max_f32_e32 v94, v94, v94
	v_max_f32_e32 v90, 0, v90
	v_mul_f32_e32 v95, v91, v91
	v_max_f32_e32 v91, v96, v96
	v_mul_f32_e32 v96, v92, v92
	v_max_f32_e32 v92, v97, v97
	v_max_f32_e32 v93, v93, v93
	v_lshl_add_u64 v[98:99], s[24:25], 0, v[98:99]
	v_max_f32_e32 v94, 0, v94
	v_mul_f32_e32 v90, v90, v90
	v_max_f32_e32 v91, 0, v91
	v_max_f32_e32 v92, 0, v92
	v_max_f32_e32 v93, 0, v93
	v_max_f32_e32 v82, v82, v82
	v_lshl_add_u64 v[98:99], v[98:99], 0, v[150:151]
	v_mul_f32_e32 v94, v94, v94
	v_mul_f32_e32 v91, v91, v91
	v_mul_f32_e32 v92, v92, v92
	v_mul_f32_e32 v93, v93, v93
	v_cvt_pk_bf16_f32 v90, v94, v90
	v_max_f32_e32 v82, 0, v82
	v_max_f32_e32 v83, v83, v83
	v_max_f32_e32 v84, v84, v84
	v_cvt_pk_bf16_f32 v91, v91, v92
	v_cvt_pk_bf16_f32 v92, v100, v95
	v_cvt_pk_bf16_f32 v93, v96, v93
	global_store_dwordx4 v[98:99], v[90:93], off nt
	v_max_f32_e32 v83, 0, v83
	v_max_f32_e32 v84, 0, v84
	v_mul_f32_e32 v90, v82, v82
	v_max_f32_e32 v82, v87, v87
	v_max_f32_e32 v86, v86, v86
	v_max_f32_e32 v82, 0, v82
	v_mul_f32_e32 v87, v83, v83
	v_max_f32_e32 v83, v88, v88
	v_mul_f32_e32 v88, v84, v84
	v_max_f32_e32 v84, v89, v89
	v_max_f32_e32 v85, v85, v85
	v_max_f32_e32 v86, 0, v86
	v_mul_f32_e32 v82, v82, v82
	v_max_f32_e32 v83, 0, v83
	v_max_f32_e32 v84, 0, v84
	v_max_f32_e32 v85, 0, v85
	v_mul_f32_e32 v86, v86, v86
	v_mul_f32_e32 v83, v83, v83
	v_mul_f32_e32 v84, v84, v84
	v_mul_f32_e32 v85, v85, v85
	v_cvt_pk_bf16_f32 v82, v86, v82
	v_max_f32_e32 v74, v74, v74
	v_cvt_pk_bf16_f32 v83, v83, v84
	v_cvt_pk_bf16_f32 v84, v90, v87
	v_cvt_pk_bf16_f32 v85, v88, v85
	global_store_dwordx4 v[98:99], v[82:85], off offset:256 nt
	v_max_f32_e32 v74, 0, v74
	v_max_f32_e32 v75, v75, v75
	v_or_b32_e32 v82, 48, v146
	v_max_f32_e32 v76, v76, v76
	v_ashrrev_i32_e32 v83, 31, v82
	v_mul_f32_e32 v84, v74, v74
	v_max_f32_e32 v74, v79, v79
	v_max_f32_e32 v75, 0, v75
	v_max_f32_e32 v76, 0, v76
	v_lshlrev_b64 v[82:83], 14, v[82:83]
	v_max_f32_e32 v78, v78, v78
	v_max_f32_e32 v74, 0, v74
	v_mul_f32_e32 v79, v75, v75
	v_max_f32_e32 v75, v80, v80
	v_mul_f32_e32 v80, v76, v76
	v_max_f32_e32 v76, v81, v81
	v_max_f32_e32 v77, v77, v77
	v_lshl_add_u64 v[82:83], s[24:25], 0, v[82:83]
	v_max_f32_e32 v78, 0, v78
	v_mul_f32_e32 v74, v74, v74
	v_max_f32_e32 v75, 0, v75
	v_max_f32_e32 v76, 0, v76
	v_max_f32_e32 v77, 0, v77
	v_max_f32_e32 v66, v66, v66
	v_max_f32_e32 v67, v67, v67
	v_max_f32_e32 v68, v68, v68
	v_lshl_add_u64 v[82:83], v[82:83], 0, v[150:151]
	v_mul_f32_e32 v78, v78, v78
	v_mul_f32_e32 v75, v75, v75
	v_mul_f32_e32 v76, v76, v76
	v_mul_f32_e32 v77, v77, v77
	v_cvt_pk_bf16_f32 v74, v78, v74
	v_max_f32_e32 v66, 0, v66
	v_max_f32_e32 v67, 0, v67
	v_max_f32_e32 v68, 0, v68
	v_cvt_pk_bf16_f32 v75, v75, v76
	v_cvt_pk_bf16_f32 v76, v84, v79
	v_cvt_pk_bf16_f32 v77, v80, v77
	global_store_dwordx4 v[82:83], v[74:77], off nt
	v_max_f32_e32 v69, v69, v69
	v_max_f32_e32 v70, v70, v70
	v_mul_f32_e32 v74, v66, v66
	v_max_f32_e32 v66, v71, v71
	v_mul_f32_e32 v71, v67, v67
	v_max_f32_e32 v67, v72, v72
	v_mul_f32_e32 v72, v68, v68
	v_max_f32_e32 v68, v73, v73
	v_max_f32_e32 v67, 0, v67
	v_max_f32_e32 v68, 0, v68
	v_max_f32_e32 v66, 0, v66
	v_mul_f32_e32 v67, v67, v67
	v_max_f32_e32 v69, 0, v69
	v_mul_f32_e32 v68, v68, v68
	v_max_f32_e32 v58, v58, v58
	v_max_f32_e32 v70, 0, v70
	v_mul_f32_e32 v66, v66, v66
	v_mul_f32_e32 v69, v69, v69
	v_cvt_pk_bf16_f32 v67, v67, v68
; __device__ __forceinline__ unsigned cvt_pk_bf16(float lo, float hi) { unsigned r; asm("v_cvt_pk_bf16_f32 %0, %1, %2" : "=v"(r) : "v"(lo), "v"(hi)); return r; }
;     __device__ __forceinline__ void operator()(const f32x4 (&acc)[2][2][4][2], const Unit& u, int wr, int wc, int fr, int fq) const {
;         const int row0 = u.pm * BM + wr * 64 + fr, col0 = u.pn * BM + wc * 32 + 8 * fq;
; #pragma unroll
;         for (int ai = 0; ai < 2; ++ai)
; #pragma unroll
;             for (int m = 0; m < 4; ++m) { bf16_t* rowp = O + (size_t)(row0 + ai * HALF + m * 16) * ldc + col0;
; #pragma unroll
;                 for (int bj = 0; bj < 2; ++bj) { f32x4 v0 = acc[ai][bj][m][0], v1 = acc[ai][bj][m][1];
;                     if (ACT == 1) {
; #pragma unroll
;                         for (int j = 0; j < 4; ++j) { float a = fmaxf(v0[j], 0.f), b = fmaxf(v1[j], 0.f); v0[j] = a * a; v1[j] = b * b; } }
;                     u32x4 w; w.x = cvt_pk_bf16(v0[0], v0[1]); w.y = cvt_pk_bf16(v0[2], v0[3]); w.z = cvt_pk_bf16(v1[0], v1[1]); w.w = cvt_pk_bf16(v1[2], v1[3]);
;                     if (ACT == 1) __builtin_nontemporal_store(w, (u32x4*)(rowp + bj * HALF));
;                     else *(u32x4*)(rowp + bj * HALF) = w; } }
	v_cvt_pk_bf16_f32 v68, v74, v71
	v_max_f32_e32 v58, 0, v58
	v_max_f32_e32 v59, v59, v59
	v_max_f32_e32 v60, v60, v60
	v_mul_f32_e32 v70, v70, v70
	v_cvt_pk_bf16_f32 v66, v70, v66
	v_cvt_pk_bf16_f32 v69, v72, v69
	global_store_dwordx4 v[82:83], v[66:69], off offset:256 nt
	v_max_f32_e32 v62, v62, v62
	v_max_f32_e32 v59, 0, v59
	v_mul_f32_e32 v68, v58, v58
	v_max_f32_e32 v58, v63, v63
	v_max_f32_e32 v60, 0, v60
	v_max_f32_e32 v62, 0, v62
	v_max_f32_e32 v58, 0, v58
	v_mul_f32_e32 v63, v59, v59
	v_max_f32_e32 v59, v64, v64
	v_mul_f32_e32 v64, v60, v60
	v_max_f32_e32 v60, v65, v65
	v_mul_f32_e32 v62, v62, v62
	v_mul_f32_e32 v58, v58, v58
	v_max_f32_e32 v59, 0, v59
	v_max_f32_e32 v60, 0, v60
	v_max_f32_e32 v61, v61, v61
	s_mov_b32 s8, 0x200000
	v_mul_f32_e32 v59, v59, v59
	v_max_f32_e32 v61, 0, v61
	v_mul_f32_e32 v60, v60, v60
	v_cvt_pk_bf16_f32 v58, v62, v58
	v_add_co_u32_e32 v62, vcc, s8, v140
	v_max_f32_e32 v50, v50, v50
	v_max_f32_e32 v51, v51, v51
	v_max_f32_e32 v52, v52, v52
	v_mul_f32_e32 v61, v61, v61
	v_cvt_pk_bf16_f32 v59, v59, v60
	v_cvt_pk_bf16_f32 v60, v68, v63
	v_addc_co_u32_e32 v63, vcc, 0, v141, vcc
	v_max_f32_e32 v50, 0, v50
	v_max_f32_e32 v51, 0, v51
	v_max_f32_e32 v52, 0, v52
	v_cvt_pk_bf16_f32 v61, v64, v61
	global_store_dwordx4 v[62:63], v[58:61], off nt
	v_max_f32_e32 v53, v53, v53
	s_mov_b64 s[38:39], 0x200000
	v_mul_f32_e32 v58, v50, v50
	v_max_f32_e32 v50, v55, v55
	v_mul_f32_e32 v55, v51, v51
	v_max_f32_e32 v51, v56, v56
	v_mul_f32_e32 v56, v52, v52
	v_max_f32_e32 v52, v57, v57
	v_max_f32_e32 v51, 0, v51
	v_max_f32_e32 v52, 0, v52
	v_max_f32_e32 v54, v54, v54
	v_max_f32_e32 v50, 0, v50
	v_mul_f32_e32 v51, v51, v51
	v_max_f32_e32 v53, 0, v53
	v_mul_f32_e32 v52, v52, v52
	v_max_f32_e32 v42, v42, v42
	v_lshl_add_u64 v[66:67], v[140:141], 0, s[38:39]
	v_max_f32_e32 v54, 0, v54
	v_mul_f32_e32 v50, v50, v50
	v_mul_f32_e32 v53, v53, v53
	v_cvt_pk_bf16_f32 v51, v51, v52
	v_cvt_pk_bf16_f32 v52, v58, v55
	v_max_f32_e32 v42, 0, v42
	v_max_f32_e32 v43, v43, v43
	v_max_f32_e32 v44, v44, v44
	v_mul_f32_e32 v54, v54, v54
	v_cvt_pk_bf16_f32 v50, v54, v50
	v_cvt_pk_bf16_f32 v53, v56, v53
	global_store_dwordx4 v[66:67], v[50:53], off offset:256 nt
	v_max_f32_e32 v46, v46, v46
	v_max_f32_e32 v43, 0, v43
	v_mul_f32_e32 v52, v42, v42
	v_max_f32_e32 v42, v47, v47
	v_max_f32_e32 v44, 0, v44
	v_max_f32_e32 v46, 0, v46
	v_max_f32_e32 v42, 0, v42
	v_mul_f32_e32 v47, v43, v43
	v_max_f32_e32 v43, v48, v48
	v_mul_f32_e32 v48, v44, v44
	v_max_f32_e32 v44, v49, v49
	v_mul_f32_e32 v46, v46, v46
	v_mul_f32_e32 v42, v42, v42
	v_max_f32_e32 v43, 0, v43
	v_max_f32_e32 v44, 0, v44
	v_max_f32_e32 v45, v45, v45
	s_mov_b32 s8, 0x240000
	v_mul_f32_e32 v43, v43, v43
	v_max_f32_e32 v45, 0, v45
	v_mul_f32_e32 v44, v44, v44
	v_cvt_pk_bf16_f32 v42, v46, v42
	v_add_co_u32_e32 v46, vcc, s8, v140
	v_max_f32_e32 v34, v34, v34
	v_max_f32_e32 v35, v35, v35
	v_max_f32_e32 v36, v36, v36
	v_mul_f32_e32 v45, v45, v45
	v_cvt_pk_bf16_f32 v43, v43, v44
	v_cvt_pk_bf16_f32 v44, v52, v47
	v_addc_co_u32_e32 v47, vcc, 0, v141, vcc
	v_max_f32_e32 v34, 0, v34
	v_max_f32_e32 v35, 0, v35
	v_max_f32_e32 v36, 0, v36
	v_cvt_pk_bf16_f32 v45, v48, v45
	global_store_dwordx4 v[46:47], v[42:45], off nt
	v_max_f32_e32 v37, v37, v37
	s_mov_b64 s[38:39], 0x240000
	v_mul_f32_e32 v42, v34, v34
	v_max_f32_e32 v34, v39, v39
	v_mul_f32_e32 v39, v35, v35
	v_max_f32_e32 v35, v40, v40
	v_mul_f32_e32 v40, v36, v36
	v_max_f32_e32 v36, v41, v41
	v_max_f32_e32 v35, 0, v35
	v_max_f32_e32 v36, 0, v36
	v_max_f32_e32 v38, v38, v38
	v_max_f32_e32 v34, 0, v34
	v_mul_f32_e32 v35, v35, v35
	v_max_f32_e32 v37, 0, v37
	v_mul_f32_e32 v36, v36, v36
	v_max_f32_e32 v26, v26, v26
	v_lshl_add_u64 v[50:51], v[140:141], 0, s[38:39]
	v_max_f32_e32 v38, 0, v38
	v_mul_f32_e32 v34, v34, v34
	v_mul_f32_e32 v37, v37, v37
	v_cvt_pk_bf16_f32 v35, v35, v36
	v_cvt_pk_bf16_f32 v36, v42, v39
	v_max_f32_e32 v26, 0, v26
	v_max_f32_e32 v27, v27, v27
	v_max_f32_e32 v28, v28, v28
	v_mul_f32_e32 v38, v38, v38
; __device__ __forceinline__ unsigned cvt_pk_bf16(float lo, float hi) { unsigned r; asm("v_cvt_pk_bf16_f32 %0, %1, %2" : "=v"(r) : "v"(lo), "v"(hi)); return r; }
;     __device__ __forceinline__ void operator()(const f32x4 (&acc)[2][2][4][2], const Unit& u, int wr, int wc, int fr, int fq) const {
;         const int row0 = u.pm * BM + wr * 64 + fr, col0 = u.pn * BM + wc * 32 + 8 * fq;
; #pragma unroll
;         for (int ai = 0; ai < 2; ++ai)
; #pragma unroll
;             for (int m = 0; m < 4; ++m) { bf16_t* rowp = O + (size_t)(row0 + ai * HALF + m * 16) * ldc + col0;
; #pragma unroll
;                 for (int bj = 0; bj < 2; ++bj) { f32x4 v0 = acc[ai][bj][m][0], v1 = acc[ai][bj][m][1];
;                     if (ACT == 1) {
; #pragma unroll
;                         for (int j = 0; j < 4; ++j) { float a = fmaxf(v0[j], 0.f), b = fmaxf(v1[j], 0.f); v0[j] = a * a; v1[j] = b * b; } }
;                     u32x4 w; w.x = cvt_pk_bf16(v0[0], v0[1]); w.y = cvt_pk_bf16(v0[2], v0[3]); w.z = cvt_pk_bf16(v1[0], v1[1]); w.w = cvt_pk_bf16(v1[2], v1[3]);
;                     if (ACT == 1) __builtin_nontemporal_store(w, (u32x4*)(rowp + bj * HALF));
;                     else *(u32x4*)(rowp + bj * HALF) = w; } }
	v_cvt_pk_bf16_f32 v34, v38, v34
	v_cvt_pk_bf16_f32 v37, v40, v37
	global_store_dwordx4 v[50:51], v[34:37], off offset:256 nt
	v_max_f32_e32 v30, v30, v30
	v_max_f32_e32 v27, 0, v27
	v_mul_f32_e32 v36, v26, v26
	v_max_f32_e32 v26, v31, v31
	v_max_f32_e32 v28, 0, v28
	v_max_f32_e32 v30, 0, v30
	v_max_f32_e32 v26, 0, v26
	v_mul_f32_e32 v31, v27, v27
	v_max_f32_e32 v27, v32, v32
	v_mul_f32_e32 v32, v28, v28
	v_max_f32_e32 v28, v33, v33
	v_mul_f32_e32 v30, v30, v30
	v_mul_f32_e32 v26, v26, v26
	v_max_f32_e32 v27, 0, v27
	v_max_f32_e32 v28, 0, v28
	v_max_f32_e32 v29, v29, v29
	s_mov_b32 s8, 0x280000
	v_mul_f32_e32 v27, v27, v27
	v_max_f32_e32 v29, 0, v29
	v_mul_f32_e32 v28, v28, v28
	v_cvt_pk_bf16_f32 v26, v30, v26
	v_add_co_u32_e32 v30, vcc, s8, v140
	v_max_f32_e32 v18, v18, v18
	v_max_f32_e32 v19, v19, v19
	v_max_f32_e32 v20, v20, v20
	v_mul_f32_e32 v29, v29, v29
	v_cvt_pk_bf16_f32 v27, v27, v28
	v_cvt_pk_bf16_f32 v28, v36, v31
	v_addc_co_u32_e32 v31, vcc, 0, v141, vcc
	v_max_f32_e32 v18, 0, v18
	v_max_f32_e32 v19, 0, v19
	v_max_f32_e32 v20, 0, v20
	v_cvt_pk_bf16_f32 v29, v32, v29
	global_store_dwordx4 v[30:31], v[26:29], off nt
	v_max_f32_e32 v21, v21, v21
	s_mov_b64 s[38:39], 0x280000
	v_mul_f32_e32 v26, v18, v18
	v_max_f32_e32 v18, v23, v23
	v_mul_f32_e32 v23, v19, v19
	v_max_f32_e32 v19, v24, v24
	v_mul_f32_e32 v24, v20, v20
	v_max_f32_e32 v20, v25, v25
	v_max_f32_e32 v19, 0, v19
	v_max_f32_e32 v20, 0, v20
	v_max_f32_e32 v22, v22, v22
	v_max_f32_e32 v18, 0, v18
	v_mul_f32_e32 v19, v19, v19
	v_max_f32_e32 v21, 0, v21
	v_mul_f32_e32 v20, v20, v20
	v_max_f32_e32 v10, v10, v10
	v_lshl_add_u64 v[34:35], v[140:141], 0, s[38:39]
	v_max_f32_e32 v22, 0, v22
	v_mul_f32_e32 v18, v18, v18
	v_mul_f32_e32 v21, v21, v21
	v_cvt_pk_bf16_f32 v19, v19, v20
	v_cvt_pk_bf16_f32 v20, v26, v23
	v_max_f32_e32 v10, 0, v10
	v_max_f32_e32 v11, v11, v11
	v_max_f32_e32 v12, v12, v12
	v_mul_f32_e32 v22, v22, v22
	v_cvt_pk_bf16_f32 v18, v22, v18
	v_cvt_pk_bf16_f32 v21, v24, v21
	global_store_dwordx4 v[34:35], v[18:21], off offset:256 nt
	v_max_f32_e32 v14, v14, v14
	v_max_f32_e32 v11, 0, v11
	v_mul_f32_e32 v20, v10, v10
	v_max_f32_e32 v10, v15, v15
	v_max_f32_e32 v12, 0, v12
	v_max_f32_e32 v14, 0, v14
	v_max_f32_e32 v10, 0, v10
	v_mul_f32_e32 v15, v11, v11
	v_max_f32_e32 v11, v16, v16
	v_mul_f32_e32 v16, v12, v12
	v_max_f32_e32 v12, v17, v17
	v_mul_f32_e32 v14, v14, v14
	v_mul_f32_e32 v10, v10, v10
	v_max_f32_e32 v11, 0, v11
	v_max_f32_e32 v12, 0, v12
	v_max_f32_e32 v13, v13, v13
	s_mov_b32 s8, 0x2c0000
	v_mul_f32_e32 v11, v11, v11
	v_max_f32_e32 v13, 0, v13
	v_mul_f32_e32 v12, v12, v12
	v_cvt_pk_bf16_f32 v10, v14, v10
	v_add_co_u32_e32 v14, vcc, s8, v140
	v_max_f32_e32 v2, v2, v2
	v_max_f32_e32 v3, v3, v3
	v_max_f32_e32 v4, v4, v4
	v_mul_f32_e32 v13, v13, v13
	v_cvt_pk_bf16_f32 v11, v11, v12
	v_cvt_pk_bf16_f32 v12, v20, v15
	v_addc_co_u32_e32 v15, vcc, 0, v141, vcc
	v_max_f32_e32 v2, 0, v2
	v_max_f32_e32 v3, 0, v3
	v_max_f32_e32 v4, 0, v4
	v_cvt_pk_bf16_f32 v13, v16, v13
	global_store_dwordx4 v[14:15], v[10:13], off nt
	v_max_f32_e32 v5, v5, v5
	s_mov_b64 s[38:39], 0x2c0000
	v_mul_f32_e32 v10, v2, v2
	v_max_f32_e32 v2, v7, v7
	v_mul_f32_e32 v7, v3, v3
	v_max_f32_e32 v3, v8, v8
	v_mul_f32_e32 v8, v4, v4
	v_max_f32_e32 v4, v9, v9
	v_max_f32_e32 v6, v6, v6
	v_max_f32_e32 v2, 0, v2
	v_max_f32_e32 v3, 0, v3
	v_max_f32_e32 v4, 0, v4
	v_max_f32_e32 v5, 0, v5
	v_lshl_add_u64 v[18:19], v[140:141], 0, s[38:39]
	v_max_f32_e32 v6, 0, v6
	v_mul_f32_e32 v2, v2, v2
	v_mul_f32_e32 v3, v3, v3
	v_mul_f32_e32 v4, v4, v4
	v_mul_f32_e32 v5, v5, v5
	s_and_b64 vcc, exec, s[40:41]
	s_mov_b32 s68, s26
	s_mov_b32 s8, s28
	s_mov_b64 s[46:47], s[44:45]
	s_mov_b64 s[48:49], s[42:43]
	v_mul_f32_e32 v6, v6, v6
	v_cvt_pk_bf16_f32 v2, v6, v2
	v_cvt_pk_bf16_f32 v3, v3, v4
	v_cvt_pk_bf16_f32 v4, v10, v7
	v_cvt_pk_bf16_f32 v5, v8, v5
	global_store_dwordx4 v[18:19], v[2:5], off offset:256 nt
	s_cbranch_vccz .LBB0_70
	s_waitcnt vmcnt(0)
	s_cmpk_gt_u32 s52, 0xff
	s_cbranch_scc1 .LBB0_77
	s_barrier

; #define PG8_STAGE(bufoff, gbase, voff) do { _Pragma("unroll") for (int _i = 0; _i < 2; ++_i) \
;         __builtin_amdgcn_global_load_lds((const unsigned*)((const char*)(gbase) + (voff)[_i]), (LAS unsigned*)(lds + (bufoff) + ldsw + _i * 8192), 16, 0, 0); } while (0)
; #define PG8_LDA(dst, b, h) do { _Pragma("unroll") for (int m = 0; m < 4; ++m) _Pragma("unroll") for (int k = 0; k < 2; ++k) dst[m][k] = *(const LAS bf16x8*)(lds + PG8_SA(b, h) + aoff + m * 2048 + k * 1024); } while (0)
; #define PG8_LDB(dst, b, h) do { _Pragma("unroll") for (int n = 0; n < 2; ++n) _Pragma("unroll") for (int k = 0; k < 2; ++k) dst[n][k] = *(const LAS bf16x8*)(lds + PG8_SB(b, h) + boff + n * 2048 + k * 1024); } while (0)
; #define PG8_MMA(ai, bj, At, Bt) do { __builtin_amdgcn_s_setprio(1); _Pragma("unroll") for (int m = 0; m < 4; ++m) _Pragma("unroll") for (int n = 0; n < 2; ++n) _Pragma("unroll") for (int k = 0; k < 2; ++k) \
;         acc[ai][bj][m][n] = __builtin_amdgcn_mfma_f32_16x16x32_bf16(Bt[n][k], At[m][k], acc[ai][bj][m][n], 0, 0, 0); __builtin_amdgcn_s_setprio(0); } while (0)
; #define PG8_WAIT_L(n) asm volatile("s_waitcnt lgkmcnt(" #n ")" ::: "memory")
; #define PG8_BAR __builtin_amdgcn_s_barrier()
; #define PG8_SCHED __builtin_amdgcn_sched_barrier(0)
; template <class Epi, class Sched>
; __device__ __forceinline__ void gemm_phase(LAS unsigned char* lds, const Gemm g, const Sched& S, const Epi& E) {
;     ...
;             PG8_LDB(B0, 0, 0); PG8_SCHED; PG8_LDA(At, 0, 0); PG8_STAGE(PG8_SA(1, 1), a1 + hstep, voffA);
;             PG8_WAIT_L(8); PG8_BAR; PG8_WAIT_L(0); PG8_MMA(0, 0, At, B0); PG8_BAR; PG8_SCHED;
;             PG8_LDB(B1, 0, 1); PG8_STAGE(PG8_SB(0, 0), b2, voffB);
;             PG8_BAR; PG8_WAIT_L(0); PG8_MMA(0, 1, At, B1); PG8_BAR;
;             PG8_LDA(At, 0, 1); PG8_STAGE(PG8_SA(0, 0), a2, voffA);
;             PG8_BAR; PG8_WAIT_L(0); PG8_MMA(1, 0, At, B0); PG8_BAR; PG8_SCHED;
;             PG8_STAGE(PG8_SB(0, 1), b2 + hstep, voffB);
.LBB0_99:
	s_add_u32 s100, s79, 0x7ff80
	s_addc_u32 s101, s80, 0
	v_lshl_add_u64 v[98:99], s[100:101], 0, v[0:1]
	s_add_i32 m0, s67, 0x1c000
	s_nop 0
	global_load_lds_dwordx4 v[98:99], off
	v_lshl_add_u64 v[98:99], s[100:101], 0, v[146:147]
	s_add_i32 m0, s67, 0x1e000
	s_nop 0
	global_load_lds_dwordx4 v[98:99], off
	s_add_u32 s56, s28, 0x100
	s_addc_u32 s57, s29, 0
	s_cmp_eq_u32 s81, 28
	s_cselect_b32 s61, s51, s57
	s_cselect_b32 s60, s77, s56
	s_cselect_b32 s59, s49, s80
	s_cselect_b32 s58, s78, s79
	v_lshl_add_u64 v[156:157], s[28:29], 0, v[150:151]
	s_add_i32 m0, s9, 0xc000
	s_nop 0
	global_load_lds_dwordx4 v[156:157], off
	v_lshl_add_u64 v[156:157], s[28:29], 0, v[148:149]
	s_add_i32 m0, s9, 0xe000
	s_nop 0
	global_load_lds_dwordx4 v[156:157], off
	s_add_i32 s38, 0, 0x10000
	v_add_u32_e32 v110, s38, v169
	ds_read_b128 v[98:101], v110
	ds_read_b128 v[102:105], v110 offset:1024
	ds_read_b128 v[106:109], v110 offset:2048
	ds_read_b128 v[110:113], v110 offset:3072
	ds_read_b128 v[152:155], v171
	ds_read_b128 v[160:163], v171 offset:1024
	ds_read_b128 v[164:167], v171 offset:2048
	ds_read_b128 v[172:175], v171 offset:3072
	ds_read_b128 v[176:179], v171 offset:4096
	ds_read_b128 v[180:183], v171 offset:5120
	ds_read_b128 v[184:187], v171 offset:6144
	ds_read_b128 v[188:191], v171 offset:7168
	s_add_i32 s39, 0, 0x14000
	v_add_u32_e32 v156, s39, v169
	ds_read_b128 v[192:195], v156
	ds_read_b128 v[196:199], v156 offset:1024
	ds_read_b128 v[200:203], v156 offset:2048
	ds_read_b128 v[204:207], v156 offset:3072
	s_waitcnt lgkmcnt(4)
	s_barrier
	s_waitcnt lgkmcnt(0)
	s_setprio 1
	v_mfma_f32_16x16x32_bf16 v[142:145], v[98:101], v[152:155], v[142:145]
	v_mfma_f32_16x16x32_bf16 v[138:141], v[106:109], v[152:155], v[138:141]
	v_mfma_f32_16x16x32_bf16 v[126:129], v[98:101], v[164:167], v[126:129]
	v_mfma_f32_16x16x32_bf16 v[122:125], v[106:109], v[164:167], v[122:125]
	v_mfma_f32_16x16x32_bf16 v[94:97], v[98:101], v[176:179], v[94:97]
	v_mfma_f32_16x16x32_bf16 v[90:93], v[106:109], v[176:179], v[90:93]
	v_mfma_f32_16x16x32_bf16 v[86:89], v[98:101], v[184:187], v[86:89]
	v_mfma_f32_16x16x32_bf16 v[82:85], v[106:109], v[184:187], v[82:85]
	v_mfma_f32_16x16x32_bf16 v[142:145], v[102:105], v[160:163], v[142:145]
	v_mfma_f32_16x16x32_bf16 v[138:141], v[110:113], v[160:163], v[138:141]
	v_mfma_f32_16x16x32_bf16 v[126:129], v[102:105], v[172:175], v[126:129]
	v_mfma_f32_16x16x32_bf16 v[122:125], v[110:113], v[172:175], v[122:125]
	v_mfma_f32_16x16x32_bf16 v[94:97], v[102:105], v[180:183], v[94:97]
	v_mfma_f32_16x16x32_bf16 v[90:93], v[110:113], v[180:183], v[90:93]
	v_mfma_f32_16x16x32_bf16 v[86:89], v[102:105], v[188:191], v[86:89]
	v_mfma_f32_16x16x32_bf16 v[82:85], v[110:113], v[188:191], v[82:85]
	v_mfma_f32_16x16x32_bf16 v[134:137], v[192:195], v[152:155], v[134:137]
	v_mfma_f32_16x16x32_bf16 v[130:133], v[200:203], v[152:155], v[130:133]
	v_mfma_f32_16x16x32_bf16 v[118:121], v[192:195], v[164:167], v[118:121]
	v_mfma_f32_16x16x32_bf16 v[114:117], v[200:203], v[164:167], v[114:117]
	v_mfma_f32_16x16x32_bf16 v[78:81], v[192:195], v[176:179], v[78:81]
	v_mfma_f32_16x16x32_bf16 v[74:77], v[200:203], v[176:179], v[74:77]
	v_mfma_f32_16x16x32_bf16 v[70:73], v[192:195], v[184:187], v[70:73]
	v_mfma_f32_16x16x32_bf16 v[66:69], v[200:203], v[184:187], v[66:69]
	v_mfma_f32_16x16x32_bf16 v[134:137], v[196:199], v[160:163], v[134:137]
	v_mfma_f32_16x16x32_bf16 v[130:133], v[204:207], v[160:163], v[130:133]
	v_mfma_f32_16x16x32_bf16 v[118:121], v[196:199], v[172:175], v[118:121]
	v_mfma_f32_16x16x32_bf16 v[114:117], v[204:207], v[172:175], v[114:117]
	v_mfma_f32_16x16x32_bf16 v[78:81], v[196:199], v[180:183], v[78:81]
	v_mfma_f32_16x16x32_bf16 v[74:77], v[204:207], v[180:183], v[74:77]
	v_mfma_f32_16x16x32_bf16 v[70:73], v[196:199], v[188:191], v[70:73]
	v_mfma_f32_16x16x32_bf16 v[66:69], v[204:207], v[188:191], v[66:69]
	s_setprio 0
	s_barrier
	s_add_i32 s28, s38, s67
	v_lshl_add_u64 v[156:157], s[58:59], 0, v[0:1]
	s_mov_b32 m0, s28
	v_lshl_add_u64 v[210:211], s[58:59], 0, v[146:147]
	global_load_lds_dwordx4 v[156:157], off
	s_add_i32 m0, s28, 0x2000
	s_nop 0
	global_load_lds_dwordx4 v[210:211], off
	s_mov_b32 m0, s9
	v_lshl_add_u64 v[212:213], s[60:61], 0, v[0:1]
	global_load_lds_dwordx4 v[212:213], off
	v_lshl_add_u64 v[214:215], s[60:61], 0, v[146:147]
	s_mov_b32 m0, s68
	s_nop 0
	global_load_lds_dwordx4 v[214:215], off
	ds_read_b128 v[152:155], v171 offset:16384
	ds_read_b128 v[160:163], v171 offset:17408
	ds_read_b128 v[164:167], v171 offset:18432
	ds_read_b128 v[172:175], v171 offset:19456
	ds_read_b128 v[176:179], v171 offset:20480
	ds_read_b128 v[180:183], v171 offset:21504
	ds_read_b128 v[184:187], v171 offset:22528
	ds_read_b128 v[188:191], v171 offset:23552
	s_waitcnt vmcnt(4)
	s_waitcnt lgkmcnt(0)
	s_barrier
; #define PG8_STAGE(bufoff, gbase, voff) do { _Pragma("unroll") for (int _i = 0; _i < 2; ++_i) \
;         __builtin_amdgcn_global_load_lds((const unsigned*)((const char*)(gbase) + (voff)[_i]), (LAS unsigned*)(lds + (bufoff) + ldsw + _i * 8192), 16, 0, 0); } while (0)
; #define PG8_LDA(dst, b, h) do { _Pragma("unroll") for (int m = 0; m < 4; ++m) _Pragma("unroll") for (int k = 0; k < 2; ++k) dst[m][k] = *(const LAS bf16x8*)(lds + PG8_SA(b, h) + aoff + m * 2048 + k * 1024); } while (0)
; #define PG8_LDB(dst, b, h) do { _Pragma("unroll") for (int n = 0; n < 2; ++n) _Pragma("unroll") for (int k = 0; k < 2; ++k) dst[n][k] = *(const LAS bf16x8*)(lds + PG8_SB(b, h) + boff + n * 2048 + k * 1024); } while (0)
; #define PG8_MMA(ai, bj, At, Bt) do { __builtin_amdgcn_s_setprio(1); _Pragma("unroll") for (int m = 0; m < 4; ++m) _Pragma("unroll") for (int n = 0; n < 2; ++n) _Pragma("unroll") for (int k = 0; k < 2; ++k) \
;         acc[ai][bj][m][n] = __builtin_amdgcn_mfma_f32_16x16x32_bf16(Bt[n][k], At[m][k], acc[ai][bj][m][n], 0, 0, 0); __builtin_amdgcn_s_setprio(0); } while (0)
; #define PG8_WAIT_V(n) asm volatile("s_waitcnt vmcnt(" #n ")" ::: "memory")
; #define PG8_WAIT_L(n) asm volatile("s_waitcnt lgkmcnt(" #n ")" ::: "memory")
; #define PG8_BAR __builtin_amdgcn_s_barrier()
; #define PG8_SCHED __builtin_amdgcn_sched_barrier(0)
; template <class Epi, class Sched>
; __device__ __forceinline__ void gemm_phase(LAS unsigned char* lds, const Gemm g, const Sched& S, const Epi& E) {
;     ...
;             PG8_BAR; PG8_WAIT_L(0); PG8_MMA(1, 0, At, B0); PG8_BAR; PG8_SCHED;
;             PG8_STAGE(PG8_SB(0, 1), b2 + hstep, voffB);
;             PG8_WAIT_V(6); PG8_BAR; PG8_MMA(1, 1, At, B1); PG8_BAR;
;             PG8_LDB(B0, 1, 0); PG8_SCHED; PG8_LDA(At, 1, 0); PG8_STAGE(PG8_SA(0, 1), a2 + hstep, voffA);
;             PG8_WAIT_L(8); PG8_BAR; PG8_WAIT_L(0); PG8_MMA(0, 0, At, B0); PG8_BAR; PG8_SCHED;
;             PG8_LDB(B1, 1, 1); PG8_STAGE(PG8_SB(1, 0), b3, voffB);
	s_setprio 1
	v_mfma_f32_16x16x32_bf16 v[62:65], v[98:101], v[152:155], v[62:65]
	v_mfma_f32_16x16x32_bf16 v[58:61], v[106:109], v[152:155], v[58:61]
	v_mfma_f32_16x16x32_bf16 v[46:49], v[98:101], v[164:167], v[46:49]
	v_mfma_f32_16x16x32_bf16 v[42:45], v[106:109], v[164:167], v[42:45]
	v_mfma_f32_16x16x32_bf16 v[30:33], v[98:101], v[176:179], v[30:33]
	v_mfma_f32_16x16x32_bf16 v[26:29], v[106:109], v[176:179], v[26:29]
	v_mfma_f32_16x16x32_bf16 v[22:25], v[98:101], v[184:187], v[22:25]
	v_mfma_f32_16x16x32_bf16 v[18:21], v[106:109], v[184:187], v[18:21]
	v_mfma_f32_16x16x32_bf16 v[62:65], v[102:105], v[160:163], v[62:65]
	v_mfma_f32_16x16x32_bf16 v[58:61], v[110:113], v[160:163], v[58:61]
	v_mfma_f32_16x16x32_bf16 v[46:49], v[102:105], v[172:175], v[46:49]
	v_mfma_f32_16x16x32_bf16 v[42:45], v[110:113], v[172:175], v[42:45]
	v_mfma_f32_16x16x32_bf16 v[30:33], v[102:105], v[180:183], v[30:33]
	v_mfma_f32_16x16x32_bf16 v[26:29], v[110:113], v[180:183], v[26:29]
	v_mfma_f32_16x16x32_bf16 v[22:25], v[102:105], v[188:191], v[22:25]
	v_mfma_f32_16x16x32_bf16 v[18:21], v[110:113], v[188:191], v[18:21]
	v_mfma_f32_16x16x32_bf16 v[54:57], v[192:195], v[152:155], v[54:57]
	v_mfma_f32_16x16x32_bf16 v[50:53], v[200:203], v[152:155], v[50:53]
	v_mfma_f32_16x16x32_bf16 v[38:41], v[192:195], v[164:167], v[38:41]
	v_mfma_f32_16x16x32_bf16 v[34:37], v[200:203], v[164:167], v[34:37]
	v_mfma_f32_16x16x32_bf16 v[14:17], v[192:195], v[176:179], v[14:17]
	v_mfma_f32_16x16x32_bf16 v[10:13], v[200:203], v[176:179], v[10:13]
	v_mfma_f32_16x16x32_bf16 v[6:9], v[192:195], v[184:187], v[6:9]
	v_mfma_f32_16x16x32_bf16 v[2:5], v[200:203], v[184:187], v[2:5]
	v_mfma_f32_16x16x32_bf16 v[54:57], v[196:199], v[160:163], v[54:57]
	v_mfma_f32_16x16x32_bf16 v[50:53], v[204:207], v[160:163], v[50:53]
	v_mfma_f32_16x16x32_bf16 v[38:41], v[196:199], v[172:175], v[38:41]
	v_mfma_f32_16x16x32_bf16 v[34:37], v[204:207], v[172:175], v[34:37]
	v_mfma_f32_16x16x32_bf16 v[14:17], v[196:199], v[180:183], v[14:17]
	v_mfma_f32_16x16x32_bf16 v[10:13], v[204:207], v[180:183], v[10:13]
	v_mfma_f32_16x16x32_bf16 v[6:9], v[196:199], v[188:191], v[6:9]
	v_mfma_f32_16x16x32_bf16 v[2:5], v[204:207], v[188:191], v[2:5]
	s_setprio 0
	s_barrier
	s_add_u32 s28, s58, 0x80000
	s_addc_u32 s29, s59, 0
	s_add_i32 s38, s39, s67
	v_lshl_add_u64 v[98:99], s[28:29], 0, v[0:1]
	s_mov_b32 m0, s38
	s_nop 0
	global_load_lds_dwordx4 v[98:99], off
	v_lshl_add_u64 v[98:99], s[28:29], 0, v[146:147]
	s_add_i32 m0, s38, 0x2000
	s_nop 0
	global_load_lds_dwordx4 v[98:99], off
	s_add_u32 s28, s60, 0x80000
	s_addc_u32 s29, s61, 0
	s_mov_b32 m0, s69
	v_lshl_add_u64 v[192:193], s[28:29], 0, v[0:1]
	global_load_lds_dwordx4 v[192:193], off
	v_lshl_add_u64 v[192:193], s[28:29], 0, v[146:147]
	s_mov_b32 m0, s70
	s_nop 0
	global_load_lds_dwordx4 v[192:193], off
	s_add_i32 s38, 0, 0x18000
	v_add_u32_e32 v110, s38, v169
	ds_read_b128 v[98:101], v110
	ds_read_b128 v[102:105], v110 offset:1024
	ds_read_b128 v[106:109], v110 offset:2048
	ds_read_b128 v[110:113], v110 offset:3072
	ds_read_b128 v[152:155], v171 offset:32768
	ds_read_b128 v[160:163], v171 offset:33792
	ds_read_b128 v[164:167], v171 offset:34816
	ds_read_b128 v[172:175], v171 offset:35840
	ds_read_b128 v[176:179], v171 offset:36864
	ds_read_b128 v[180:183], v171 offset:37888
	ds_read_b128 v[184:187], v171 offset:38912
	ds_read_b128 v[188:191], v171 offset:39936
	s_add_i32 s39, 0, 0x1c000
	v_add_u32_e32 v204, s39, v169
	ds_read_b128 v[192:195], v204
	ds_read_b128 v[196:199], v204 offset:1024
	ds_read_b128 v[200:203], v204 offset:2048
	ds_read_b128 v[204:207], v204 offset:3072
	s_waitcnt lgkmcnt(4)
	s_barrier
; #define PG8_STAGE(bufoff, gbase, voff) do { _Pragma("unroll") for (int _i = 0; _i < 2; ++_i) \
;         __builtin_amdgcn_global_load_lds((const unsigned*)((const char*)(gbase) + (voff)[_i]), (LAS unsigned*)(lds + (bufoff) + ldsw + _i * 8192), 16, 0, 0); } while (0)
; #define PG8_LDA(dst, b, h) do { _Pragma("unroll") for (int m = 0; m < 4; ++m) _Pragma("unroll") for (int k = 0; k < 2; ++k) dst[m][k] = *(const LAS bf16x8*)(lds + PG8_SA(b, h) + aoff + m * 2048 + k * 1024); } while (0)
; #define PG8_LDB(dst, b, h) do { _Pragma("unroll") for (int n = 0; n < 2; ++n) _Pragma("unroll") for (int k = 0; k < 2; ++k) dst[n][k] = *(const LAS bf16x8*)(lds + PG8_SB(b, h) + boff + n * 2048 + k * 1024); } while (0)
; #define PG8_MMA(ai, bj, At, Bt) do { __builtin_amdgcn_s_setprio(1); _Pragma("unroll") for (int m = 0; m < 4; ++m) _Pragma("unroll") for (int n = 0; n < 2; ++n) _Pragma("unroll") for (int k = 0; k < 2; ++k) \
;         acc[ai][bj][m][n] = __builtin_amdgcn_mfma_f32_16x16x32_bf16(Bt[n][k], At[m][k], acc[ai][bj][m][n], 0, 0, 0); __builtin_amdgcn_s_setprio(0); } while (0)
; #define PG8_WAIT_V(n) asm volatile("s_waitcnt vmcnt(" #n ")" ::: "memory")
; #define PG8_WAIT_L(n) asm volatile("s_waitcnt lgkmcnt(" #n ")" ::: "memory")
; #define PG8_BAR __builtin_amdgcn_s_barrier()
; #define PG8_SCHED __builtin_amdgcn_sched_barrier(0)
; template <class Epi, class Sched>
; __device__ __forceinline__ void gemm_phase(LAS unsigned char* lds, const Gemm g, const Sched& S, const Epi& E) {
;     ...
;             PG8_WAIT_L(8); PG8_BAR; PG8_WAIT_L(0); PG8_MMA(0, 0, At, B0); PG8_BAR; PG8_SCHED;
;             PG8_LDB(B1, 1, 1); PG8_STAGE(PG8_SB(1, 0), b3, voffB);
;             PG8_BAR; PG8_WAIT_L(0); PG8_MMA(0, 1, At, B1); PG8_BAR;
;             PG8_LDA(At, 1, 1); PG8_STAGE(PG8_SA(1, 0), a3, voffA);
;             PG8_BAR; PG8_WAIT_L(0); PG8_MMA(1, 0, At, B0); PG8_BAR; PG8_SCHED;
;             PG8_STAGE(PG8_SB(1, 1), b3 + hstep, voffB);
;             PG8_WAIT_V(6); PG8_BAR; PG8_MMA(1, 1, At, B1); PG8_BAR;
;         }
;         E(acc, cur, wr, wc, fr, fq);
	s_waitcnt lgkmcnt(0)
	s_setprio 1
	v_mfma_f32_16x16x32_bf16 v[142:145], v[98:101], v[152:155], v[142:145]
	v_mfma_f32_16x16x32_bf16 v[138:141], v[106:109], v[152:155], v[138:141]
	v_mfma_f32_16x16x32_bf16 v[126:129], v[98:101], v[164:167], v[126:129]
	v_mfma_f32_16x16x32_bf16 v[122:125], v[106:109], v[164:167], v[122:125]
	v_mfma_f32_16x16x32_bf16 v[94:97], v[98:101], v[176:179], v[94:97]
	v_mfma_f32_16x16x32_bf16 v[90:93], v[106:109], v[176:179], v[90:93]
	v_mfma_f32_16x16x32_bf16 v[86:89], v[98:101], v[184:187], v[86:89]
	v_mfma_f32_16x16x32_bf16 v[82:85], v[106:109], v[184:187], v[82:85]
	v_mfma_f32_16x16x32_bf16 v[142:145], v[102:105], v[160:163], v[142:145]
	v_mfma_f32_16x16x32_bf16 v[138:141], v[110:113], v[160:163], v[138:141]
	v_mfma_f32_16x16x32_bf16 v[126:129], v[102:105], v[172:175], v[126:129]
	v_mfma_f32_16x16x32_bf16 v[122:125], v[110:113], v[172:175], v[122:125]
	v_mfma_f32_16x16x32_bf16 v[94:97], v[102:105], v[180:183], v[94:97]
	v_mfma_f32_16x16x32_bf16 v[90:93], v[110:113], v[180:183], v[90:93]
	v_mfma_f32_16x16x32_bf16 v[86:89], v[102:105], v[188:191], v[86:89]
	v_mfma_f32_16x16x32_bf16 v[82:85], v[110:113], v[188:191], v[82:85]
	v_mfma_f32_16x16x32_bf16 v[134:137], v[192:195], v[152:155], v[134:137]
	v_mfma_f32_16x16x32_bf16 v[130:133], v[200:203], v[152:155], v[130:133]
	v_mfma_f32_16x16x32_bf16 v[118:121], v[192:195], v[164:167], v[118:121]
	v_mfma_f32_16x16x32_bf16 v[114:117], v[200:203], v[164:167], v[114:117]
	v_mfma_f32_16x16x32_bf16 v[78:81], v[192:195], v[176:179], v[78:81]
	v_mfma_f32_16x16x32_bf16 v[74:77], v[200:203], v[176:179], v[74:77]
	v_mfma_f32_16x16x32_bf16 v[70:73], v[192:195], v[184:187], v[70:73]
	v_mfma_f32_16x16x32_bf16 v[66:69], v[200:203], v[184:187], v[66:69]
	v_mfma_f32_16x16x32_bf16 v[134:137], v[196:199], v[160:163], v[134:137]
	v_mfma_f32_16x16x32_bf16 v[130:133], v[204:207], v[160:163], v[130:133]
	v_mfma_f32_16x16x32_bf16 v[118:121], v[196:199], v[172:175], v[118:121]
	v_mfma_f32_16x16x32_bf16 v[114:117], v[204:207], v[172:175], v[114:117]
	v_mfma_f32_16x16x32_bf16 v[78:81], v[196:199], v[180:183], v[78:81]
	v_mfma_f32_16x16x32_bf16 v[74:77], v[204:207], v[180:183], v[74:77]
	v_mfma_f32_16x16x32_bf16 v[70:73], v[196:199], v[188:191], v[70:73]
	v_mfma_f32_16x16x32_bf16 v[66:69], v[204:207], v[188:191], v[66:69]
	s_setprio 0
	s_barrier
	s_add_i32 s28, s38, s67
	v_lshl_add_u64 v[156:157], v[156:157], 0, s[36:37]
	s_mov_b32 m0, s28
	s_nop 0
	global_load_lds_dwordx4 v[156:157], off
	v_lshl_add_u64 v[156:157], v[210:211], 0, s[36:37]
	s_add_i32 m0, s28, 0x2000
	s_nop 0
	global_load_lds_dwordx4 v[156:157], off
	s_mov_b32 m0, s72
	v_lshl_add_u64 v[156:157], v[212:213], 0, s[36:37]
	global_load_lds_dwordx4 v[156:157], off
	v_lshl_add_u64 v[156:157], v[214:215], 0, s[36:37]
	s_mov_b32 m0, s73
	s_nop 0
	global_load_lds_dwordx4 v[156:157], off
	ds_read_b128 v[152:155], v171 offset:49152
	ds_read_b128 v[160:163], v171 offset:50176
	ds_read_b128 v[164:167], v171 offset:51200
	ds_read_b128 v[172:175], v171 offset:52224
	ds_read_b128 v[176:179], v171 offset:53248
	ds_read_b128 v[180:183], v171 offset:54272
	ds_read_b128 v[184:187], v171 offset:55296
	ds_read_b128 v[188:191], v171 offset:56320
	s_waitcnt vmcnt(4)
	s_waitcnt lgkmcnt(0)
	s_barrier
	s_setprio 1
	v_mfma_f32_16x16x32_bf16 v[62:65], v[98:101], v[152:155], v[62:65]
	v_mfma_f32_16x16x32_bf16 v[58:61], v[106:109], v[152:155], v[58:61]
	v_mfma_f32_16x16x32_bf16 v[46:49], v[98:101], v[164:167], v[46:49]
	v_mfma_f32_16x16x32_bf16 v[42:45], v[106:109], v[164:167], v[42:45]
	v_mfma_f32_16x16x32_bf16 v[30:33], v[98:101], v[176:179], v[30:33]
	v_mfma_f32_16x16x32_bf16 v[26:29], v[106:109], v[176:179], v[26:29]
	v_mfma_f32_16x16x32_bf16 v[22:25], v[98:101], v[184:187], v[22:25]
	v_mfma_f32_16x16x32_bf16 v[18:21], v[106:109], v[184:187], v[18:21]
	v_mfma_f32_16x16x32_bf16 v[62:65], v[102:105], v[160:163], v[62:65]
	v_mfma_f32_16x16x32_bf16 v[58:61], v[110:113], v[160:163], v[58:61]
	v_mfma_f32_16x16x32_bf16 v[46:49], v[102:105], v[172:175], v[46:49]
	v_mfma_f32_16x16x32_bf16 v[42:45], v[110:113], v[172:175], v[42:45]
	v_mfma_f32_16x16x32_bf16 v[30:33], v[102:105], v[180:183], v[30:33]
	v_mfma_f32_16x16x32_bf16 v[26:29], v[110:113], v[180:183], v[26:29]
	v_mfma_f32_16x16x32_bf16 v[22:25], v[102:105], v[188:191], v[22:25]
	v_mfma_f32_16x16x32_bf16 v[18:21], v[110:113], v[188:191], v[18:21]
	v_mfma_f32_16x16x32_bf16 v[54:57], v[192:195], v[152:155], v[54:57]
	v_mfma_f32_16x16x32_bf16 v[50:53], v[200:203], v[152:155], v[50:53]
	v_mfma_f32_16x16x32_bf16 v[38:41], v[192:195], v[164:167], v[38:41]
	v_mfma_f32_16x16x32_bf16 v[34:37], v[200:203], v[164:167], v[34:37]
	v_mfma_f32_16x16x32_bf16 v[14:17], v[192:195], v[176:179], v[14:17]
	v_mfma_f32_16x16x32_bf16 v[10:13], v[200:203], v[176:179], v[10:13]
	v_mfma_f32_16x16x32_bf16 v[6:9], v[192:195], v[184:187], v[6:9]
	v_mfma_f32_16x16x32_bf16 v[2:5], v[200:203], v[184:187], v[2:5]
	v_mfma_f32_16x16x32_bf16 v[54:57], v[196:199], v[160:163], v[54:57]
	v_mfma_f32_16x16x32_bf16 v[50:53], v[204:207], v[160:163], v[50:53]
	v_mfma_f32_16x16x32_bf16 v[38:41], v[196:199], v[172:175], v[38:41]
	v_mfma_f32_16x16x32_bf16 v[34:37], v[204:207], v[172:175], v[34:37]
	v_mfma_f32_16x16x32_bf16 v[14:17], v[196:199], v[180:183], v[14:17]
	v_mfma_f32_16x16x32_bf16 v[10:13], v[204:207], v[180:183], v[10:13]
	v_mfma_f32_16x16x32_bf16 v[6:9], v[196:199], v[188:191], v[6:9]
	v_mfma_f32_16x16x32_bf16 v[2:5], v[204:207], v[188:191], v[2:5]
	s_setprio 0
	s_add_i32 s81, s81, 2
	s_add_u32 s79, s79, 0x100
	s_addc_u32 s80, s80, 0
	s_cmp_gt_u32 s81, 29
	s_mov_b64 s[28:29], s[56:57]
	s_barrier
	s_cbranch_scc0 .LBB0_99
	s_cmp_lt_i32 s8, 64
	s_cselect_b64 s[58:59], -1, 0
	s_cmp_gt_i32 s8, 63
	s_cbranch_scc0 .LBB0_90
	s_mov_b64 s[60:61], 0x18000
	s_mov_b64 s[28:29], s[46:47]
	s_mov_b64 s[56:57], s[24:25]
	s_branch .LBB0_91

; #define PG8_STAGE(bufoff, gbase, voff) do { _Pragma("unroll") for (int _i = 0; _i < 2; ++_i) \
;         __builtin_amdgcn_global_load_lds((const unsigned*)((const char*)(gbase) + (voff)[_i]), (LAS unsigned*)(lds + (bufoff) + ldsw + _i * 8192), 16, 0, 0); } while (0)
; #define PG8_LDA(dst, b, h) do { _Pragma("unroll") for (int m = 0; m < 4; ++m) _Pragma("unroll") for (int k = 0; k < 2; ++k) dst[m][k] = *(const LAS bf16x8*)(lds + PG8_SA(b, h) + aoff + m * 2048 + k * 1024); } while (0)
; #define PG8_LDB(dst, b, h) do { _Pragma("unroll") for (int n = 0; n < 2; ++n) _Pragma("unroll") for (int k = 0; k < 2; ++k) dst[n][k] = *(const LAS bf16x8*)(lds + PG8_SB(b, h) + boff + n * 2048 + k * 1024); } while (0)
; #define PG8_MMA(ai, bj, At, Bt) do { __builtin_amdgcn_s_setprio(1); _Pragma("unroll") for (int m = 0; m < 4; ++m) _Pragma("unroll") for (int n = 0; n < 2; ++n) _Pragma("unroll") for (int k = 0; k < 2; ++k) \
;         acc[ai][bj][m][n] = __builtin_amdgcn_mfma_f32_16x16x32_bf16(Bt[n][k], At[m][k], acc[ai][bj][m][n], 0, 0, 0); __builtin_amdgcn_s_setprio(0); } while (0)
; #define PG8_WAIT_L(n) asm volatile("s_waitcnt lgkmcnt(" #n ")" ::: "memory")
; #define PG8_BAR __builtin_amdgcn_s_barrier()
; #define PG8_SCHED __builtin_amdgcn_sched_barrier(0)
; template <class Epi, class Sched>
; __device__ __forceinline__ void gemm_phase(LAS unsigned char* lds, const Gemm g, const Sched& S, const Epi& E) {
;     ...
;             PG8_LDB(B0, 0, 0); PG8_SCHED; PG8_LDA(At, 0, 0); PG8_STAGE(PG8_SA(1, 1), a1 + hstep, voffA);
;             PG8_WAIT_L(8); PG8_BAR; PG8_WAIT_L(0); PG8_MMA(0, 0, At, B0); PG8_BAR; PG8_SCHED;
;             PG8_LDB(B1, 0, 1); PG8_STAGE(PG8_SB(0, 0), b2, voffB);
;             PG8_BAR; PG8_WAIT_L(0); PG8_MMA(0, 1, At, B1); PG8_BAR;
;             PG8_LDA(At, 0, 1); PG8_STAGE(PG8_SA(0, 0), a2, voffA);
;             PG8_BAR; PG8_WAIT_L(0); PG8_MMA(1, 0, At, B0); PG8_BAR; PG8_SCHED;
;             PG8_STAGE(PG8_SB(0, 1), b2 + hstep, voffB);
.LBB0_113:
	s_add_u32 s100, s71, 0x7ff80
	s_addc_u32 s101, s72, 0
	v_lshl_add_u64 v[140:141], s[100:101], 0, v[0:1]
	s_add_i32 m0, s65, 0x1c000
	s_nop 0
	global_load_lds_dwordx4 v[140:141], off
	v_lshl_add_u64 v[140:141], s[100:101], 0, v[130:131]
	s_add_i32 m0, s65, 0x1e000
	s_nop 0
	global_load_lds_dwordx4 v[140:141], off
	s_add_u32 s54, s52, 0x100
	s_addc_u32 s55, s53, 0
	s_cmp_eq_u32 s73, 4
	s_cselect_b32 s59, s11, s55
	s_cselect_b32 s58, s29, s54
	s_cselect_b32 s57, s41, s72
	s_cselect_b32 s56, s45, s71
	v_lshl_add_u64 v[156:157], s[52:53], 0, v[134:135]
	s_add_i32 m0, s25, 0xc000
	s_nop 0
	global_load_lds_dwordx4 v[156:157], off
	v_lshl_add_u64 v[156:157], s[52:53], 0, v[132:133]
	s_add_i32 m0, s25, 0xe000
	s_nop 0
	global_load_lds_dwordx4 v[156:157], off
	s_add_i32 s38, 0, 0x10000
	v_add_u32_e32 v152, s38, v137
	ds_read_b128 v[140:143], v152
	ds_read_b128 v[144:147], v152 offset:1024
	ds_read_b128 v[148:151], v152 offset:2048
	ds_read_b128 v[152:155], v152 offset:3072
	ds_read_b128 v[160:163], v139
	ds_read_b128 v[164:167], v139 offset:1024
	ds_read_b128 v[168:171], v139 offset:2048
	ds_read_b128 v[172:175], v139 offset:3072
	ds_read_b128 v[176:179], v139 offset:4096
	ds_read_b128 v[180:183], v139 offset:5120
	ds_read_b128 v[184:187], v139 offset:6144
	ds_read_b128 v[188:191], v139 offset:7168
	s_add_i32 s52, 0, 0x14000
	v_add_u32_e32 v156, s52, v137
	ds_read_b128 v[192:195], v156
	ds_read_b128 v[196:199], v156 offset:1024
	ds_read_b128 v[200:203], v156 offset:2048
	ds_read_b128 v[204:207], v156 offset:3072
	s_waitcnt lgkmcnt(4)
	s_barrier
	s_waitcnt lgkmcnt(0)
	s_setprio 1
	v_mfma_f32_16x16x32_bf16 v[126:129], v[140:143], v[160:163], v[126:129]
	v_mfma_f32_16x16x32_bf16 v[122:125], v[148:151], v[160:163], v[122:125]
	v_mfma_f32_16x16x32_bf16 v[118:121], v[140:143], v[168:171], v[118:121]
	v_mfma_f32_16x16x32_bf16 v[114:117], v[148:151], v[168:171], v[114:117]
	v_mfma_f32_16x16x32_bf16 v[106:109], v[140:143], v[176:179], v[106:109]
	v_mfma_f32_16x16x32_bf16 v[98:101], v[148:151], v[176:179], v[98:101]
	v_mfma_f32_16x16x32_bf16 v[90:93], v[140:143], v[184:187], v[90:93]
	v_mfma_f32_16x16x32_bf16 v[82:85], v[148:151], v[184:187], v[82:85]
	v_mfma_f32_16x16x32_bf16 v[126:129], v[144:147], v[164:167], v[126:129]
	v_mfma_f32_16x16x32_bf16 v[122:125], v[152:155], v[164:167], v[122:125]
	v_mfma_f32_16x16x32_bf16 v[118:121], v[144:147], v[172:175], v[118:121]
	v_mfma_f32_16x16x32_bf16 v[114:117], v[152:155], v[172:175], v[114:117]
	v_mfma_f32_16x16x32_bf16 v[106:109], v[144:147], v[180:183], v[106:109]
	v_mfma_f32_16x16x32_bf16 v[98:101], v[152:155], v[180:183], v[98:101]
	v_mfma_f32_16x16x32_bf16 v[90:93], v[144:147], v[188:191], v[90:93]
	v_mfma_f32_16x16x32_bf16 v[82:85], v[152:155], v[188:191], v[82:85]
	v_mfma_f32_16x16x32_bf16 v[110:113], v[192:195], v[160:163], v[110:113]
	v_mfma_f32_16x16x32_bf16 v[102:105], v[200:203], v[160:163], v[102:105]
	v_mfma_f32_16x16x32_bf16 v[94:97], v[192:195], v[168:171], v[94:97]
	v_mfma_f32_16x16x32_bf16 v[86:89], v[200:203], v[168:171], v[86:89]
	v_mfma_f32_16x16x32_bf16 v[78:81], v[192:195], v[176:179], v[78:81]
	v_mfma_f32_16x16x32_bf16 v[74:77], v[200:203], v[176:179], v[74:77]
	v_mfma_f32_16x16x32_bf16 v[70:73], v[192:195], v[184:187], v[70:73]
	v_mfma_f32_16x16x32_bf16 v[66:69], v[200:203], v[184:187], v[66:69]
	v_mfma_f32_16x16x32_bf16 v[110:113], v[196:199], v[164:167], v[110:113]
	v_mfma_f32_16x16x32_bf16 v[102:105], v[204:207], v[164:167], v[102:105]
	v_mfma_f32_16x16x32_bf16 v[94:97], v[196:199], v[172:175], v[94:97]
	v_mfma_f32_16x16x32_bf16 v[86:89], v[204:207], v[172:175], v[86:89]
	v_mfma_f32_16x16x32_bf16 v[78:81], v[196:199], v[180:183], v[78:81]
	v_mfma_f32_16x16x32_bf16 v[74:77], v[204:207], v[180:183], v[74:77]
	v_mfma_f32_16x16x32_bf16 v[70:73], v[196:199], v[188:191], v[70:73]
	v_mfma_f32_16x16x32_bf16 v[66:69], v[204:207], v[188:191], v[66:69]
	s_setprio 0
	s_barrier
	s_add_i32 s38, s38, s65
	v_lshl_add_u64 v[156:157], s[56:57], 0, v[0:1]
	s_mov_b32 m0, s38
	v_lshl_add_u64 v[210:211], s[56:57], 0, v[130:131]
	global_load_lds_dwordx4 v[156:157], off
	s_add_i32 m0, s38, 0x2000
	s_nop 0
	global_load_lds_dwordx4 v[210:211], off
	s_mov_b32 m0, s25
	v_lshl_add_u64 v[212:213], s[58:59], 0, v[0:1]
	global_load_lds_dwordx4 v[212:213], off
	v_lshl_add_u64 v[214:215], s[58:59], 0, v[130:131]
	s_mov_b32 m0, s27
	s_nop 0
	global_load_lds_dwordx4 v[214:215], off
	ds_read_b128 v[160:163], v139 offset:16384
	ds_read_b128 v[164:167], v139 offset:17408
	ds_read_b128 v[168:171], v139 offset:18432
	ds_read_b128 v[172:175], v139 offset:19456
	ds_read_b128 v[176:179], v139 offset:20480
	ds_read_b128 v[180:183], v139 offset:21504
	ds_read_b128 v[184:187], v139 offset:22528
	ds_read_b128 v[188:191], v139 offset:23552
	s_waitcnt vmcnt(4)
	s_waitcnt lgkmcnt(0)
	s_barrier
; #define PG8_STAGE(bufoff, gbase, voff) do { _Pragma("unroll") for (int _i = 0; _i < 2; ++_i) \
;         __builtin_amdgcn_global_load_lds((const unsigned*)((const char*)(gbase) + (voff)[_i]), (LAS unsigned*)(lds + (bufoff) + ldsw + _i * 8192), 16, 0, 0); } while (0)
; #define PG8_LDA(dst, b, h) do { _Pragma("unroll") for (int m = 0; m < 4; ++m) _Pragma("unroll") for (int k = 0; k < 2; ++k) dst[m][k] = *(const LAS bf16x8*)(lds + PG8_SA(b, h) + aoff + m * 2048 + k * 1024); } while (0)
; #define PG8_LDB(dst, b, h) do { _Pragma("unroll") for (int n = 0; n < 2; ++n) _Pragma("unroll") for (int k = 0; k < 2; ++k) dst[n][k] = *(const LAS bf16x8*)(lds + PG8_SB(b, h) + boff + n * 2048 + k * 1024); } while (0)
; #define PG8_MMA(ai, bj, At, Bt) do { __builtin_amdgcn_s_setprio(1); _Pragma("unroll") for (int m = 0; m < 4; ++m) _Pragma("unroll") for (int n = 0; n < 2; ++n) _Pragma("unroll") for (int k = 0; k < 2; ++k) \
;         acc[ai][bj][m][n] = __builtin_amdgcn_mfma_f32_16x16x32_bf16(Bt[n][k], At[m][k], acc[ai][bj][m][n], 0, 0, 0); __builtin_amdgcn_s_setprio(0); } while (0)
; #define PG8_WAIT_V(n) asm volatile("s_waitcnt vmcnt(" #n ")" ::: "memory")
; #define PG8_WAIT_L(n) asm volatile("s_waitcnt lgkmcnt(" #n ")" ::: "memory")
; #define PG8_BAR __builtin_amdgcn_s_barrier()
; #define PG8_SCHED __builtin_amdgcn_sched_barrier(0)
; template <class Epi, class Sched>
; __device__ __forceinline__ void gemm_phase(LAS unsigned char* lds, const Gemm g, const Sched& S, const Epi& E) {
;     ...
;             PG8_BAR; PG8_WAIT_L(0); PG8_MMA(1, 0, At, B0); PG8_BAR; PG8_SCHED;
;             PG8_STAGE(PG8_SB(0, 1), b2 + hstep, voffB);
;             PG8_WAIT_V(6); PG8_BAR; PG8_MMA(1, 1, At, B1); PG8_BAR;
;             PG8_LDB(B0, 1, 0); PG8_SCHED; PG8_LDA(At, 1, 0); PG8_STAGE(PG8_SA(0, 1), a2 + hstep, voffA);
;             PG8_WAIT_L(8); PG8_BAR; PG8_WAIT_L(0); PG8_MMA(0, 0, At, B0); PG8_BAR; PG8_SCHED;
;             PG8_LDB(B1, 1, 1); PG8_STAGE(PG8_SB(1, 0), b3, voffB);
;             PG8_BAR; PG8_WAIT_L(0); PG8_MMA(0, 1, At, B1); PG8_BAR;
	s_setprio 1
	v_mfma_f32_16x16x32_bf16 v[62:65], v[140:143], v[160:163], v[62:65]
	v_mfma_f32_16x16x32_bf16 v[58:61], v[148:151], v[160:163], v[58:61]
	v_mfma_f32_16x16x32_bf16 v[54:57], v[140:143], v[168:171], v[54:57]
	v_mfma_f32_16x16x32_bf16 v[50:53], v[148:151], v[168:171], v[50:53]
	v_mfma_f32_16x16x32_bf16 v[38:41], v[140:143], v[176:179], v[38:41]
	v_mfma_f32_16x16x32_bf16 v[34:37], v[148:151], v[176:179], v[34:37]
	v_mfma_f32_16x16x32_bf16 v[22:25], v[140:143], v[184:187], v[22:25]
	v_mfma_f32_16x16x32_bf16 v[18:21], v[148:151], v[184:187], v[18:21]
	v_mfma_f32_16x16x32_bf16 v[62:65], v[144:147], v[164:167], v[62:65]
	v_mfma_f32_16x16x32_bf16 v[58:61], v[152:155], v[164:167], v[58:61]
	v_mfma_f32_16x16x32_bf16 v[54:57], v[144:147], v[172:175], v[54:57]
	v_mfma_f32_16x16x32_bf16 v[50:53], v[152:155], v[172:175], v[50:53]
	v_mfma_f32_16x16x32_bf16 v[38:41], v[144:147], v[180:183], v[38:41]
	v_mfma_f32_16x16x32_bf16 v[34:37], v[152:155], v[180:183], v[34:37]
	v_mfma_f32_16x16x32_bf16 v[22:25], v[144:147], v[188:191], v[22:25]
	v_mfma_f32_16x16x32_bf16 v[18:21], v[152:155], v[188:191], v[18:21]
	v_mfma_f32_16x16x32_bf16 v[46:49], v[192:195], v[160:163], v[46:49]
	v_mfma_f32_16x16x32_bf16 v[42:45], v[200:203], v[160:163], v[42:45]
	v_mfma_f32_16x16x32_bf16 v[30:33], v[192:195], v[168:171], v[30:33]
	v_mfma_f32_16x16x32_bf16 v[26:29], v[200:203], v[168:171], v[26:29]
	v_mfma_f32_16x16x32_bf16 v[14:17], v[192:195], v[176:179], v[14:17]
	v_mfma_f32_16x16x32_bf16 v[10:13], v[200:203], v[176:179], v[10:13]
	v_mfma_f32_16x16x32_bf16 v[6:9], v[192:195], v[184:187], v[6:9]
	v_mfma_f32_16x16x32_bf16 v[2:5], v[200:203], v[184:187], v[2:5]
	v_mfma_f32_16x16x32_bf16 v[46:49], v[196:199], v[164:167], v[46:49]
	v_mfma_f32_16x16x32_bf16 v[42:45], v[204:207], v[164:167], v[42:45]
	v_mfma_f32_16x16x32_bf16 v[30:33], v[196:199], v[172:175], v[30:33]
	v_mfma_f32_16x16x32_bf16 v[26:29], v[204:207], v[172:175], v[26:29]
	v_mfma_f32_16x16x32_bf16 v[14:17], v[196:199], v[180:183], v[14:17]
	v_mfma_f32_16x16x32_bf16 v[10:13], v[204:207], v[180:183], v[10:13]
	v_mfma_f32_16x16x32_bf16 v[6:9], v[196:199], v[188:191], v[6:9]
	v_mfma_f32_16x16x32_bf16 v[2:5], v[204:207], v[188:191], v[2:5]
	s_setprio 0
	s_barrier
	s_add_u32 s38, s56, 0x80000
	s_addc_u32 s39, s57, 0
	s_add_i32 s52, s52, s65
	v_lshl_add_u64 v[140:141], s[38:39], 0, v[0:1]
	s_mov_b32 m0, s52
	s_nop 0
	global_load_lds_dwordx4 v[140:141], off
	v_lshl_add_u64 v[140:141], s[38:39], 0, v[130:131]
	s_add_i32 m0, s52, 0x2000
	s_nop 0
	global_load_lds_dwordx4 v[140:141], off
	s_add_u32 s38, s58, 0x80000
	s_addc_u32 s39, s59, 0
	s_mov_b32 m0, s66
	v_lshl_add_u64 v[192:193], s[38:39], 0, v[0:1]
	global_load_lds_dwordx4 v[192:193], off
	v_lshl_add_u64 v[192:193], s[38:39], 0, v[130:131]
	s_mov_b32 m0, s67
	s_nop 0
	global_load_lds_dwordx4 v[192:193], off
	s_add_i32 s52, 0, 0x18000
	v_add_u32_e32 v152, s52, v137
	ds_read_b128 v[140:143], v152
	ds_read_b128 v[144:147], v152 offset:1024
	ds_read_b128 v[148:151], v152 offset:2048
	ds_read_b128 v[152:155], v152 offset:3072
	ds_read_b128 v[160:163], v139 offset:32768
	ds_read_b128 v[164:167], v139 offset:33792
	ds_read_b128 v[168:171], v139 offset:34816
	ds_read_b128 v[172:175], v139 offset:35840
	ds_read_b128 v[176:179], v139 offset:36864
	ds_read_b128 v[180:183], v139 offset:37888
	ds_read_b128 v[184:187], v139 offset:38912
	ds_read_b128 v[188:191], v139 offset:39936
	s_add_i32 s53, 0, 0x1c000
	v_add_u32_e32 v204, s53, v137
	ds_read_b128 v[192:195], v204
	ds_read_b128 v[196:199], v204 offset:1024
	ds_read_b128 v[200:203], v204 offset:2048
	ds_read_b128 v[204:207], v204 offset:3072
	s_waitcnt lgkmcnt(4)
	s_barrier
	s_waitcnt lgkmcnt(0)
	s_setprio 1
	v_mfma_f32_16x16x32_bf16 v[126:129], v[140:143], v[160:163], v[126:129]
	v_mfma_f32_16x16x32_bf16 v[122:125], v[148:151], v[160:163], v[122:125]
	v_mfma_f32_16x16x32_bf16 v[118:121], v[140:143], v[168:171], v[118:121]
	v_mfma_f32_16x16x32_bf16 v[114:117], v[148:151], v[168:171], v[114:117]
	v_mfma_f32_16x16x32_bf16 v[106:109], v[140:143], v[176:179], v[106:109]
	v_mfma_f32_16x16x32_bf16 v[98:101], v[148:151], v[176:179], v[98:101]
	v_mfma_f32_16x16x32_bf16 v[90:93], v[140:143], v[184:187], v[90:93]
	v_mfma_f32_16x16x32_bf16 v[82:85], v[148:151], v[184:187], v[82:85]
	v_mfma_f32_16x16x32_bf16 v[126:129], v[144:147], v[164:167], v[126:129]
	v_mfma_f32_16x16x32_bf16 v[122:125], v[152:155], v[164:167], v[122:125]
	v_mfma_f32_16x16x32_bf16 v[118:121], v[144:147], v[172:175], v[118:121]
	v_mfma_f32_16x16x32_bf16 v[114:117], v[152:155], v[172:175], v[114:117]
	v_mfma_f32_16x16x32_bf16 v[106:109], v[144:147], v[180:183], v[106:109]
	v_mfma_f32_16x16x32_bf16 v[98:101], v[152:155], v[180:183], v[98:101]
	v_mfma_f32_16x16x32_bf16 v[90:93], v[144:147], v[188:191], v[90:93]
	v_mfma_f32_16x16x32_bf16 v[82:85], v[152:155], v[188:191], v[82:85]
	v_mfma_f32_16x16x32_bf16 v[110:113], v[192:195], v[160:163], v[110:113]
	v_mfma_f32_16x16x32_bf16 v[102:105], v[200:203], v[160:163], v[102:105]
	v_mfma_f32_16x16x32_bf16 v[94:97], v[192:195], v[168:171], v[94:97]
	v_mfma_f32_16x16x32_bf16 v[86:89], v[200:203], v[168:171], v[86:89]
	v_mfma_f32_16x16x32_bf16 v[78:81], v[192:195], v[176:179], v[78:81]
	v_mfma_f32_16x16x32_bf16 v[74:77], v[200:203], v[176:179], v[74:77]
	v_mfma_f32_16x16x32_bf16 v[70:73], v[192:195], v[184:187], v[70:73]
	v_mfma_f32_16x16x32_bf16 v[66:69], v[200:203], v[184:187], v[66:69]
	v_mfma_f32_16x16x32_bf16 v[110:113], v[196:199], v[164:167], v[110:113]
	v_mfma_f32_16x16x32_bf16 v[102:105], v[204:207], v[164:167], v[102:105]
	v_mfma_f32_16x16x32_bf16 v[94:97], v[196:199], v[172:175], v[94:97]
	v_mfma_f32_16x16x32_bf16 v[86:89], v[204:207], v[172:175], v[86:89]
	v_mfma_f32_16x16x32_bf16 v[78:81], v[196:199], v[180:183], v[78:81]
	v_mfma_f32_16x16x32_bf16 v[74:77], v[204:207], v[180:183], v[74:77]
	v_mfma_f32_16x16x32_bf16 v[70:73], v[196:199], v[188:191], v[70:73]
	v_mfma_f32_16x16x32_bf16 v[66:69], v[204:207], v[188:191], v[66:69]
	s_setprio 0
	s_barrier
; #define PG8_STAGE(bufoff, gbase, voff) do { _Pragma("unroll") for (int _i = 0; _i < 2; ++_i) \
;         __builtin_amdgcn_global_load_lds((const unsigned*)((const char*)(gbase) + (voff)[_i]), (LAS unsigned*)(lds + (bufoff) + ldsw + _i * 8192), 16, 0, 0); } while (0)
; #define PG8_LDA(dst, b, h) do { _Pragma("unroll") for (int m = 0; m < 4; ++m) _Pragma("unroll") for (int k = 0; k < 2; ++k) dst[m][k] = *(const LAS bf16x8*)(lds + PG8_SA(b, h) + aoff + m * 2048 + k * 1024); } while (0)
; #define PG8_MMA(ai, bj, At, Bt) do { __builtin_amdgcn_s_setprio(1); _Pragma("unroll") for (int m = 0; m < 4; ++m) _Pragma("unroll") for (int n = 0; n < 2; ++n) _Pragma("unroll") for (int k = 0; k < 2; ++k) \
;         acc[ai][bj][m][n] = __builtin_amdgcn_mfma_f32_16x16x32_bf16(Bt[n][k], At[m][k], acc[ai][bj][m][n], 0, 0, 0); __builtin_amdgcn_s_setprio(0); } while (0)
; #define PG8_WAIT_V(n) asm volatile("s_waitcnt vmcnt(" #n ")" ::: "memory")
; #define PG8_WAIT_L(n) asm volatile("s_waitcnt lgkmcnt(" #n ")" ::: "memory")
; #define PG8_BAR __builtin_amdgcn_s_barrier()
; #define PG8_SCHED __builtin_amdgcn_sched_barrier(0)
;     __device__ __forceinline__ void operator()(const f32x4 (&acc)[2][2][4][2], const Unit& u, int wr, int wc, int fr, int fq) const {
;         const int row0 = u.pm * BM + wr * 64 + fr, col0 = u.pn * BM + wc * 32 + 4 * fq;
;         float* base = part + (size_t)u.ks * Mp * ldc;
; #pragma unroll
;         for (int ai = 0; ai < 2; ++ai)
; #pragma unroll
;             for (int m = 0; m < 4; ++m) { float* rowp = base + (size_t)(row0 + ai * HALF + m * 16) * ldc + col0;
; #pragma unroll
;                 for (int bj = 0; bj < 2; ++bj)
; #pragma unroll
;                     for (int n = 0; n < 2; ++n) *(f32x4*)(rowp + bj * HALF + n * 16) = acc[ai][bj][m][n]; }
;     }
; template <class Epi, class Sched>
; __device__ __forceinline__ void gemm_phase(LAS unsigned char* lds, const Gemm g, const Sched& S, const Epi& E) {
;     ...
;             PG8_BAR; PG8_WAIT_L(0); PG8_MMA(0, 1, At, B1); PG8_BAR;
;             PG8_LDA(At, 1, 1); PG8_STAGE(PG8_SA(1, 0), a3, voffA);
;             PG8_BAR; PG8_WAIT_L(0); PG8_MMA(1, 0, At, B0); PG8_BAR; PG8_SCHED;
;             PG8_STAGE(PG8_SB(1, 1), b3 + hstep, voffB);
;             PG8_WAIT_V(6); PG8_BAR; PG8_MMA(1, 1, At, B1); PG8_BAR;
;         }
;         E(acc, cur, wr, wc, fr, fq);
	s_add_i32 s38, s52, s65
	v_lshl_add_u64 v[156:157], v[156:157], 0, s[36:37]
	s_mov_b32 m0, s38
	s_nop 0
	global_load_lds_dwordx4 v[156:157], off
	v_lshl_add_u64 v[156:157], v[210:211], 0, s[36:37]
	s_add_i32 m0, s38, 0x2000
	s_nop 0
	global_load_lds_dwordx4 v[156:157], off
	s_mov_b32 m0, s68
	v_lshl_add_u64 v[156:157], v[212:213], 0, s[36:37]
	global_load_lds_dwordx4 v[156:157], off
	v_lshl_add_u64 v[156:157], v[214:215], 0, s[36:37]
	s_mov_b32 m0, s69
	s_nop 0
	global_load_lds_dwordx4 v[156:157], off
	ds_read_b128 v[160:163], v139 offset:49152
	ds_read_b128 v[164:167], v139 offset:50176
	ds_read_b128 v[168:171], v139 offset:51200
	ds_read_b128 v[172:175], v139 offset:52224
	ds_read_b128 v[176:179], v139 offset:53248
	ds_read_b128 v[180:183], v139 offset:54272
	ds_read_b128 v[184:187], v139 offset:55296
	ds_read_b128 v[188:191], v139 offset:56320
	s_waitcnt vmcnt(4)
	s_waitcnt lgkmcnt(0)
	s_barrier
	s_setprio 1
	v_mfma_f32_16x16x32_bf16 v[62:65], v[140:143], v[160:163], v[62:65]
	v_mfma_f32_16x16x32_bf16 v[58:61], v[148:151], v[160:163], v[58:61]
	v_mfma_f32_16x16x32_bf16 v[54:57], v[140:143], v[168:171], v[54:57]
	v_mfma_f32_16x16x32_bf16 v[50:53], v[148:151], v[168:171], v[50:53]
	v_mfma_f32_16x16x32_bf16 v[38:41], v[140:143], v[176:179], v[38:41]
	v_mfma_f32_16x16x32_bf16 v[34:37], v[148:151], v[176:179], v[34:37]
	v_mfma_f32_16x16x32_bf16 v[22:25], v[140:143], v[184:187], v[22:25]
	v_mfma_f32_16x16x32_bf16 v[18:21], v[148:151], v[184:187], v[18:21]
	v_mfma_f32_16x16x32_bf16 v[62:65], v[144:147], v[164:167], v[62:65]
	v_mfma_f32_16x16x32_bf16 v[58:61], v[152:155], v[164:167], v[58:61]
	v_mfma_f32_16x16x32_bf16 v[54:57], v[144:147], v[172:175], v[54:57]
	v_mfma_f32_16x16x32_bf16 v[50:53], v[152:155], v[172:175], v[50:53]
	v_mfma_f32_16x16x32_bf16 v[38:41], v[144:147], v[180:183], v[38:41]
	v_mfma_f32_16x16x32_bf16 v[34:37], v[152:155], v[180:183], v[34:37]
	v_mfma_f32_16x16x32_bf16 v[22:25], v[144:147], v[188:191], v[22:25]
	v_mfma_f32_16x16x32_bf16 v[18:21], v[152:155], v[188:191], v[18:21]
	v_mfma_f32_16x16x32_bf16 v[46:49], v[192:195], v[160:163], v[46:49]
	v_mfma_f32_16x16x32_bf16 v[42:45], v[200:203], v[160:163], v[42:45]
	v_mfma_f32_16x16x32_bf16 v[30:33], v[192:195], v[168:171], v[30:33]
	v_mfma_f32_16x16x32_bf16 v[26:29], v[200:203], v[168:171], v[26:29]
	v_mfma_f32_16x16x32_bf16 v[14:17], v[192:195], v[176:179], v[14:17]
	v_mfma_f32_16x16x32_bf16 v[10:13], v[200:203], v[176:179], v[10:13]
	v_mfma_f32_16x16x32_bf16 v[6:9], v[192:195], v[184:187], v[6:9]
	v_mfma_f32_16x16x32_bf16 v[2:5], v[200:203], v[184:187], v[2:5]
	v_mfma_f32_16x16x32_bf16 v[46:49], v[196:199], v[164:167], v[46:49]
	v_mfma_f32_16x16x32_bf16 v[42:45], v[204:207], v[164:167], v[42:45]
	v_mfma_f32_16x16x32_bf16 v[30:33], v[196:199], v[172:175], v[30:33]
	v_mfma_f32_16x16x32_bf16 v[26:29], v[204:207], v[172:175], v[26:29]
	v_mfma_f32_16x16x32_bf16 v[14:17], v[196:199], v[180:183], v[14:17]
	v_mfma_f32_16x16x32_bf16 v[10:13], v[204:207], v[180:183], v[10:13]
	v_mfma_f32_16x16x32_bf16 v[6:9], v[196:199], v[188:191], v[6:9]
	v_mfma_f32_16x16x32_bf16 v[2:5], v[204:207], v[188:191], v[2:5]
	s_setprio 0
	s_add_i32 s73, s73, 2
	s_add_u32 s71, s71, 0x100
	s_addc_u32 s72, s72, 0
	s_cmp_gt_u32 s73, 5
	s_mov_b64 s[52:53], s[54:55]
	s_barrier
	s_cbranch_scc0 .LBB0_113
	s_ashr_i32 s11, s10, 31
	s_lshl_b64 s[10:11], s[10:11], 24
	v_lshl_or_b32 v140, s26, 8, v138
	s_add_u32 s10, s8, s10
	v_lshl_add_u32 v142, s24, 8, v136
	s_addc_u32 s11, s9, s11
	v_ashrrev_i32_e32 v141, 31, v140
	v_ashrrev_i32_e32 v143, 31, v142
	v_lshl_add_u64 v[140:141], v[140:141], 2, s[10:11]
	v_lshlrev_b64 v[144:145], 13, v[142:143]
	v_lshl_add_u64 v[144:145], v[140:141], 0, v[144:145]
	global_store_dwordx4 v[144:145], v[126:129], off
	global_store_dwordx4 v[144:145], v[122:125], off offset:64
	global_store_dwordx4 v[144:145], v[110:113], off offset:512
	global_store_dwordx4 v[144:145], v[102:105], off offset:576
	s_mov_b64 s[10:11], 0x100000
	s_mov_b32 s26, s40
	v_or_b32_e32 v102, 16, v142
	v_ashrrev_i32_e32 v103, 31, v102
	v_lshlrev_b64 v[102:103], 13, v[102:103]
	v_lshl_add_u64 v[102:103], v[140:141], 0, v[102:103]
	global_store_dwordx4 v[102:103], v[118:121], off
	global_store_dwordx4 v[102:103], v[114:117], off offset:64
	global_store_dwordx4 v[102:103], v[94:97], off offset:512
	global_store_dwordx4 v[102:103], v[86:89], off offset:576
	s_mov_b32 s24, s44
	s_mov_b64 s[54:55], s[50:51]
	v_or_b32_e32 v86, 32, v142
	v_ashrrev_i32_e32 v87, 31, v86
	v_lshlrev_b64 v[86:87], 13, v[86:87]
	v_lshl_add_u64 v[86:87], v[140:141], 0, v[86:87]
	global_store_dwordx4 v[86:87], v[106:109], off
	global_store_dwordx4 v[86:87], v[98:101], off offset:64
	global_store_dwordx4 v[86:87], v[78:81], off offset:512
	global_store_dwordx4 v[86:87], v[74:77], off offset:576
	s_mov_b64 s[52:53], s[48:49]
	s_nop 0
	v_or_b32_e32 v74, 48, v142
	v_ashrrev_i32_e32 v75, 31, v74
	v_lshlrev_b64 v[74:75], 13, v[74:75]
	v_lshl_add_u64 v[74:75], v[140:141], 0, v[74:75]
	global_store_dwordx4 v[74:75], v[90:93], off
	global_store_dwordx4 v[74:75], v[82:85], off offset:64
	global_store_dwordx4 v[74:75], v[70:73], off offset:512
	global_store_dwordx4 v[74:75], v[66:69], off offset:576
	s_nop 1
	v_add_co_u32_e32 v68, vcc, s93, v144
	v_lshl_add_u64 v[66:67], v[144:145], 0, s[10:11]
	s_nop 0
	v_addc_co_u32_e32 v69, vcc, 0, v145, vcc
	s_mov_b64 s[10:11], 0x120000
	global_store_dwordx4 v[68:69], v[62:65], off
	global_store_dwordx4 v[66:67], v[58:61], off offset:64
	global_store_dwordx4 v[66:67], v[46:49], off offset:512
	global_store_dwordx4 v[66:67], v[42:45], off offset:576
	s_nop 1
	v_lshl_add_u64 v[42:43], v[144:145], 0, s[10:11]
	s_mov_b32 s10, 0x120000
	v_add_co_u32_e32 v44, vcc, s10, v144
	s_mov_b64 s[10:11], 0x140000
	s_nop 0
	v_addc_co_u32_e32 v45, vcc, 0, v145, vcc
	global_store_dwordx4 v[44:45], v[54:57], off
	global_store_dwordx4 v[42:43], v[50:53], off offset:64
	global_store_dwordx4 v[42:43], v[30:33], off offset:512
	global_store_dwordx4 v[42:43], v[26:29], off offset:576
	s_nop 1
	v_lshl_add_u64 v[26:27], v[144:145], 0, s[10:11]
	s_mov_b32 s10, 0x140000
	v_add_co_u32_e32 v28, vcc, s10, v144
	s_mov_b64 s[10:11], 0x160000
	s_nop 0
	v_addc_co_u32_e32 v29, vcc, 0, v145, vcc
	global_store_dwordx4 v[28:29], v[38:41], off
	global_store_dwordx4 v[26:27], v[34:37], off offset:64
	global_store_dwordx4 v[26:27], v[14:17], off offset:512
	global_store_dwordx4 v[26:27], v[10:13], off offset:576
	s_nop 1
	v_add_co_u32_e32 v12, vcc, 0x160000, v144
	v_lshl_add_u64 v[10:11], v[144:145], 0, s[10:11]
	s_nop 0
	v_addc_co_u32_e32 v13, vcc, 0, v145, vcc
	s_and_b64 vcc, exec, s[46:47]
	s_mov_b32 s10, s28
	global_store_dwordx4 v[12:13], v[22:25], off
	global_store_dwordx4 v[10:11], v[18:21], off offset:64
	global_store_dwordx4 v[10:11], v[6:9], off offset:512
	global_store_dwordx4 v[10:11], v[2:5], off offset:576
	s_cbranch_vccz .LBB0_110
	s_waitcnt vmcnt(0)
	s_cmpk_gt_u32 s60, 0xff
	s_cbranch_scc1 .LBB0_117
	s_barrier

; #define PG8_STAGE(bufoff, gbase, voff) do { _Pragma("unroll") for (int _i = 0; _i < 2; ++_i) \
;         __builtin_amdgcn_global_load_lds((const unsigned*)((const char*)(gbase) + (voff)[_i]), (LAS unsigned*)(lds + (bufoff) + ldsw + _i * 8192), 16, 0, 0); } while (0)
; #define PG8_LDA(dst, b, h) do { _Pragma("unroll") for (int m = 0; m < 4; ++m) _Pragma("unroll") for (int k = 0; k < 2; ++k) dst[m][k] = *(const LAS bf16x8*)(lds + PG8_SA(b, h) + aoff + m * 2048 + k * 1024); } while (0)
; #define PG8_LDB(dst, b, h) do { _Pragma("unroll") for (int n = 0; n < 2; ++n) _Pragma("unroll") for (int k = 0; k < 2; ++k) dst[n][k] = *(const LAS bf16x8*)(lds + PG8_SB(b, h) + boff + n * 2048 + k * 1024); } while (0)
; #define PG8_MMA(ai, bj, At, Bt) do { __builtin_amdgcn_s_setprio(1); _Pragma("unroll") for (int m = 0; m < 4; ++m) _Pragma("unroll") for (int n = 0; n < 2; ++n) _Pragma("unroll") for (int k = 0; k < 2; ++k) \
;         acc[ai][bj][m][n] = __builtin_amdgcn_mfma_f32_16x16x32_bf16(Bt[n][k], At[m][k], acc[ai][bj][m][n], 0, 0, 0); __builtin_amdgcn_s_setprio(0); } while (0)
; #define PG8_WAIT_L(n) asm volatile("s_waitcnt lgkmcnt(" #n ")" ::: "memory")
; #define PG8_BAR __builtin_amdgcn_s_barrier()
; #define PG8_SCHED __builtin_amdgcn_sched_barrier(0)
; template <class Epi, class Sched>
; __device__ __forceinline__ void gemm_phase(LAS unsigned char* lds, const Gemm g, const Sched& S, const Epi& E) {
;     ...
;             PG8_LDB(B0, 0, 0); PG8_SCHED; PG8_LDA(At, 0, 0); PG8_STAGE(PG8_SA(1, 1), a1 + hstep, voffA);
;             PG8_WAIT_L(8); PG8_BAR; PG8_WAIT_L(0); PG8_MMA(0, 0, At, B0); PG8_BAR; PG8_SCHED;
;             PG8_LDB(B1, 0, 1); PG8_STAGE(PG8_SB(0, 0), b2, voffB);
;             PG8_BAR; PG8_WAIT_L(0); PG8_MMA(0, 1, At, B1); PG8_BAR;
;             PG8_LDA(At, 0, 1); PG8_STAGE(PG8_SA(0, 0), a2, voffA);
;             PG8_BAR; PG8_WAIT_L(0); PG8_MMA(1, 0, At, B0); PG8_BAR; PG8_SCHED;
;             PG8_STAGE(PG8_SB(0, 1), b2 + hstep, voffB);
.LBB0_354:
	s_add_u32 s100, s68, 0x7ff80
	s_addc_u32 s101, s69, 0
	v_lshl_add_u64 v[140:141], s[100:101], 0, v[0:1]
	s_add_i32 m0, s56, 0x1c000
	s_nop 0
	global_load_lds_dwordx4 v[140:141], off
	v_lshl_add_u64 v[140:141], s[100:101], 0, v[134:135]
	s_add_i32 m0, s56, 0x1e000
	s_nop 0
	global_load_lds_dwordx4 v[140:141], off
	s_add_u32 s38, s50, 0xfff80080
	s_addc_u32 s39, s51, -1
	s_cmp_eq_u32 s70, 28
	s_cselect_b32 s55, s9, s39
	s_cselect_b32 s54, s66, s38
	s_cselect_b32 s53, s43, s69
	s_cselect_b32 s52, s67, s68
	v_lshl_add_u64 v[156:157], s[50:51], 0, v[138:139]
	s_add_i32 m0, s29, 0xc000
	s_nop 0
	global_load_lds_dwordx4 v[156:157], off
	v_lshl_add_u64 v[156:157], s[50:51], 0, v[136:137]
	s_add_i32 m0, s29, 0xe000
	s_nop 0
	global_load_lds_dwordx4 v[156:157], off
	s_add_i32 s71, 0, 0x10000
	v_add_u32_e32 v156, s71, v145
	ds_read_b128 v[140:143], v156
	ds_read_b128 v[148:151], v156 offset:1024
	ds_read_b128 v[152:155], v156 offset:2048
	ds_read_b128 v[160:163], v156 offset:3072
	ds_read_b128 v[164:167], v147
	ds_read_b128 v[168:171], v147 offset:1024
	ds_read_b128 v[172:175], v147 offset:2048
	ds_read_b128 v[176:179], v147 offset:3072
	ds_read_b128 v[180:183], v147 offset:4096
	ds_read_b128 v[184:187], v147 offset:5120
	ds_read_b128 v[188:191], v147 offset:6144
	ds_read_b128 v[192:195], v147 offset:7168
	s_add_i32 s38, 0, 0x14000
	v_add_u32_e32 v156, s38, v145
	ds_read_b128 v[196:199], v156
	ds_read_b128 v[200:203], v156 offset:1024
	ds_read_b128 v[204:207], v156 offset:2048
	ds_read_b128 v[210:213], v156 offset:3072
	s_waitcnt lgkmcnt(4)
	s_barrier
	s_waitcnt lgkmcnt(0)
	s_setprio 1
	v_mfma_f32_16x16x32_bf16 v[126:129], v[140:143], v[164:167], v[126:129]
	v_mfma_f32_16x16x32_bf16 v[122:125], v[152:155], v[164:167], v[122:125]
	v_mfma_f32_16x16x32_bf16 v[118:121], v[140:143], v[172:175], v[118:121]
	v_mfma_f32_16x16x32_bf16 v[110:113], v[152:155], v[172:175], v[110:113]
	v_mfma_f32_16x16x32_bf16 v[102:105], v[140:143], v[180:183], v[102:105]
	v_mfma_f32_16x16x32_bf16 v[94:97], v[152:155], v[180:183], v[94:97]
	v_mfma_f32_16x16x32_bf16 v[86:89], v[140:143], v[188:191], v[86:89]
	v_mfma_f32_16x16x32_bf16 v[78:81], v[152:155], v[188:191], v[78:81]
	v_mfma_f32_16x16x32_bf16 v[126:129], v[148:151], v[168:171], v[126:129]
	v_mfma_f32_16x16x32_bf16 v[122:125], v[160:163], v[168:171], v[122:125]
	v_mfma_f32_16x16x32_bf16 v[118:121], v[148:151], v[176:179], v[118:121]
	v_mfma_f32_16x16x32_bf16 v[110:113], v[160:163], v[176:179], v[110:113]
	v_mfma_f32_16x16x32_bf16 v[102:105], v[148:151], v[184:187], v[102:105]
	v_mfma_f32_16x16x32_bf16 v[94:97], v[160:163], v[184:187], v[94:97]
	v_mfma_f32_16x16x32_bf16 v[86:89], v[148:151], v[192:195], v[86:89]
	v_mfma_f32_16x16x32_bf16 v[78:81], v[160:163], v[192:195], v[78:81]
	v_mfma_f32_16x16x32_bf16 v[114:117], v[196:199], v[164:167], v[114:117]
	v_mfma_f32_16x16x32_bf16 v[106:109], v[204:207], v[164:167], v[106:109]
	v_mfma_f32_16x16x32_bf16 v[98:101], v[196:199], v[172:175], v[98:101]
	v_mfma_f32_16x16x32_bf16 v[90:93], v[204:207], v[172:175], v[90:93]
	v_mfma_f32_16x16x32_bf16 v[82:85], v[196:199], v[180:183], v[82:85]
	v_mfma_f32_16x16x32_bf16 v[74:77], v[204:207], v[180:183], v[74:77]
	v_mfma_f32_16x16x32_bf16 v[70:73], v[196:199], v[188:191], v[70:73]
	v_mfma_f32_16x16x32_bf16 v[66:69], v[204:207], v[188:191], v[66:69]
	v_mfma_f32_16x16x32_bf16 v[114:117], v[200:203], v[168:171], v[114:117]
	v_mfma_f32_16x16x32_bf16 v[106:109], v[210:213], v[168:171], v[106:109]
	v_mfma_f32_16x16x32_bf16 v[98:101], v[200:203], v[176:179], v[98:101]
	v_mfma_f32_16x16x32_bf16 v[90:93], v[210:213], v[176:179], v[90:93]
	v_mfma_f32_16x16x32_bf16 v[82:85], v[200:203], v[184:187], v[82:85]
	v_mfma_f32_16x16x32_bf16 v[74:77], v[210:213], v[184:187], v[74:77]
	v_mfma_f32_16x16x32_bf16 v[70:73], v[200:203], v[192:195], v[70:73]
	v_mfma_f32_16x16x32_bf16 v[66:69], v[210:213], v[192:195], v[66:69]
	s_setprio 0
	s_barrier
	s_add_i32 s39, s71, s56
	v_lshl_add_u64 v[156:157], s[52:53], 0, v[0:1]
	s_mov_b32 m0, s39
	v_lshl_add_u64 v[214:215], s[52:53], 0, v[134:135]
	global_load_lds_dwordx4 v[156:157], off
	s_add_i32 m0, s39, 0x2000
	s_nop 0
	global_load_lds_dwordx4 v[214:215], off
	s_mov_b32 m0, s29
	v_lshl_add_u64 v[216:217], s[54:55], 0, v[130:131]
	global_load_lds_dwordx4 v[216:217], off
	v_lshl_add_u64 v[224:225], s[54:55], 0, v[132:133]
	s_mov_b32 m0, s41
	s_nop 0
	global_load_lds_dwordx4 v[224:225], off
	ds_read_b128 v[164:167], v147 offset:16384
	ds_read_b128 v[168:171], v147 offset:17408
	ds_read_b128 v[172:175], v147 offset:18432
	ds_read_b128 v[176:179], v147 offset:19456
	ds_read_b128 v[180:183], v147 offset:20480
	ds_read_b128 v[184:187], v147 offset:21504
	ds_read_b128 v[188:191], v147 offset:22528
	ds_read_b128 v[192:195], v147 offset:23552
	s_waitcnt vmcnt(4)
	s_waitcnt lgkmcnt(0)
	s_barrier
; #define PG8_STAGE(bufoff, gbase, voff) do { _Pragma("unroll") for (int _i = 0; _i < 2; ++_i) \
;         __builtin_amdgcn_global_load_lds((const unsigned*)((const char*)(gbase) + (voff)[_i]), (LAS unsigned*)(lds + (bufoff) + ldsw + _i * 8192), 16, 0, 0); } while (0)
; #define PG8_LDA(dst, b, h) do { _Pragma("unroll") for (int m = 0; m < 4; ++m) _Pragma("unroll") for (int k = 0; k < 2; ++k) dst[m][k] = *(const LAS bf16x8*)(lds + PG8_SA(b, h) + aoff + m * 2048 + k * 1024); } while (0)
; #define PG8_LDB(dst, b, h) do { _Pragma("unroll") for (int n = 0; n < 2; ++n) _Pragma("unroll") for (int k = 0; k < 2; ++k) dst[n][k] = *(const LAS bf16x8*)(lds + PG8_SB(b, h) + boff + n * 2048 + k * 1024); } while (0)
; #define PG8_MMA(ai, bj, At, Bt) do { __builtin_amdgcn_s_setprio(1); _Pragma("unroll") for (int m = 0; m < 4; ++m) _Pragma("unroll") for (int n = 0; n < 2; ++n) _Pragma("unroll") for (int k = 0; k < 2; ++k) \
;         acc[ai][bj][m][n] = __builtin_amdgcn_mfma_f32_16x16x32_bf16(Bt[n][k], At[m][k], acc[ai][bj][m][n], 0, 0, 0); __builtin_amdgcn_s_setprio(0); } while (0)
; #define PG8_WAIT_V(n) asm volatile("s_waitcnt vmcnt(" #n ")" ::: "memory")
; #define PG8_WAIT_L(n) asm volatile("s_waitcnt lgkmcnt(" #n ")" ::: "memory")
; #define PG8_BAR __builtin_amdgcn_s_barrier()
; #define PG8_SCHED __builtin_amdgcn_sched_barrier(0)
; template <class Epi, class Sched>
; __device__ __forceinline__ void gemm_phase(LAS unsigned char* lds, const Gemm g, const Sched& S, const Epi& E) {
;     ...
;             PG8_BAR; PG8_WAIT_L(0); PG8_MMA(1, 0, At, B0); PG8_BAR; PG8_SCHED;
;             PG8_STAGE(PG8_SB(0, 1), b2 + hstep, voffB);
;             PG8_WAIT_V(6); PG8_BAR; PG8_MMA(1, 1, At, B1); PG8_BAR;
;             PG8_LDB(B0, 1, 0); PG8_SCHED; PG8_LDA(At, 1, 0); PG8_STAGE(PG8_SA(0, 1), a2 + hstep, voffA);
;             PG8_WAIT_L(8); PG8_BAR; PG8_WAIT_L(0); PG8_MMA(0, 0, At, B0); PG8_BAR; PG8_SCHED;
;             PG8_LDB(B1, 1, 1); PG8_STAGE(PG8_SB(1, 0), b3, voffB);
;             PG8_BAR; PG8_WAIT_L(0); PG8_MMA(0, 1, At, B1); PG8_BAR;
	s_setprio 1
	v_mfma_f32_16x16x32_bf16 v[62:65], v[140:143], v[164:167], v[62:65]
	v_mfma_f32_16x16x32_bf16 v[58:61], v[152:155], v[164:167], v[58:61]
	v_mfma_f32_16x16x32_bf16 v[54:57], v[140:143], v[172:175], v[54:57]
	v_mfma_f32_16x16x32_bf16 v[46:49], v[152:155], v[172:175], v[46:49]
	v_mfma_f32_16x16x32_bf16 v[38:41], v[140:143], v[180:183], v[38:41]
	v_mfma_f32_16x16x32_bf16 v[30:33], v[152:155], v[180:183], v[30:33]
	v_mfma_f32_16x16x32_bf16 v[22:25], v[140:143], v[188:191], v[22:25]
	v_mfma_f32_16x16x32_bf16 v[14:17], v[152:155], v[188:191], v[14:17]
	v_mfma_f32_16x16x32_bf16 v[62:65], v[148:151], v[168:171], v[62:65]
	v_mfma_f32_16x16x32_bf16 v[58:61], v[160:163], v[168:171], v[58:61]
	v_mfma_f32_16x16x32_bf16 v[54:57], v[148:151], v[176:179], v[54:57]
	v_mfma_f32_16x16x32_bf16 v[46:49], v[160:163], v[176:179], v[46:49]
	v_mfma_f32_16x16x32_bf16 v[38:41], v[148:151], v[184:187], v[38:41]
	v_mfma_f32_16x16x32_bf16 v[30:33], v[160:163], v[184:187], v[30:33]
	v_mfma_f32_16x16x32_bf16 v[22:25], v[148:151], v[192:195], v[22:25]
	v_mfma_f32_16x16x32_bf16 v[14:17], v[160:163], v[192:195], v[14:17]
	v_mfma_f32_16x16x32_bf16 v[50:53], v[196:199], v[164:167], v[50:53]
	v_mfma_f32_16x16x32_bf16 v[42:45], v[204:207], v[164:167], v[42:45]
	v_mfma_f32_16x16x32_bf16 v[34:37], v[196:199], v[172:175], v[34:37]
	v_mfma_f32_16x16x32_bf16 v[26:29], v[204:207], v[172:175], v[26:29]
	v_mfma_f32_16x16x32_bf16 v[18:21], v[196:199], v[180:183], v[18:21]
	v_mfma_f32_16x16x32_bf16 v[10:13], v[204:207], v[180:183], v[10:13]
	v_mfma_f32_16x16x32_bf16 v[6:9], v[196:199], v[188:191], v[6:9]
	v_mfma_f32_16x16x32_bf16 v[2:5], v[204:207], v[188:191], v[2:5]
	v_mfma_f32_16x16x32_bf16 v[50:53], v[200:203], v[168:171], v[50:53]
	v_mfma_f32_16x16x32_bf16 v[42:45], v[210:213], v[168:171], v[42:45]
	v_mfma_f32_16x16x32_bf16 v[34:37], v[200:203], v[176:179], v[34:37]
	v_mfma_f32_16x16x32_bf16 v[26:29], v[210:213], v[176:179], v[26:29]
	v_mfma_f32_16x16x32_bf16 v[18:21], v[200:203], v[184:187], v[18:21]
	v_mfma_f32_16x16x32_bf16 v[10:13], v[210:213], v[184:187], v[10:13]
	v_mfma_f32_16x16x32_bf16 v[6:9], v[200:203], v[192:195], v[6:9]
	v_mfma_f32_16x16x32_bf16 v[2:5], v[210:213], v[192:195], v[2:5]
	s_setprio 0
	s_barrier
	s_add_u32 s72, s52, 0x80000
	s_addc_u32 s73, s53, 0
	s_add_i32 s38, s38, s56
	v_lshl_add_u64 v[140:141], s[72:73], 0, v[0:1]
	s_mov_b32 m0, s38
	s_nop 0
	global_load_lds_dwordx4 v[140:141], off
	v_lshl_add_u64 v[140:141], s[72:73], 0, v[134:135]
	s_add_i32 m0, s38, 0x2000
	s_nop 0
	global_load_lds_dwordx4 v[140:141], off
	s_add_u32 s54, s54, 0x80000
	s_addc_u32 s55, s55, 0
	s_mov_b32 m0, s57
	v_lshl_add_u64 v[196:197], s[54:55], 0, v[130:131]
	global_load_lds_dwordx4 v[196:197], off
	v_lshl_add_u64 v[196:197], s[54:55], 0, v[132:133]
	s_mov_b32 m0, s58
	s_nop 0
	global_load_lds_dwordx4 v[196:197], off
	s_add_i32 s38, 0, 0x18000
	v_add_u32_e32 v160, s38, v145
	ds_read_b128 v[140:143], v160
	ds_read_b128 v[148:151], v160 offset:1024
	ds_read_b128 v[152:155], v160 offset:2048
	ds_read_b128 v[160:163], v160 offset:3072
	ds_read_b128 v[164:167], v147 offset:32768
	ds_read_b128 v[168:171], v147 offset:33792
	ds_read_b128 v[172:175], v147 offset:34816
	ds_read_b128 v[176:179], v147 offset:35840
	ds_read_b128 v[180:183], v147 offset:36864
	ds_read_b128 v[184:187], v147 offset:37888
	ds_read_b128 v[188:191], v147 offset:38912
	ds_read_b128 v[192:195], v147 offset:39936
	s_add_i32 s39, 0, 0x1c000
	v_add_u32_e32 v210, s39, v145
	ds_read_b128 v[196:199], v210
	ds_read_b128 v[200:203], v210 offset:1024
	ds_read_b128 v[204:207], v210 offset:2048
	ds_read_b128 v[210:213], v210 offset:3072
	s_waitcnt lgkmcnt(4)
	s_barrier
	s_waitcnt lgkmcnt(0)
	s_setprio 1
	v_mfma_f32_16x16x32_bf16 v[126:129], v[140:143], v[164:167], v[126:129]
	v_mfma_f32_16x16x32_bf16 v[122:125], v[152:155], v[164:167], v[122:125]
	v_mfma_f32_16x16x32_bf16 v[118:121], v[140:143], v[172:175], v[118:121]
	v_mfma_f32_16x16x32_bf16 v[110:113], v[152:155], v[172:175], v[110:113]
	v_mfma_f32_16x16x32_bf16 v[102:105], v[140:143], v[180:183], v[102:105]
	v_mfma_f32_16x16x32_bf16 v[94:97], v[152:155], v[180:183], v[94:97]
	v_mfma_f32_16x16x32_bf16 v[86:89], v[140:143], v[188:191], v[86:89]
	v_mfma_f32_16x16x32_bf16 v[78:81], v[152:155], v[188:191], v[78:81]
	v_mfma_f32_16x16x32_bf16 v[126:129], v[148:151], v[168:171], v[126:129]
	v_mfma_f32_16x16x32_bf16 v[122:125], v[160:163], v[168:171], v[122:125]
	v_mfma_f32_16x16x32_bf16 v[118:121], v[148:151], v[176:179], v[118:121]
	v_mfma_f32_16x16x32_bf16 v[110:113], v[160:163], v[176:179], v[110:113]
	v_mfma_f32_16x16x32_bf16 v[102:105], v[148:151], v[184:187], v[102:105]
	v_mfma_f32_16x16x32_bf16 v[94:97], v[160:163], v[184:187], v[94:97]
	v_mfma_f32_16x16x32_bf16 v[86:89], v[148:151], v[192:195], v[86:89]
	v_mfma_f32_16x16x32_bf16 v[78:81], v[160:163], v[192:195], v[78:81]
	v_mfma_f32_16x16x32_bf16 v[114:117], v[196:199], v[164:167], v[114:117]
	v_mfma_f32_16x16x32_bf16 v[106:109], v[204:207], v[164:167], v[106:109]
	v_mfma_f32_16x16x32_bf16 v[98:101], v[196:199], v[172:175], v[98:101]
	v_mfma_f32_16x16x32_bf16 v[90:93], v[204:207], v[172:175], v[90:93]
	v_mfma_f32_16x16x32_bf16 v[82:85], v[196:199], v[180:183], v[82:85]
	v_mfma_f32_16x16x32_bf16 v[74:77], v[204:207], v[180:183], v[74:77]
	v_mfma_f32_16x16x32_bf16 v[70:73], v[196:199], v[188:191], v[70:73]
	v_mfma_f32_16x16x32_bf16 v[66:69], v[204:207], v[188:191], v[66:69]
	v_mfma_f32_16x16x32_bf16 v[114:117], v[200:203], v[168:171], v[114:117]
	v_mfma_f32_16x16x32_bf16 v[106:109], v[210:213], v[168:171], v[106:109]
	v_mfma_f32_16x16x32_bf16 v[98:101], v[200:203], v[176:179], v[98:101]
	v_mfma_f32_16x16x32_bf16 v[90:93], v[210:213], v[176:179], v[90:93]
	v_mfma_f32_16x16x32_bf16 v[82:85], v[200:203], v[184:187], v[82:85]
	v_mfma_f32_16x16x32_bf16 v[74:77], v[210:213], v[184:187], v[74:77]
	v_mfma_f32_16x16x32_bf16 v[70:73], v[200:203], v[192:195], v[70:73]
	v_mfma_f32_16x16x32_bf16 v[66:69], v[210:213], v[192:195], v[66:69]
	s_setprio 0
	s_barrier
; #define PG8_STAGE(bufoff, gbase, voff) do { _Pragma("unroll") for (int _i = 0; _i < 2; ++_i) \
;         __builtin_amdgcn_global_load_lds((const unsigned*)((const char*)(gbase) + (voff)[_i]), (LAS unsigned*)(lds + (bufoff) + ldsw + _i * 8192), 16, 0, 0); } while (0)
; #define PG8_LDA(dst, b, h) do { _Pragma("unroll") for (int m = 0; m < 4; ++m) _Pragma("unroll") for (int k = 0; k < 2; ++k) dst[m][k] = *(const LAS bf16x8*)(lds + PG8_SA(b, h) + aoff + m * 2048 + k * 1024); } while (0)
; #define PG8_MMA(ai, bj, At, Bt) do { __builtin_amdgcn_s_setprio(1); _Pragma("unroll") for (int m = 0; m < 4; ++m) _Pragma("unroll") for (int n = 0; n < 2; ++n) _Pragma("unroll") for (int k = 0; k < 2; ++k) \
;         acc[ai][bj][m][n] = __builtin_amdgcn_mfma_f32_16x16x32_bf16(Bt[n][k], At[m][k], acc[ai][bj][m][n], 0, 0, 0); __builtin_amdgcn_s_setprio(0); } while (0)
; #define PG8_WAIT_V(n) asm volatile("s_waitcnt vmcnt(" #n ")" ::: "memory")
; #define PG8_WAIT_L(n) asm volatile("s_waitcnt lgkmcnt(" #n ")" ::: "memory")
; #define PG8_BAR __builtin_amdgcn_s_barrier()
; #define PG8_SCHED __builtin_amdgcn_sched_barrier(0)
; template <class Epi, class Sched>
; __device__ __forceinline__ void gemm_phase(LAS unsigned char* lds, const Gemm g, const Sched& S, const Epi& E) {
;     ...
;             PG8_BAR; PG8_WAIT_L(0); PG8_MMA(0, 1, At, B1); PG8_BAR;
;             PG8_LDA(At, 1, 1); PG8_STAGE(PG8_SA(1, 0), a3, voffA);
;             PG8_BAR; PG8_WAIT_L(0); PG8_MMA(1, 0, At, B0); PG8_BAR; PG8_SCHED;
;             PG8_STAGE(PG8_SB(1, 1), b3 + hstep, voffB);
;             PG8_WAIT_V(6); PG8_BAR; PG8_MMA(1, 1, At, B1); PG8_BAR;
;         }
	s_add_i32 s38, s38, s56
	v_lshl_add_u64 v[156:157], v[156:157], 0, s[36:37]
	s_mov_b32 m0, s38
	s_nop 0
	global_load_lds_dwordx4 v[156:157], off
	v_lshl_add_u64 v[156:157], v[214:215], 0, s[36:37]
	s_add_i32 m0, s38, 0x2000
	s_nop 0
	global_load_lds_dwordx4 v[156:157], off
	s_mov_b32 m0, s59
	v_lshl_add_u64 v[156:157], v[216:217], 0, s[36:37]
	global_load_lds_dwordx4 v[156:157], off
	v_lshl_add_u64 v[156:157], v[224:225], 0, s[36:37]
	s_mov_b32 m0, s60
	s_nop 0
	global_load_lds_dwordx4 v[156:157], off
	ds_read_b128 v[164:167], v147 offset:49152
	ds_read_b128 v[168:171], v147 offset:50176
	ds_read_b128 v[172:175], v147 offset:51200
	ds_read_b128 v[176:179], v147 offset:52224
	ds_read_b128 v[180:183], v147 offset:53248
	ds_read_b128 v[184:187], v147 offset:54272
	ds_read_b128 v[188:191], v147 offset:55296
	ds_read_b128 v[192:195], v147 offset:56320
	s_waitcnt vmcnt(4)
	s_waitcnt lgkmcnt(0)
	s_barrier
	s_setprio 1
	v_mfma_f32_16x16x32_bf16 v[62:65], v[140:143], v[164:167], v[62:65]
	v_mfma_f32_16x16x32_bf16 v[58:61], v[152:155], v[164:167], v[58:61]
	v_mfma_f32_16x16x32_bf16 v[54:57], v[140:143], v[172:175], v[54:57]
	v_mfma_f32_16x16x32_bf16 v[46:49], v[152:155], v[172:175], v[46:49]
	v_mfma_f32_16x16x32_bf16 v[38:41], v[140:143], v[180:183], v[38:41]
	v_mfma_f32_16x16x32_bf16 v[30:33], v[152:155], v[180:183], v[30:33]
	v_mfma_f32_16x16x32_bf16 v[22:25], v[140:143], v[188:191], v[22:25]
	v_mfma_f32_16x16x32_bf16 v[14:17], v[152:155], v[188:191], v[14:17]
	v_mfma_f32_16x16x32_bf16 v[62:65], v[148:151], v[168:171], v[62:65]
	v_mfma_f32_16x16x32_bf16 v[58:61], v[160:163], v[168:171], v[58:61]
	v_mfma_f32_16x16x32_bf16 v[54:57], v[148:151], v[176:179], v[54:57]
	v_mfma_f32_16x16x32_bf16 v[46:49], v[160:163], v[176:179], v[46:49]
	v_mfma_f32_16x16x32_bf16 v[38:41], v[148:151], v[184:187], v[38:41]
	v_mfma_f32_16x16x32_bf16 v[30:33], v[160:163], v[184:187], v[30:33]
	v_mfma_f32_16x16x32_bf16 v[22:25], v[148:151], v[192:195], v[22:25]
	v_mfma_f32_16x16x32_bf16 v[14:17], v[160:163], v[192:195], v[14:17]
	v_mfma_f32_16x16x32_bf16 v[50:53], v[196:199], v[164:167], v[50:53]
	v_mfma_f32_16x16x32_bf16 v[42:45], v[204:207], v[164:167], v[42:45]
	v_mfma_f32_16x16x32_bf16 v[34:37], v[196:199], v[172:175], v[34:37]
	v_mfma_f32_16x16x32_bf16 v[26:29], v[204:207], v[172:175], v[26:29]
	v_mfma_f32_16x16x32_bf16 v[18:21], v[196:199], v[180:183], v[18:21]
	v_mfma_f32_16x16x32_bf16 v[10:13], v[204:207], v[180:183], v[10:13]
	v_mfma_f32_16x16x32_bf16 v[6:9], v[196:199], v[188:191], v[6:9]
	v_mfma_f32_16x16x32_bf16 v[2:5], v[204:207], v[188:191], v[2:5]
	v_mfma_f32_16x16x32_bf16 v[50:53], v[200:203], v[168:171], v[50:53]
	v_mfma_f32_16x16x32_bf16 v[42:45], v[210:213], v[168:171], v[42:45]
	v_mfma_f32_16x16x32_bf16 v[34:37], v[200:203], v[176:179], v[34:37]
	v_mfma_f32_16x16x32_bf16 v[26:29], v[210:213], v[176:179], v[26:29]
	v_mfma_f32_16x16x32_bf16 v[18:21], v[200:203], v[184:187], v[18:21]
	v_mfma_f32_16x16x32_bf16 v[10:13], v[210:213], v[184:187], v[10:13]
	v_mfma_f32_16x16x32_bf16 v[6:9], v[200:203], v[192:195], v[6:9]
	v_mfma_f32_16x16x32_bf16 v[2:5], v[210:213], v[192:195], v[2:5]
	s_setprio 0
	s_add_i32 s70, s70, 2
	s_add_u32 s68, s68, 0x100
	s_addc_u32 s69, s69, 0
	s_add_u32 s50, s50, 0x100
	s_addc_u32 s51, s51, 0
	s_cmp_gt_u32 s70, 29
	s_barrier
	s_cbranch_scc0 .LBB0_354
; __device__ __forceinline__ unsigned cvt_pk_bf16(float lo, float hi) { unsigned r; asm("v_cvt_pk_bf16_f32 %0, %1, %2" : "=v"(r) : "v"(lo), "v"(hi)); return r; }
;     __device__ __forceinline__ void operator()(const f32x4 (&acc)[2][2][4][2], const Unit& u, int wr, int wc, int fr, int fq) const {
;         const int row0 = u.pm * BM + wr * 64 + fr, col0 = u.pn * BM + wc * 32 + 8 * fq;
; #pragma unroll
;         for (int ai = 0; ai < 2; ++ai)
; #pragma unroll
;             for (int m = 0; m < 4; ++m) { bf16_t* rowp = O + (size_t)(row0 + ai * HALF + m * 16) * ldc + col0;
; #pragma unroll
;                 for (int bj = 0; bj < 2; ++bj) { f32x4 v0 = acc[ai][bj][m][0], v1 = acc[ai][bj][m][1];
;                     if (ACT == 1) {
; #pragma unroll
;                         for (int j = 0; j < 4; ++j) { float a = fmaxf(v0[j], 0.f), b = fmaxf(v1[j], 0.f); v0[j] = a * a; v1[j] = b * b; } }
;                     u32x4 w; w.x = cvt_pk_bf16(v0[0], v0[1]); w.y = cvt_pk_bf16(v0[2], v0[3]); w.z = cvt_pk_bf16(v1[0], v1[1]); w.w = cvt_pk_bf16(v1[2], v1[3]);
;                     if (ACT == 1) __builtin_nontemporal_store(w, (u32x4*)(rowp + bj * HALF));
;                     else *(u32x4*)(rowp + bj * HALF) = w; } }
	s_load_dwordx2 s[50:51], s[0:1], 0xc0
	v_lshl_add_u32 v150, s28, 8, v144
	v_lshl_or_b32 v142, s40, 8, v146
	v_ashrrev_i32_e32 v143, 31, v142
	v_cvt_pk_bf16_f32 v70, v70, v71
	s_waitcnt lgkmcnt(0)
	v_mov_b64_e32 v[140:141], s[50:51]
	v_cvt_pk_bf16_f32 v71, v72, v73
	v_cvt_pk_bf16_f32 v72, v66, v67
	v_add_u32_e32 v66, 0x80, v150
	v_mad_i64_i32 v[148:149], s[50:51], v150, s17, v[140:141]
	v_lshlrev_b64 v[142:143], 1, v[142:143]
	v_cvt_pk_bf16_f32 v114, v114, v115
	v_cvt_pk_bf16_f32 v115, v116, v117
	v_cvt_pk_bf16_f32 v116, v106, v107
	v_or_b32_e32 v106, 16, v150
	v_mad_i64_i32 v[66:67], s[50:51], v66, s17, v[140:141]
	v_cvt_pk_bf16_f32 v50, v50, v51
	v_cvt_pk_bf16_f32 v51, v52, v53
	v_cvt_pk_bf16_f32 v52, v42, v43
	v_add_u32_e32 v42, 0x90, v150
	v_lshl_add_u64 v[148:149], v[148:149], 0, v[142:143]
	v_mad_i64_i32 v[106:107], s[50:51], v106, s17, v[140:141]
	v_cvt_pk_bf16_f32 v98, v98, v99
	v_cvt_pk_bf16_f32 v99, v100, v101
	v_cvt_pk_bf16_f32 v100, v90, v91
	v_or_b32_e32 v90, 32, v150
	v_lshl_add_u64 v[66:67], v[66:67], 0, v[142:143]
	v_mad_i64_i32 v[42:43], s[50:51], v42, s17, v[140:141]
	v_cvt_pk_bf16_f32 v34, v34, v35
	v_cvt_pk_bf16_f32 v35, v36, v37
	v_cvt_pk_bf16_f32 v36, v26, v27
	v_add_u32_e32 v26, 0xa0, v150
	v_cvt_pk_bf16_f32 v117, v108, v109
	global_store_dwordx4 v[148:149], v[114:117], off offset:256
	v_mad_i64_i32 v[90:91], s[50:51], v90, s17, v[140:141]
	s_nop 0
	v_lshl_add_u64 v[114:115], v[106:107], 0, v[142:143]
	v_cvt_pk_bf16_f32 v82, v82, v83
	v_cvt_pk_bf16_f32 v83, v84, v85
	v_cvt_pk_bf16_f32 v84, v74, v75
	v_or_b32_e32 v74, 48, v150
	v_cvt_pk_bf16_f32 v53, v44, v45
	global_store_dwordx4 v[66:67], v[50:53], off offset:256
	v_mad_i64_i32 v[26:27], s[50:51], v26, s17, v[140:141]
	s_nop 0
	v_lshl_add_u64 v[50:51], v[42:43], 0, v[142:143]
	v_cvt_pk_bf16_f32 v18, v18, v19
	v_cvt_pk_bf16_f32 v19, v20, v21
	v_cvt_pk_bf16_f32 v20, v10, v11
	v_add_u32_e32 v10, 0xb0, v150
	v_cvt_pk_bf16_f32 v101, v92, v93
	global_store_dwordx4 v[114:115], v[98:101], off offset:256
	v_mad_i64_i32 v[74:75], s[50:51], v74, s17, v[140:141]
	s_nop 0
	v_lshl_add_u64 v[98:99], v[90:91], 0, v[142:143]
	v_cvt_pk_bf16_f32 v37, v28, v29
	global_store_dwordx4 v[50:51], v[34:37], off offset:256
	v_mad_i64_i32 v[10:11], s[50:51], v10, s17, v[140:141]
	s_nop 0
	v_lshl_add_u64 v[34:35], v[26:27], 0, v[142:143]
	v_cvt_pk_bf16_f32 v85, v76, v77
	global_store_dwordx4 v[98:99], v[82:85], off offset:256
	v_cvt_pk_bf16_f32 v21, v12, v13
	global_store_dwordx4 v[34:35], v[18:21], off offset:256
	s_and_b64 vcc, exec, s[46:47]
	v_lshl_add_u64 v[82:83], v[74:75], 0, v[142:143]
	v_lshl_add_u64 v[18:19], v[10:11], 0, v[142:143]
	s_mov_b32 s40, s42
	s_mov_b32 s28, s8
	s_mov_b32 s43, s42
	s_mov_b32 s46, s8
	s_mov_b64 s[50:51], s[48:49]
	s_mov_b64 s[52:53], s[44:45]
	v_cvt_pk_bf16_f32 v126, v126, v127
	v_cvt_pk_bf16_f32 v127, v128, v129
	v_cvt_pk_bf16_f32 v128, v122, v123
	v_cvt_pk_bf16_f32 v129, v124, v125
	global_store_dwordx4 v[148:149], v[126:129], off
	v_cvt_pk_bf16_f32 v106, v118, v119
	v_cvt_pk_bf16_f32 v107, v120, v121
	v_cvt_pk_bf16_f32 v108, v110, v111
	v_cvt_pk_bf16_f32 v109, v112, v113
	global_store_dwordx4 v[114:115], v[106:109], off
	v_cvt_pk_bf16_f32 v90, v102, v103
	v_cvt_pk_bf16_f32 v91, v104, v105
	v_cvt_pk_bf16_f32 v92, v94, v95
	v_cvt_pk_bf16_f32 v93, v96, v97
	global_store_dwordx4 v[98:99], v[90:93], off
	v_cvt_pk_bf16_f32 v74, v86, v87
	v_cvt_pk_bf16_f32 v75, v88, v89
	v_cvt_pk_bf16_f32 v76, v78, v79
	v_cvt_pk_bf16_f32 v77, v80, v81
	global_store_dwordx4 v[82:83], v[74:77], off
	v_cvt_pk_bf16_f32 v73, v68, v69
	global_store_dwordx4 v[82:83], v[70:73], off offset:256
	v_cvt_pk_bf16_f32 v62, v62, v63
	v_cvt_pk_bf16_f32 v63, v64, v65
	v_cvt_pk_bf16_f32 v64, v58, v59
	v_cvt_pk_bf16_f32 v65, v60, v61
	global_store_dwordx4 v[66:67], v[62:65], off
	v_cvt_pk_bf16_f32 v42, v54, v55
	v_cvt_pk_bf16_f32 v43, v56, v57
	v_cvt_pk_bf16_f32 v44, v46, v47
	v_cvt_pk_bf16_f32 v45, v48, v49
	global_store_dwordx4 v[50:51], v[42:45], off
	v_cvt_pk_bf16_f32 v26, v38, v39
	v_cvt_pk_bf16_f32 v27, v40, v41
	v_cvt_pk_bf16_f32 v28, v30, v31
	v_cvt_pk_bf16_f32 v29, v32, v33
	global_store_dwordx4 v[34:35], v[26:29], off
	v_cvt_pk_bf16_f32 v10, v22, v23
	v_cvt_pk_bf16_f32 v11, v24, v25
	v_cvt_pk_bf16_f32 v12, v14, v15
	v_cvt_pk_bf16_f32 v13, v16, v17
	global_store_dwordx4 v[18:19], v[10:13], off
	v_cvt_pk_bf16_f32 v6, v6, v7
	v_cvt_pk_bf16_f32 v7, v8, v9
	v_cvt_pk_bf16_f32 v8, v2, v3
	v_cvt_pk_bf16_f32 v9, v4, v5
	global_store_dwordx4 v[18:19], v[6:9], off offset:256
	s_cbranch_vccz .LBB0_346
	s_waitcnt vmcnt(0)
	s_cmpk_gt_u32 s25, 0xff
	s_cbranch_scc1 .LBB0_358
	s_barrier
